# scan: packed (sa,y) dots via interleaved a/r LDS layout, loader writes (a_t, r_t-1)
# baseline (speedup 1.0000x reference)
; #define LAS __attribute__((address_space(3)))
; __device__ __forceinline__ void rwkv_scan(Frame& F, int wg, unsigned* shw, unsigned wait_target, int wait_blk) {
;     ...
;     auto gload = [&](LdRegs& L, int blk) {
;         const int t = blk * RW_TB + lstep; const size_t o = (size_t)t * 1024 + h * 64 + 8 * part;
;         L.w0 = *(const f32x4*)(Wd + o); L.w1 = *(const f32x4*)(Wd + o + 4);
;         L.a = *(const u32x4*)(Ab + o); L.b = *(const u32x4*)(Bb + o); L.k = *(const u32x4*)(Kp + o); L.r = *(const u32x4*)(Rb + o);
;         if (part < 2) { L.v = *(const u32x4*)(Vb + (size_t)t * 1024 + h * 64 + 16 * rq + 8 * part); L.br = BR[t * 16 + h]; L.kr = KR[t * 16 + h]; }
;     };
;     auto lstore = [&](const LdRegs& L, int b) {
;         LAS float* rec = buf + (b * RW_TB + lstep) * RW_REC;
;         const u32x4 av = L.a, bv = L.b, kv = L.k, rv = L.r;
;         f32x4 a_0 = {bflo(av.x), bfhi(av.x), bflo(av.y), bfhi(av.y)}, a_1 = {bflo(av.z), bfhi(av.z), bflo(av.w), bfhi(av.w)};
;         f32x4 b_0 = {bflo(bv.x), bfhi(bv.x), bflo(bv.y), bfhi(bv.y)}, b_1 = {bflo(bv.z), bfhi(bv.z), bflo(bv.w), bfhi(bv.w)};
;         f32x4 k_0 = {bflo(kv.x), bfhi(kv.x), bflo(kv.y), bfhi(kv.y)}, k_1 = {bflo(kv.z), bfhi(kv.z), bflo(kv.w), bfhi(kv.w)};
;         f32x4 r_0 = {bflo(rv.x), bfhi(rv.x), bflo(rv.y), bfhi(rv.y)}, r_1 = {bflo(rv.z), bfhi(rv.z), bflo(rv.w), bfhi(rv.w)};
;         *(LAS f32x4*)(rec + 8 * part) = L.w0; *(LAS f32x4*)(rec + 8 * part + 4) = L.w1;
;         *(LAS f32x4*)(rec + 64 + 8 * part) = a_0; *(LAS f32x4*)(rec + 64 + 8 * part + 4) = a_1;
;         *(LAS f32x4*)(rec + 128 + 8 * part) = b_0; *(LAS f32x4*)(rec + 128 + 8 * part + 4) = b_1;
;         *(LAS f32x4*)(rec + 192 + 8 * part) = k_0; *(LAS f32x4*)(rec + 192 + 8 * part + 4) = k_1;
;         *(LAS f32x4*)(rec + 256 + 8 * part) = L.w0 * r_0; *(LAS f32x4*)(rec + 256 + 8 * part + 4) = L.w1 * r_1;
;         if (part < 2) { const u32x4 vv = L.v;
;             const float v8[8] = {bflo(vv.x), bfhi(vv.x), bflo(vv.y), bfhi(vv.y), bflo(vv.z), bfhi(vv.z), bflo(vv.w), bfhi(vv.w)};
; #pragma unroll
;             for (int e = 0; e < 8; ++e) *(LAS f32x4*)(rec + 320 + (8 * part + e) * 4) = (f32x4){v8[e], v8[e] * L.kr, L.br, 0.f}; }
;     };
;     ...
;     if (loader) { gload(L0, 0); lstore(L0, 0); gload(L0, 1); gload(L1, 2); }
.LBB0_836:
	v_ashrrev_i32_e32 v61, 31, v60
	s_lshl_b32 s52, s58, 6
	v_lshlrev_b64 v[4:5], 10, v[60:61]
	s_ashr_i32 s53, s52, 31
	v_lshl_add_u64 v[0:1], v[4:5], 0, s[52:53]
	v_or_b32_e32 v0, v0, v64
	v_lshl_add_u64 v[2:3], v[0:1], 2, s[12:13]
	v_lshlrev_b64 v[0:1], 1, v[0:1]
	global_load_dwordx4 v[8:11], v[2:3], off offset:16
	global_load_dwordx4 v[12:15], v[2:3], off
	v_lshl_add_u64 v[2:3], s[14:15], 0, v[0:1]
	v_lshl_add_u64 v[6:7], s[16:17], 0, v[0:1]
	global_load_dwordx4 v[28:31], v[2:3], off
	global_load_dwordx4 v[24:27], v[6:7], off
	v_lshl_add_u64 v[2:3], s[18:19], 0, v[0:1]
	v_lshl_add_u64 v[0:1], s[40:41], 0, v[0:1]
	global_load_dwordx4 v[20:23], v[2:3], off
	global_load_dwordx4 v[16:19], v[0:1], off offset:-2048
	v_mov_b32_e32 v65, 0
	v_lshlrev_b32_e32 v66, 1, v64
	s_and_saveexec_b64 s[6:7], s[4:5]
	s_cbranch_execz .LBB0_838
	v_lshl_add_u64 v[0:1], v[4:5], 1, s[50:51]
	v_lshl_add_u64 v[0:1], s[52:53], 1, v[0:1]
	s_lshl_b32 s8, s54, 5
	s_mov_b32 s9, 0
	v_lshl_add_u32 v2, v60, 4, s58
	v_lshl_add_u64 v[0:1], v[0:1], 0, s[8:9]
	v_mov_b32_e32 v67, v65
	v_ashrrev_i32_e32 v3, 31, v2
	v_lshl_add_u64 v[0:1], v[0:1], 0, v[66:67]
	v_lshlrev_b64 v[2:3], 2, v[2:3]
	v_lshl_add_u64 v[4:5], s[22:23], 0, v[2:3]
	v_lshl_add_u64 v[32:33], s[24:25], 0, v[2:3]
	global_load_dwordx4 v[0:3], v[0:1], off
	s_nop 0
	global_load_dword v6, v[4:5], off
	global_load_dword v196, v[32:33], off
.LBB0_838:
	s_or_b64 exec, exec, s[6:7]
	s_movk_i32 s6, 0x600
	v_mad_i32_i24 v7, v60, s6, 0
	s_waitcnt vmcnt(0)
	v_add_u32_e32 v100, v7, v195
	v_lshl_add_u32 v101, v195, 1, v7
	v_lshlrev_b32_e32 v104, 16, v24
	v_and_b32_e32 v105, 0xffff0000, v24
	v_lshlrev_b32_e32 v106, 16, v25
	v_and_b32_e32 v107, 0xffff0000, v25
	v_lshlrev_b32_e32 v108, 16, v26
	v_and_b32_e32 v109, 0xffff0000, v26
	v_lshlrev_b32_e32 v110, 16, v27
	v_and_b32_e32 v111, 0xffff0000, v27
	ds_write_b128 v100, v[104:107] offset:768
	ds_write_b128 v100, v[108:111] offset:784
	v_lshlrev_b32_e32 v112, 16, v20
	v_and_b32_e32 v113, 0xffff0000, v20
	v_lshlrev_b32_e32 v114, 16, v21
	v_and_b32_e32 v115, 0xffff0000, v21
	v_lshlrev_b32_e32 v116, 16, v22
	v_and_b32_e32 v117, 0xffff0000, v22
	v_lshlrev_b32_e32 v118, 16, v23
	v_and_b32_e32 v119, 0xffff0000, v23
	ds_write_b128 v100, v[112:115] offset:1024
	ds_write_b128 v100, v[116:119] offset:1040
	v_lshlrev_b32_e32 v120, 16, v28
	v_lshlrev_b32_e32 v121, 16, v16
	v_and_b32_e32 v122, 0xffff0000, v28
	v_and_b32_e32 v123, 0xffff0000, v16
	ds_write_b128 v101, v[120:123] offset:256
	v_lshlrev_b32_e32 v124, 16, v29
	v_lshlrev_b32_e32 v125, 16, v17
	v_and_b32_e32 v126, 0xffff0000, v29
	v_and_b32_e32 v127, 0xffff0000, v17
	ds_write_b128 v101, v[124:127] offset:272
	v_lshlrev_b32_e32 v128, 16, v30
	v_lshlrev_b32_e32 v129, 16, v18
	v_and_b32_e32 v130, 0xffff0000, v30
	v_and_b32_e32 v131, 0xffff0000, v18
	ds_write_b128 v101, v[128:131] offset:288
	v_lshlrev_b32_e32 v132, 16, v31
	v_lshlrev_b32_e32 v133, 16, v19
	v_and_b32_e32 v134, 0xffff0000, v31
	v_and_b32_e32 v135, 0xffff0000, v19
	ds_write_b128 v101, v[132:135] offset:304
	ds_write_b128 v100, v[12:15] offset:0
	ds_write_b128 v100, v[8:11] offset:16
	s_and_saveexec_b64 s[6:7], s[4:5]
	s_cbranch_execz .LBB0_840
	v_lshlrev_b32_e32 v4, 16, v0
	v_and_b32_e32 v8, 0xffff0000, v0
	v_lshlrev_b32_e32 v12, 16, v1
	v_and_b32_e32 v16, 0xffff0000, v1
	v_lshlrev_b32_e32 v20, 16, v2
	v_and_b32_e32 v24, 0xffff0000, v2
	v_lshlrev_b32_e32 v28, 16, v3
	v_and_b32_e32 v32, 0xffff0000, v3
	v_lshl_add_u32 v36, v63, 7, v7
	v_mov_b32_e32 v7, 0
	v_mul_f32_e32 v5, v196, v4
	v_mul_f32_e32 v9, v196, v8
	v_mov_b32_e32 v10, v6
	v_mov_b32_e32 v11, v7
	v_mul_f32_e32 v13, v196, v12
	v_mov_b32_e32 v14, v6
	v_mov_b32_e32 v15, v7
	v_mul_f32_e32 v17, v196, v16
	v_mov_b32_e32 v18, v6
	v_mov_b32_e32 v19, v7
	v_mul_f32_e32 v21, v196, v20
	v_mov_b32_e32 v22, v6
	v_mov_b32_e32 v23, v7
	v_mul_f32_e32 v25, v196, v24
	v_mov_b32_e32 v26, v6
	v_mov_b32_e32 v27, v7
	v_mul_f32_e32 v29, v196, v28
	v_mov_b32_e32 v30, v6
	v_mov_b32_e32 v31, v7
	v_mul_f32_e32 v33, v196, v32
	v_mov_b32_e32 v34, v6
	v_mov_b32_e32 v35, v7
	ds_write_b128 v36, v[4:7] offset:1280
	ds_write_b128 v36, v[8:11] offset:1296
	ds_write_b128 v36, v[12:15] offset:1312
	ds_write_b128 v36, v[16:19] offset:1328
	ds_write_b128 v36, v[20:23] offset:1344
	ds_write_b128 v36, v[24:27] offset:1360
	ds_write_b128 v36, v[28:31] offset:1376
	ds_write_b128 v36, v[32:35] offset:1392
; __device__ __forceinline__ void rwkv_scan(Frame& F, int wg, unsigned* shw, unsigned wait_target, int wait_blk) {
;     ...
;     auto gload = [&](LdRegs& L, int blk) {
;         const int t = blk * RW_TB + lstep; const size_t o = (size_t)t * 1024 + h * 64 + 8 * part;
;         L.w0 = *(const f32x4*)(Wd + o); L.w1 = *(const f32x4*)(Wd + o + 4);
;         L.a = *(const u32x4*)(Ab + o); L.b = *(const u32x4*)(Bb + o); L.k = *(const u32x4*)(Kp + o); L.r = *(const u32x4*)(Rb + o);
;         if (part < 2) { L.v = *(const u32x4*)(Vb + (size_t)t * 1024 + h * 64 + 16 * rq + 8 * part); L.br = BR[t * 16 + h]; L.kr = KR[t * 16 + h]; }
;     };
;     ...
;     if (loader) { gload(L0, 0); lstore(L0, 0); gload(L0, 1); gload(L1, 2); }
.LBB0_840:
	s_or_b64 exec, exec, s[6:7]
	v_add_u32_e32 v4, 32, v60
	v_mov_b32_e32 v5, 0
	v_lshlrev_b64 v[32:33], 10, v[4:5]
	v_lshl_add_u64 v[16:17], v[32:33], 0, s[52:53]
	v_or_b32_e32 v16, v16, v64
	v_lshlrev_b64 v[24:25], 1, v[16:17]
	v_lshl_add_u64 v[18:19], v[16:17], 2, s[12:13]
	v_lshl_add_u64 v[26:27], s[14:15], 0, v[24:25]
	v_lshl_add_u64 v[28:29], s[16:17], 0, v[24:25]
	v_lshl_add_u64 v[34:35], s[18:19], 0, v[24:25]
	global_load_dwordx4 v[8:11], v[18:19], off offset:16
	global_load_dwordx4 v[12:15], v[18:19], off
	s_nop 0
	global_load_dwordx4 v[16:19], v[26:27], off
	global_load_dwordx4 v[20:23], v[28:29], off
	v_lshl_add_u64 v[36:37], s[40:41], 0, v[24:25]
	global_load_dwordx4 v[24:27], v[34:35], off
	global_load_dwordx4 v[28:31], v[36:37], off offset:-2048
	s_and_saveexec_b64 s[6:7], s[4:5]
	s_cbranch_execz .LBB0_842
	v_lshl_add_u64 v[0:1], v[32:33], 1, s[50:51]
	v_lshl_add_u32 v2, v4, 4, s58
	v_lshl_add_u64 v[0:1], s[52:53], 1, v[0:1]
	s_lshl_b32 s8, s54, 5
	s_mov_b32 s9, 0
	v_ashrrev_i32_e32 v3, 31, v2
	v_lshl_add_u64 v[0:1], v[0:1], 0, s[8:9]
	v_mov_b32_e32 v67, v5
	v_lshlrev_b64 v[2:3], 2, v[2:3]
	v_lshl_add_u64 v[0:1], v[0:1], 0, v[66:67]
	v_lshl_add_u64 v[6:7], s[22:23], 0, v[2:3]
	v_lshl_add_u64 v[32:33], s[24:25], 0, v[2:3]
	global_load_dwordx4 v[0:3], v[0:1], off
	s_nop 0
	global_load_dword v6, v[6:7], off
	s_nop 0
	global_load_dword v196, v[32:33], off
.LBB0_842:
	s_or_b64 exec, exec, s[6:7]
	v_add_u32_e32 v4, 64, v60
	v_lshlrev_b64 v[68:69], 10, v[4:5]
	v_lshl_add_u64 v[40:41], v[68:69], 0, s[52:53]
	v_or_b32_e32 v40, v40, v64
	v_lshlrev_b64 v[48:49], 1, v[40:41]
	v_lshl_add_u64 v[42:43], v[40:41], 2, s[12:13]
	v_lshl_add_u64 v[50:51], s[14:15], 0, v[48:49]
	v_lshl_add_u64 v[52:53], s[16:17], 0, v[48:49]
	v_lshl_add_u64 v[56:57], s[18:19], 0, v[48:49]
	global_load_dwordx4 v[32:35], v[42:43], off offset:16
	global_load_dwordx4 v[36:39], v[42:43], off
	s_nop 0
	global_load_dwordx4 v[40:43], v[50:51], off
	global_load_dwordx4 v[44:47], v[52:53], off
	v_lshl_add_u64 v[58:59], s[40:41], 0, v[48:49]
	global_load_dwordx4 v[48:51], v[56:57], off
	global_load_dwordx4 v[52:55], v[58:59], off offset:-2048
	s_and_saveexec_b64 s[6:7], s[4:5]
	s_cbranch_execz .LBB0_844
	v_lshl_add_u64 v[56:57], v[68:69], 1, s[50:51]
	v_lshl_add_u64 v[56:57], s[52:53], 1, v[56:57]
	s_lshl_b32 s4, s54, 5
	s_mov_b32 s5, 0
	v_lshl_add_u32 v4, v4, 4, s58
	v_lshl_add_u64 v[56:57], v[56:57], 0, s[4:5]
	v_mov_b32_e32 v67, 0
	v_ashrrev_i32_e32 v5, 31, v4
	v_lshl_add_u64 v[66:67], v[56:57], 0, v[66:67]
	v_lshlrev_b64 v[4:5], 2, v[4:5]
	v_lshl_add_u64 v[68:69], s[22:23], 0, v[4:5]
	v_lshl_add_u64 v[4:5], s[24:25], 0, v[4:5]
	global_load_dwordx4 v[56:59], v[66:67], off
	global_load_dword v62, v[68:69], off
	global_load_dword v197, v[4:5], off

; #define LAS __attribute__((address_space(3)))
; __device__ __forceinline__ void rwkv_scan(Frame& F, int wg, unsigned* shw, unsigned wait_target, int wait_blk) {
;     ...
;     auto gload = [&](LdRegs& L, int blk) {
;         const int t = blk * RW_TB + lstep; const size_t o = (size_t)t * 1024 + h * 64 + 8 * part;
;         L.w0 = *(const f32x4*)(Wd + o); L.w1 = *(const f32x4*)(Wd + o + 4);
;         L.a = *(const u32x4*)(Ab + o); L.b = *(const u32x4*)(Bb + o); L.k = *(const u32x4*)(Kp + o); L.r = *(const u32x4*)(Rb + o);
;         if (part < 2) { L.v = *(const u32x4*)(Vb + (size_t)t * 1024 + h * 64 + 16 * rq + 8 * part); L.br = BR[t * 16 + h]; L.kr = KR[t * 16 + h]; }
;     };
;     auto lstore = [&](const LdRegs& L, int b) {
;         LAS float* rec = buf + (b * RW_TB + lstep) * RW_REC;
;         const u32x4 av = L.a, bv = L.b, kv = L.k, rv = L.r;
;         f32x4 a_0 = {bflo(av.x), bfhi(av.x), bflo(av.y), bfhi(av.y)}, a_1 = {bflo(av.z), bfhi(av.z), bflo(av.w), bfhi(av.w)};
;         f32x4 b_0 = {bflo(bv.x), bfhi(bv.x), bflo(bv.y), bfhi(bv.y)}, b_1 = {bflo(bv.z), bfhi(bv.z), bflo(bv.w), bfhi(bv.w)};
;         f32x4 k_0 = {bflo(kv.x), bfhi(kv.x), bflo(kv.y), bfhi(kv.y)}, k_1 = {bflo(kv.z), bfhi(kv.z), bflo(kv.w), bfhi(kv.w)};
;         f32x4 r_0 = {bflo(rv.x), bfhi(rv.x), bflo(rv.y), bfhi(rv.y)}, r_1 = {bflo(rv.z), bfhi(rv.z), bflo(rv.w), bfhi(rv.w)};
;         *(LAS f32x4*)(rec + 8 * part) = L.w0; *(LAS f32x4*)(rec + 8 * part + 4) = L.w1;
;         *(LAS f32x4*)(rec + 64 + 8 * part) = a_0; *(LAS f32x4*)(rec + 64 + 8 * part + 4) = a_1;
;         *(LAS f32x4*)(rec + 128 + 8 * part) = b_0; *(LAS f32x4*)(rec + 128 + 8 * part + 4) = b_1;
;         *(LAS f32x4*)(rec + 192 + 8 * part) = k_0; *(LAS f32x4*)(rec + 192 + 8 * part + 4) = k_1;
;         *(LAS f32x4*)(rec + 256 + 8 * part) = L.w0 * r_0; *(LAS f32x4*)(rec + 256 + 8 * part + 4) = L.w1 * r_1;
;         if (part < 2) { const u32x4 vv = L.v;
;             const float v8[8] = {bflo(vv.x), bfhi(vv.x), bflo(vv.y), bfhi(vv.y), bflo(vv.z), bfhi(vv.z), bflo(vv.w), bfhi(vv.w)};
; #pragma unroll
;             for (int e = 0; e < 8; ++e) *(LAS f32x4*)(rec + 320 + (8 * part + e) * 4) = (f32x4){v8[e], v8[e] * L.kr, L.br, 0.f}; }
;     };
.LBB0_850:
	s_and_b64 vcc, exec, s[50:51]
	s_cbranch_vccz .LBB0_890
	s_waitcnt vmcnt(0)
	v_add_u32_e32 v100, v199, v195
	v_lshl_add_u32 v101, v195, 1, v199
	v_lshlrev_b32_e32 v104, 16, v20
	v_and_b32_e32 v105, 0xffff0000, v20
	v_lshlrev_b32_e32 v106, 16, v21
	v_and_b32_e32 v107, 0xffff0000, v21
	v_lshlrev_b32_e32 v108, 16, v22
	v_and_b32_e32 v109, 0xffff0000, v22
	v_lshlrev_b32_e32 v110, 16, v23
	v_and_b32_e32 v111, 0xffff0000, v23
	ds_write_b128 v100, v[104:107] offset:49920
	ds_write_b128 v100, v[108:111] offset:49936
	v_lshlrev_b32_e32 v112, 16, v24
	v_and_b32_e32 v113, 0xffff0000, v24
	v_lshlrev_b32_e32 v114, 16, v25
	v_and_b32_e32 v115, 0xffff0000, v25
	v_lshlrev_b32_e32 v116, 16, v26
	v_and_b32_e32 v117, 0xffff0000, v26
	v_lshlrev_b32_e32 v118, 16, v27
	v_and_b32_e32 v119, 0xffff0000, v27
	ds_write_b128 v100, v[112:115] offset:50176
	ds_write_b128 v100, v[116:119] offset:50192
	v_lshlrev_b32_e32 v120, 16, v16
	v_lshlrev_b32_e32 v121, 16, v28
	v_and_b32_e32 v122, 0xffff0000, v16
	v_and_b32_e32 v123, 0xffff0000, v28
	ds_write_b128 v101, v[120:123] offset:49408
	v_lshlrev_b32_e32 v124, 16, v17
	v_lshlrev_b32_e32 v125, 16, v29
	v_and_b32_e32 v126, 0xffff0000, v17
	v_and_b32_e32 v127, 0xffff0000, v29
	ds_write_b128 v101, v[124:127] offset:49424
	v_lshlrev_b32_e32 v128, 16, v18
	v_lshlrev_b32_e32 v129, 16, v30
	v_and_b32_e32 v130, 0xffff0000, v18
	v_and_b32_e32 v131, 0xffff0000, v30
	ds_write_b128 v101, v[128:131] offset:49440
	v_lshlrev_b32_e32 v132, 16, v19
	v_lshlrev_b32_e32 v133, 16, v31
	v_and_b32_e32 v134, 0xffff0000, v19
	v_and_b32_e32 v135, 0xffff0000, v31
	ds_write_b128 v101, v[132:135] offset:49456
	ds_write_b128 v100, v[12:15] offset:49152
	ds_write_b128 v100, v[8:11] offset:49168
	s_and_saveexec_b64 s[50:51], s[10:11]
	s_cbranch_execz .LBB0_853
	v_lshlrev_b32_e32 v4, 16, v0
	v_and_b32_e32 v64, 0xffff0000, v0
	v_lshlrev_b32_e32 v72, 16, v1
	v_and_b32_e32 v76, 0xffff0000, v1
	v_lshlrev_b32_e32 v80, 16, v2
	v_and_b32_e32 v84, 0xffff0000, v2
	v_lshlrev_b32_e32 v88, 16, v3
	v_and_b32_e32 v92, 0xffff0000, v3
	v_mul_f32_e32 v5, v196, v4
	v_add_u32_e32 v60, v199, v200
	v_mov_b32_e32 v7, v67
	v_mul_f32_e32 v65, v196, v64
	v_mov_b32_e32 v66, v6
	v_mul_f32_e32 v73, v196, v72
	v_mov_b32_e32 v74, v6
	v_mov_b32_e32 v75, v67
	v_mul_f32_e32 v77, v196, v76
	v_mov_b32_e32 v78, v6
	v_mov_b32_e32 v79, v67
	v_mul_f32_e32 v81, v196, v80
	v_mov_b32_e32 v82, v6
	v_mov_b32_e32 v83, v67
	v_mul_f32_e32 v85, v196, v84
	v_mov_b32_e32 v86, v6
	v_mov_b32_e32 v87, v67
	v_mul_f32_e32 v89, v196, v88
	v_mov_b32_e32 v90, v6
	v_mov_b32_e32 v91, v67
	v_mul_f32_e32 v93, v196, v92
	v_mov_b32_e32 v94, v6
	v_mov_b32_e32 v95, v67
	ds_write_b128 v60, v[4:7] offset:50432
	ds_write_b128 v60, v[64:67] offset:50448
	ds_write_b128 v60, v[72:75] offset:50464
	ds_write_b128 v60, v[76:79] offset:50480
	ds_write_b128 v60, v[80:83] offset:50496
	ds_write_b128 v60, v[84:87] offset:50512
	ds_write_b128 v60, v[88:91] offset:50528
	ds_write_b128 v60, v[92:95] offset:50544
.LBB0_853:
	s_or_b64 exec, exec, s[50:51]
	s_cmpk_gt_u32 s59, 0x1fc
	s_cbranch_scc1 .LBB0_891
	v_lshl_add_u32 v66, s59, 5, v201
	v_lshlrev_b64 v[4:5], 10, v[66:67]
	v_lshl_add_u64 v[16:17], v[4:5], 0, v[190:191]
	v_lshlrev_b64 v[24:25], 1, v[16:17]
	v_lshl_add_u64 v[12:13], v[16:17], 2, s[12:13]
	v_lshl_add_u64 v[16:17], s[14:15], 0, v[24:25]
	v_lshl_add_u64 v[20:21], s[16:17], 0, v[24:25]
	v_lshl_add_u64 v[26:27], s[18:19], 0, v[24:25]
	v_lshl_add_u64 v[28:29], s[40:41], 0, v[24:25]
	global_load_dwordx4 v[8:11], v[12:13], off offset:16
	s_nop 0
	global_load_dwordx4 v[12:15], v[12:13], off
	s_nop 0
	global_load_dwordx4 v[16:19], v[16:17], off
	s_nop 0
	global_load_dwordx4 v[20:23], v[20:21], off
	s_nop 0
	global_load_dwordx4 v[24:27], v[26:27], off
	s_nop 0
	global_load_dwordx4 v[28:31], v[28:29], off offset:-2048
	s_and_saveexec_b64 s[50:51], s[10:11]
	s_cbranch_execz .LBB0_856
	v_lshl_add_u32 v0, v66, 4, s58
	v_ashrrev_i32_e32 v1, 31, v0
	v_lshlrev_b64 v[0:1], 2, v[0:1]
	v_lshl_add_u64 v[60:61], s[24:25], 0, v[0:1]
	v_lshl_add_u64 v[6:7], s[22:23], 0, v[0:1]
	v_lshl_add_u64 v[0:1], v[4:5], 1, v[192:193]
	global_load_dwordx4 v[0:3], v[0:1], off
	s_nop 0
	global_load_dword v6, v[6:7], off
	s_nop 0
	global_load_dword v196, v[60:61], off

; __device__ __forceinline__ void rwkv_scan(Frame& F, int wg, unsigned* shw, unsigned wait_target, int wait_blk) {
;     ...
;             RwOps R[4];
;             RW_LD(R[0], 0); RW_LD(R[1], 1); RW_LD(R[2], 2);
;             for (int s4 = 0; s4 < RW_TB; s4 += 4) {
;                 float pz[4], u[4];
; #pragma unroll
;                 for (int q = 0; q < 4; ++q) {
;                     RW_LD(R[(q + 3) & 3], s4 + q + 3);
;                     const RwOps& cur = R[q];
;                     const f32x2 slo = {st.x, st.y}, shi = {st.z, st.w};
;                     f32x2 ma = slo * (f32x2){cur.a.x, cur.a.y}; ma = __builtin_elementwise_fma(shi, (f32x2){cur.a.z, cur.a.w}, ma);
;                     f32x2 mz = slo * (f32x2){cur.wr.x, cur.wr.y}; mz = __builtin_elementwise_fma(shi, (f32x2){cur.wr.z, cur.wr.w}, mz);
;                     float psa = ma.x + ma.y; pz[q] = mz.x + mz.y;
;                     const f32x2 vb = {cur.vs.x, cur.vs.x};
;                     f32x2 tlo = (f32x2){cur.k.x, cur.k.y} * vb, thi = (f32x2){cur.k.z, cur.k.w} * vb;
;                     tlo = __builtin_elementwise_fma(slo, (f32x2){cur.w.x, cur.w.y}, tlo); thi = __builtin_elementwise_fma(shi, (f32x2){cur.w.z, cur.w.w}, thi);
;                     psa = red16(psa);
;                     const f32x2 pb = {psa, psa};
;                     tlo = __builtin_elementwise_fma((f32x2){cur.b.x, cur.b.y}, pb, tlo); thi = __builtin_elementwise_fma((f32x2){cur.b.z, cur.b.w}, pb, thi);
;                     st = (f32x4){tlo.x, tlo.y, thi.x, thi.y};
;                     u[q] = psa * cur.vs.z + cur.vs.y;
;                 }
;                 const float qa = (odd1 ? pz[1] : pz[0]) + dppf<0xB1>(odd1 ? pz[0] : pz[1]);
;                 const float qb = (odd1 ? pz[3] : pz[2]) + dppf<0xB1>(odd1 ? pz[2] : pz[3]);
;                 float r = (odd2 ? qb : qa) + dppf<0x4E>(odd2 ? qa : qb);
;                 r += dppf<0x124>(r); r += dppf<0x128>(r);
;                 const float us = odd2 ? (odd1 ? u[3] : u[2]) : (odd1 ? u[1] : u[0]);
;                 if (j < 4) { const int t = blk * RW_TB + s4 + j; ((float*)(Ub + (size_t)t * (PWP * 2) + URR * 2))[h * 64 + row] = r + us; }
;             }
.LBB0_873:
	s_mul_i32 s50, s59, 0x58000
	s_add_i32 s50, s50, 0xffff5000
	v_add_u32_e32 v160, v198, v198
	ds_read_b128 v[80:83], v160 offset:256
	ds_read_b128 v[84:87], v160 offset:272
	ds_read_b128 v[92:95], v198 offset:1024
	ds_read_b32 v96, v204 offset:1280
	ds_read_b128 v[76:79], v198 offset:0
	ds_read_b128 v[88:91], v198 offset:768
	ds_read_b128 v[102:105], v160 offset:1792
	ds_read_b128 v[106:109], v160 offset:1808
	ds_read_b128 v[114:117], v198 offset:2560
	ds_read_b32 v118, v204 offset:2816
	ds_read_b128 v[98:101], v198 offset:1536
	ds_read_b128 v[110:113], v198 offset:2304
	v_lshrrev_b32_e32 v159, 2, v194
	v_mul_u32_u24_e32 v159, 0x2c00, v159
	v_lshl_add_u32 v159, v186, 2, v159
	v_add_u32_e32 v159, s50, v159
	s_waitcnt lgkmcnt(6)
	v_pk_mul_f32 v[142:143], v[68:69], v[80:81] op_sel_hi:[0,1]
	v_pk_fma_f32 v[142:143], v[68:69], v[82:83], v[142:143] op_sel:[1,0,0] op_sel_hi:[1,1,1]
	v_pk_fma_f32 v[142:143], v[70:71], v[84:85], v[142:143] op_sel_hi:[0,1,1]
	v_pk_fma_f32 v[142:143], v[70:71], v[86:87], v[142:143] op_sel:[1,0,0] op_sel_hi:[1,1,1]
	v_pk_mul_f32 v[152:153], v[92:93], v[96:97] op_sel_hi:[1,0]
	v_pk_mul_f32 v[154:155], v[94:95], v[96:97] op_sel_hi:[1,0]
	v_add_f32_dpp v150, v142, v142 quad_perm:[1,0,3,2] row_mask:0xf bank_mask:0xf bound_ctrl:1
	v_pk_fma_f32 v[152:153], v[68:69], v[76:77], v[152:153]
	v_pk_fma_f32 v[154:155], v[70:71], v[78:79], v[154:155]
	v_add_f32_dpp v150, v150, v150 quad_perm:[2,3,0,1] row_mask:0xf bank_mask:0xf bound_ctrl:1
	v_add_f32_dpp v156, v145, v145 row_ror:8 row_mask:0xf bank_mask:0xf
	v_add_f32_dpp v157, v147, v147 row_ror:8 row_mask:0xf bank_mask:0xf
	v_add_f32_dpp v150, v150, v150 row_half_mirror row_mask:0xf bank_mask:0xf bound_ctrl:1
	v_add_f32_dpp v156, v149, v149 row_ror:8 row_mask:0xf bank_mask:0xc
	v_add_f32_dpp v157, v143, v143 row_ror:8 row_mask:0xf bank_mask:0xc
	v_add_f32_dpp v150, v150, v150 row_mirror row_mask:0xf bank_mask:0xf bound_ctrl:1
	v_pk_fma_f32 v[72:73], v[88:89], v[150:151], v[152:153] op_sel_hi:[1,0,1]
	v_pk_fma_f32 v[74:75], v[90:91], v[150:151], v[154:155] op_sel_hi:[1,0,1]
	ds_read_b128 v[124:127], v160 offset:3328
	ds_read_b128 v[128:131], v160 offset:3344
	v_add_f32_dpp v158, v156, v156 row_half_mirror row_mask:0xf bank_mask:0xf
	v_add_f32_dpp v158, v157, v157 row_half_mirror row_mask:0xf bank_mask:0xa
	ds_read_b128 v[136:139], v198 offset:4096
	ds_read_b32 v140, v204 offset:4352
	v_add_f32_dpp v158, v158, v158 quad_perm:[1,0,3,2] row_mask:0xf bank_mask:0xf bound_ctrl:1
	ds_read_b128 v[120:123], v198 offset:3072
	ds_read_b128 v[132:135], v198 offset:3840
	v_add_f32_dpp v158, v158, v158 quad_perm:[2,3,0,1] row_mask:0xf bank_mask:0xf bound_ctrl:1
	s_cmp_lg_u32 s59, 0
	s_cselect_b64 exec, -1, 0
	global_store_dword v159, v158, s[34:35]
	s_mov_b64 exec, -1
	v_add_u32_e32 v159, 0xb000, v159
	s_waitcnt lgkmcnt(6)
	v_pk_mul_f32 v[144:145], v[72:73], v[102:103] op_sel_hi:[0,1]
	v_pk_fma_f32 v[144:145], v[72:73], v[104:105], v[144:145] op_sel:[1,0,0] op_sel_hi:[1,1,1]
	v_pk_fma_f32 v[144:145], v[74:75], v[106:107], v[144:145] op_sel_hi:[0,1,1]
	v_pk_fma_f32 v[144:145], v[74:75], v[108:109], v[144:145] op_sel:[1,0,0] op_sel_hi:[1,1,1]
	v_pk_mul_f32 v[152:153], v[114:115], v[118:119] op_sel_hi:[1,0]
	v_pk_mul_f32 v[154:155], v[116:117], v[118:119] op_sel_hi:[1,0]
	v_add_f32_dpp v150, v144, v144 quad_perm:[1,0,3,2] row_mask:0xf bank_mask:0xf bound_ctrl:1
	v_pk_fma_f32 v[152:153], v[72:73], v[98:99], v[152:153]
	v_pk_fma_f32 v[154:155], v[74:75], v[100:101], v[154:155]
	v_add_f32_dpp v150, v150, v150 quad_perm:[2,3,0,1] row_mask:0xf bank_mask:0xf bound_ctrl:1
	ds_read_b128 v[80:83], v160 offset:4864
	ds_read_b128 v[84:87], v160 offset:4880
	v_add_f32_dpp v150, v150, v150 row_half_mirror row_mask:0xf bank_mask:0xf bound_ctrl:1
	ds_read_b128 v[92:95], v198 offset:5632
	ds_read_b32 v96, v204 offset:5888
	v_add_f32_dpp v150, v150, v150 row_mirror row_mask:0xf bank_mask:0xf bound_ctrl:1
	v_pk_fma_f32 v[68:69], v[110:111], v[150:151], v[152:153] op_sel_hi:[1,0,1]
	v_pk_fma_f32 v[70:71], v[112:113], v[150:151], v[154:155] op_sel_hi:[1,0,1]
	ds_read_b128 v[76:79], v198 offset:4608
	ds_read_b128 v[88:91], v198 offset:5376
	s_waitcnt lgkmcnt(6)
	v_pk_mul_f32 v[146:147], v[68:69], v[124:125] op_sel_hi:[0,1]
	v_pk_fma_f32 v[146:147], v[68:69], v[126:127], v[146:147] op_sel:[1,0,0] op_sel_hi:[1,1,1]
	v_pk_fma_f32 v[146:147], v[70:71], v[128:129], v[146:147] op_sel_hi:[0,1,1]
	v_pk_fma_f32 v[146:147], v[70:71], v[130:131], v[146:147] op_sel:[1,0,0] op_sel_hi:[1,1,1]
	v_pk_mul_f32 v[152:153], v[136:137], v[140:141] op_sel_hi:[1,0]
	v_pk_mul_f32 v[154:155], v[138:139], v[140:141] op_sel_hi:[1,0]
	v_add_f32_dpp v150, v146, v146 quad_perm:[1,0,3,2] row_mask:0xf bank_mask:0xf bound_ctrl:1
	v_pk_fma_f32 v[152:153], v[68:69], v[120:121], v[152:153]
	v_pk_fma_f32 v[154:155], v[70:71], v[122:123], v[154:155]
	v_add_f32_dpp v150, v150, v150 quad_perm:[2,3,0,1] row_mask:0xf bank_mask:0xf bound_ctrl:1
	ds_read_b128 v[102:105], v160 offset:6400
	ds_read_b128 v[106:109], v160 offset:6416
	v_add_f32_dpp v150, v150, v150 row_half_mirror row_mask:0xf bank_mask:0xf bound_ctrl:1
	ds_read_b128 v[114:117], v198 offset:7168
	ds_read_b32 v118, v204 offset:7424
	v_add_f32_dpp v150, v150, v150 row_mirror row_mask:0xf bank_mask:0xf bound_ctrl:1
	v_pk_fma_f32 v[72:73], v[132:133], v[150:151], v[152:153] op_sel_hi:[1,0,1]
	v_pk_fma_f32 v[74:75], v[134:135], v[150:151], v[154:155] op_sel_hi:[1,0,1]
	ds_read_b128 v[98:101], v198 offset:6144
	ds_read_b128 v[110:113], v198 offset:6912
	s_waitcnt lgkmcnt(6)
; __device__ __forceinline__ void rwkv_scan(Frame& F, int wg, unsigned* shw, unsigned wait_target, int wait_blk) {
;     ...
;             RwOps R[4];
;             RW_LD(R[0], 0); RW_LD(R[1], 1); RW_LD(R[2], 2);
;             for (int s4 = 0; s4 < RW_TB; s4 += 4) {
;                 float pz[4], u[4];
; #pragma unroll
;                 for (int q = 0; q < 4; ++q) {
;                     RW_LD(R[(q + 3) & 3], s4 + q + 3);
;                     const RwOps& cur = R[q];
;                     const f32x2 slo = {st.x, st.y}, shi = {st.z, st.w};
;                     f32x2 ma = slo * (f32x2){cur.a.x, cur.a.y}; ma = __builtin_elementwise_fma(shi, (f32x2){cur.a.z, cur.a.w}, ma);
;                     f32x2 mz = slo * (f32x2){cur.wr.x, cur.wr.y}; mz = __builtin_elementwise_fma(shi, (f32x2){cur.wr.z, cur.wr.w}, mz);
;                     float psa = ma.x + ma.y; pz[q] = mz.x + mz.y;
;                     const f32x2 vb = {cur.vs.x, cur.vs.x};
;                     f32x2 tlo = (f32x2){cur.k.x, cur.k.y} * vb, thi = (f32x2){cur.k.z, cur.k.w} * vb;
;                     tlo = __builtin_elementwise_fma(slo, (f32x2){cur.w.x, cur.w.y}, tlo); thi = __builtin_elementwise_fma(shi, (f32x2){cur.w.z, cur.w.w}, thi);
;                     psa = red16(psa);
;                     const f32x2 pb = {psa, psa};
;                     tlo = __builtin_elementwise_fma((f32x2){cur.b.x, cur.b.y}, pb, tlo); thi = __builtin_elementwise_fma((f32x2){cur.b.z, cur.b.w}, pb, thi);
;                     st = (f32x4){tlo.x, tlo.y, thi.x, thi.y};
;                     u[q] = psa * cur.vs.z + cur.vs.y;
;                 }
;                 const float qa = (odd1 ? pz[1] : pz[0]) + dppf<0xB1>(odd1 ? pz[0] : pz[1]);
;                 const float qb = (odd1 ? pz[3] : pz[2]) + dppf<0xB1>(odd1 ? pz[2] : pz[3]);
;                 float r = (odd2 ? qb : qa) + dppf<0x4E>(odd2 ? qa : qb);
;                 r += dppf<0x124>(r); r += dppf<0x128>(r);
;                 const float us = odd2 ? (odd1 ? u[3] : u[2]) : (odd1 ? u[1] : u[0]);
;                 if (j < 4) { const int t = blk * RW_TB + s4 + j; ((float*)(Ub + (size_t)t * (PWP * 2) + URR * 2))[h * 64 + row] = r + us; }
;             }
	v_pk_mul_f32 v[148:149], v[72:73], v[80:81] op_sel_hi:[0,1]
	v_pk_fma_f32 v[148:149], v[72:73], v[82:83], v[148:149] op_sel:[1,0,0] op_sel_hi:[1,1,1]
	v_pk_fma_f32 v[148:149], v[74:75], v[84:85], v[148:149] op_sel_hi:[0,1,1]
	v_pk_fma_f32 v[148:149], v[74:75], v[86:87], v[148:149] op_sel:[1,0,0] op_sel_hi:[1,1,1]
	v_pk_mul_f32 v[152:153], v[92:93], v[96:97] op_sel_hi:[1,0]
	v_pk_mul_f32 v[154:155], v[94:95], v[96:97] op_sel_hi:[1,0]
	v_add_f32_dpp v150, v148, v148 quad_perm:[1,0,3,2] row_mask:0xf bank_mask:0xf bound_ctrl:1
	v_pk_fma_f32 v[152:153], v[72:73], v[76:77], v[152:153]
	v_pk_fma_f32 v[154:155], v[74:75], v[78:79], v[154:155]
	v_add_f32_dpp v150, v150, v150 quad_perm:[2,3,0,1] row_mask:0xf bank_mask:0xf bound_ctrl:1
	ds_read_b128 v[124:127], v160 offset:7936
	ds_read_b128 v[128:131], v160 offset:7952
	v_add_f32_dpp v150, v150, v150 row_half_mirror row_mask:0xf bank_mask:0xf bound_ctrl:1
	ds_read_b128 v[136:139], v198 offset:8704
	ds_read_b32 v140, v204 offset:8960
	v_add_f32_dpp v150, v150, v150 row_mirror row_mask:0xf bank_mask:0xf bound_ctrl:1
	v_pk_fma_f32 v[68:69], v[88:89], v[150:151], v[152:153] op_sel_hi:[1,0,1]
	v_pk_fma_f32 v[70:71], v[90:91], v[150:151], v[154:155] op_sel_hi:[1,0,1]
	ds_read_b128 v[120:123], v198 offset:7680
	ds_read_b128 v[132:135], v198 offset:8448
	s_waitcnt lgkmcnt(6)
	v_pk_mul_f32 v[142:143], v[68:69], v[102:103] op_sel_hi:[0,1]
	v_pk_fma_f32 v[142:143], v[68:69], v[104:105], v[142:143] op_sel:[1,0,0] op_sel_hi:[1,1,1]
	v_pk_fma_f32 v[142:143], v[70:71], v[106:107], v[142:143] op_sel_hi:[0,1,1]
	v_pk_fma_f32 v[142:143], v[70:71], v[108:109], v[142:143] op_sel:[1,0,0] op_sel_hi:[1,1,1]
	v_pk_mul_f32 v[152:153], v[114:115], v[118:119] op_sel_hi:[1,0]
	v_pk_mul_f32 v[154:155], v[116:117], v[118:119] op_sel_hi:[1,0]
	v_add_f32_dpp v150, v142, v142 quad_perm:[1,0,3,2] row_mask:0xf bank_mask:0xf bound_ctrl:1
	v_pk_fma_f32 v[152:153], v[68:69], v[98:99], v[152:153]
	v_pk_fma_f32 v[154:155], v[70:71], v[100:101], v[154:155]
	v_add_f32_dpp v150, v150, v150 quad_perm:[2,3,0,1] row_mask:0xf bank_mask:0xf bound_ctrl:1
	v_add_f32_dpp v156, v145, v145 row_ror:8 row_mask:0xf bank_mask:0xf
	v_add_f32_dpp v157, v147, v147 row_ror:8 row_mask:0xf bank_mask:0xf
	v_add_f32_dpp v150, v150, v150 row_half_mirror row_mask:0xf bank_mask:0xf bound_ctrl:1
	v_add_f32_dpp v156, v149, v149 row_ror:8 row_mask:0xf bank_mask:0xc
	v_add_f32_dpp v157, v143, v143 row_ror:8 row_mask:0xf bank_mask:0xc
	v_add_f32_dpp v150, v150, v150 row_mirror row_mask:0xf bank_mask:0xf bound_ctrl:1
	v_pk_fma_f32 v[72:73], v[110:111], v[150:151], v[152:153] op_sel_hi:[1,0,1]
	v_pk_fma_f32 v[74:75], v[112:113], v[150:151], v[154:155] op_sel_hi:[1,0,1]
	ds_read_b128 v[80:83], v160 offset:9472
	ds_read_b128 v[84:87], v160 offset:9488
	v_add_f32_dpp v158, v156, v156 row_half_mirror row_mask:0xf bank_mask:0xf
	v_add_f32_dpp v158, v157, v157 row_half_mirror row_mask:0xf bank_mask:0xa
	ds_read_b128 v[92:95], v198 offset:10240
	ds_read_b32 v96, v204 offset:10496
	v_add_f32_dpp v158, v158, v158 quad_perm:[1,0,3,2] row_mask:0xf bank_mask:0xf bound_ctrl:1
	ds_read_b128 v[76:79], v198 offset:9216
	ds_read_b128 v[88:91], v198 offset:9984
	v_add_f32_dpp v158, v158, v158 quad_perm:[2,3,0,1] row_mask:0xf bank_mask:0xf bound_ctrl:1
	global_store_dword v159, v158, s[34:35]
	v_add_u32_e32 v159, 0xb000, v159
	s_waitcnt lgkmcnt(6)
	v_pk_mul_f32 v[144:145], v[72:73], v[124:125] op_sel_hi:[0,1]
	v_pk_fma_f32 v[144:145], v[72:73], v[126:127], v[144:145] op_sel:[1,0,0] op_sel_hi:[1,1,1]
	v_pk_fma_f32 v[144:145], v[74:75], v[128:129], v[144:145] op_sel_hi:[0,1,1]
	v_pk_fma_f32 v[144:145], v[74:75], v[130:131], v[144:145] op_sel:[1,0,0] op_sel_hi:[1,1,1]
	v_pk_mul_f32 v[152:153], v[136:137], v[140:141] op_sel_hi:[1,0]
	v_pk_mul_f32 v[154:155], v[138:139], v[140:141] op_sel_hi:[1,0]
	v_add_f32_dpp v150, v144, v144 quad_perm:[1,0,3,2] row_mask:0xf bank_mask:0xf bound_ctrl:1
	v_pk_fma_f32 v[152:153], v[72:73], v[120:121], v[152:153]
	v_pk_fma_f32 v[154:155], v[74:75], v[122:123], v[154:155]
	v_add_f32_dpp v150, v150, v150 quad_perm:[2,3,0,1] row_mask:0xf bank_mask:0xf bound_ctrl:1
	ds_read_b128 v[102:105], v160 offset:11008
	ds_read_b128 v[106:109], v160 offset:11024
	v_add_f32_dpp v150, v150, v150 row_half_mirror row_mask:0xf bank_mask:0xf bound_ctrl:1
	ds_read_b128 v[114:117], v198 offset:11776
	ds_read_b32 v118, v204 offset:12032
	v_add_f32_dpp v150, v150, v150 row_mirror row_mask:0xf bank_mask:0xf bound_ctrl:1
	v_pk_fma_f32 v[68:69], v[132:133], v[150:151], v[152:153] op_sel_hi:[1,0,1]
	v_pk_fma_f32 v[70:71], v[134:135], v[150:151], v[154:155] op_sel_hi:[1,0,1]
	ds_read_b128 v[98:101], v198 offset:10752
	ds_read_b128 v[110:113], v198 offset:11520
	s_waitcnt lgkmcnt(6)
	v_pk_mul_f32 v[146:147], v[68:69], v[80:81] op_sel_hi:[0,1]
	v_pk_fma_f32 v[146:147], v[68:69], v[82:83], v[146:147] op_sel:[1,0,0] op_sel_hi:[1,1,1]
	v_pk_fma_f32 v[146:147], v[70:71], v[84:85], v[146:147] op_sel_hi:[0,1,1]
	v_pk_fma_f32 v[146:147], v[70:71], v[86:87], v[146:147] op_sel:[1,0,0] op_sel_hi:[1,1,1]
	v_pk_mul_f32 v[152:153], v[92:93], v[96:97] op_sel_hi:[1,0]
	v_pk_mul_f32 v[154:155], v[94:95], v[96:97] op_sel_hi:[1,0]
	v_add_f32_dpp v150, v146, v146 quad_perm:[1,0,3,2] row_mask:0xf bank_mask:0xf bound_ctrl:1
	v_pk_fma_f32 v[152:153], v[68:69], v[76:77], v[152:153]
	v_pk_fma_f32 v[154:155], v[70:71], v[78:79], v[154:155]
	v_add_f32_dpp v150, v150, v150 quad_perm:[2,3,0,1] row_mask:0xf bank_mask:0xf bound_ctrl:1
	ds_read_b128 v[124:127], v160 offset:12544
	ds_read_b128 v[128:131], v160 offset:12560
	v_add_f32_dpp v150, v150, v150 row_half_mirror row_mask:0xf bank_mask:0xf bound_ctrl:1
	ds_read_b128 v[136:139], v198 offset:13312
	ds_read_b32 v140, v204 offset:13568
	v_add_f32_dpp v150, v150, v150 row_mirror row_mask:0xf bank_mask:0xf bound_ctrl:1
	v_pk_fma_f32 v[72:73], v[88:89], v[150:151], v[152:153] op_sel_hi:[1,0,1]
	v_pk_fma_f32 v[74:75], v[90:91], v[150:151], v[154:155] op_sel_hi:[1,0,1]
	ds_read_b128 v[120:123], v198 offset:12288
	ds_read_b128 v[132:135], v198 offset:13056
	s_waitcnt lgkmcnt(6)
; __device__ __forceinline__ void rwkv_scan(Frame& F, int wg, unsigned* shw, unsigned wait_target, int wait_blk) {
;     ...
;             RwOps R[4];
;             RW_LD(R[0], 0); RW_LD(R[1], 1); RW_LD(R[2], 2);
;             for (int s4 = 0; s4 < RW_TB; s4 += 4) {
;                 float pz[4], u[4];
; #pragma unroll
;                 for (int q = 0; q < 4; ++q) {
;                     RW_LD(R[(q + 3) & 3], s4 + q + 3);
;                     const RwOps& cur = R[q];
;                     const f32x2 slo = {st.x, st.y}, shi = {st.z, st.w};
;                     f32x2 ma = slo * (f32x2){cur.a.x, cur.a.y}; ma = __builtin_elementwise_fma(shi, (f32x2){cur.a.z, cur.a.w}, ma);
;                     f32x2 mz = slo * (f32x2){cur.wr.x, cur.wr.y}; mz = __builtin_elementwise_fma(shi, (f32x2){cur.wr.z, cur.wr.w}, mz);
;                     float psa = ma.x + ma.y; pz[q] = mz.x + mz.y;
;                     const f32x2 vb = {cur.vs.x, cur.vs.x};
;                     f32x2 tlo = (f32x2){cur.k.x, cur.k.y} * vb, thi = (f32x2){cur.k.z, cur.k.w} * vb;
;                     tlo = __builtin_elementwise_fma(slo, (f32x2){cur.w.x, cur.w.y}, tlo); thi = __builtin_elementwise_fma(shi, (f32x2){cur.w.z, cur.w.w}, thi);
;                     psa = red16(psa);
;                     const f32x2 pb = {psa, psa};
;                     tlo = __builtin_elementwise_fma((f32x2){cur.b.x, cur.b.y}, pb, tlo); thi = __builtin_elementwise_fma((f32x2){cur.b.z, cur.b.w}, pb, thi);
;                     st = (f32x4){tlo.x, tlo.y, thi.x, thi.y};
;                     u[q] = psa * cur.vs.z + cur.vs.y;
;                 }
;                 const float qa = (odd1 ? pz[1] : pz[0]) + dppf<0xB1>(odd1 ? pz[0] : pz[1]);
;                 const float qb = (odd1 ? pz[3] : pz[2]) + dppf<0xB1>(odd1 ? pz[2] : pz[3]);
;                 float r = (odd2 ? qb : qa) + dppf<0x4E>(odd2 ? qa : qb);
;                 r += dppf<0x124>(r); r += dppf<0x128>(r);
;                 const float us = odd2 ? (odd1 ? u[3] : u[2]) : (odd1 ? u[1] : u[0]);
;                 if (j < 4) { const int t = blk * RW_TB + s4 + j; ((float*)(Ub + (size_t)t * (PWP * 2) + URR * 2))[h * 64 + row] = r + us; }
;             }
	v_pk_mul_f32 v[148:149], v[72:73], v[102:103] op_sel_hi:[0,1]
	v_pk_fma_f32 v[148:149], v[72:73], v[104:105], v[148:149] op_sel:[1,0,0] op_sel_hi:[1,1,1]
	v_pk_fma_f32 v[148:149], v[74:75], v[106:107], v[148:149] op_sel_hi:[0,1,1]
	v_pk_fma_f32 v[148:149], v[74:75], v[108:109], v[148:149] op_sel:[1,0,0] op_sel_hi:[1,1,1]
	v_pk_mul_f32 v[152:153], v[114:115], v[118:119] op_sel_hi:[1,0]
	v_pk_mul_f32 v[154:155], v[116:117], v[118:119] op_sel_hi:[1,0]
	v_add_f32_dpp v150, v148, v148 quad_perm:[1,0,3,2] row_mask:0xf bank_mask:0xf bound_ctrl:1
	v_pk_fma_f32 v[152:153], v[72:73], v[98:99], v[152:153]
	v_pk_fma_f32 v[154:155], v[74:75], v[100:101], v[154:155]
	v_add_f32_dpp v150, v150, v150 quad_perm:[2,3,0,1] row_mask:0xf bank_mask:0xf bound_ctrl:1
	ds_read_b128 v[80:83], v160 offset:14080
	ds_read_b128 v[84:87], v160 offset:14096
	v_add_f32_dpp v150, v150, v150 row_half_mirror row_mask:0xf bank_mask:0xf bound_ctrl:1
	ds_read_b128 v[92:95], v198 offset:14848
	ds_read_b32 v96, v204 offset:15104
	v_add_f32_dpp v150, v150, v150 row_mirror row_mask:0xf bank_mask:0xf bound_ctrl:1
	v_pk_fma_f32 v[68:69], v[110:111], v[150:151], v[152:153] op_sel_hi:[1,0,1]
	v_pk_fma_f32 v[70:71], v[112:113], v[150:151], v[154:155] op_sel_hi:[1,0,1]
	ds_read_b128 v[76:79], v198 offset:13824
	ds_read_b128 v[88:91], v198 offset:14592
	s_waitcnt lgkmcnt(6)
	v_pk_mul_f32 v[142:143], v[68:69], v[124:125] op_sel_hi:[0,1]
	v_pk_fma_f32 v[142:143], v[68:69], v[126:127], v[142:143] op_sel:[1,0,0] op_sel_hi:[1,1,1]
	v_pk_fma_f32 v[142:143], v[70:71], v[128:129], v[142:143] op_sel_hi:[0,1,1]
	v_pk_fma_f32 v[142:143], v[70:71], v[130:131], v[142:143] op_sel:[1,0,0] op_sel_hi:[1,1,1]
	v_pk_mul_f32 v[152:153], v[136:137], v[140:141] op_sel_hi:[1,0]
	v_pk_mul_f32 v[154:155], v[138:139], v[140:141] op_sel_hi:[1,0]
	v_add_f32_dpp v150, v142, v142 quad_perm:[1,0,3,2] row_mask:0xf bank_mask:0xf bound_ctrl:1
	v_pk_fma_f32 v[152:153], v[68:69], v[120:121], v[152:153]
	v_pk_fma_f32 v[154:155], v[70:71], v[122:123], v[154:155]
	v_add_f32_dpp v150, v150, v150 quad_perm:[2,3,0,1] row_mask:0xf bank_mask:0xf bound_ctrl:1
	v_add_f32_dpp v156, v145, v145 row_ror:8 row_mask:0xf bank_mask:0xf
	v_add_f32_dpp v157, v147, v147 row_ror:8 row_mask:0xf bank_mask:0xf
	v_add_f32_dpp v150, v150, v150 row_half_mirror row_mask:0xf bank_mask:0xf bound_ctrl:1
	v_add_f32_dpp v156, v149, v149 row_ror:8 row_mask:0xf bank_mask:0xc
	v_add_f32_dpp v157, v143, v143 row_ror:8 row_mask:0xf bank_mask:0xc
	v_add_f32_dpp v150, v150, v150 row_mirror row_mask:0xf bank_mask:0xf bound_ctrl:1
	v_pk_fma_f32 v[72:73], v[132:133], v[150:151], v[152:153] op_sel_hi:[1,0,1]
	v_pk_fma_f32 v[74:75], v[134:135], v[150:151], v[154:155] op_sel_hi:[1,0,1]
	ds_read_b128 v[102:105], v160 offset:15616
	ds_read_b128 v[106:109], v160 offset:15632
	v_add_f32_dpp v158, v156, v156 row_half_mirror row_mask:0xf bank_mask:0xf
	v_add_f32_dpp v158, v157, v157 row_half_mirror row_mask:0xf bank_mask:0xa
	ds_read_b128 v[114:117], v198 offset:16384
	ds_read_b32 v118, v204 offset:16640
	v_add_f32_dpp v158, v158, v158 quad_perm:[1,0,3,2] row_mask:0xf bank_mask:0xf bound_ctrl:1
	ds_read_b128 v[98:101], v198 offset:15360
	ds_read_b128 v[110:113], v198 offset:16128
	v_add_f32_dpp v158, v158, v158 quad_perm:[2,3,0,1] row_mask:0xf bank_mask:0xf bound_ctrl:1
	global_store_dword v159, v158, s[34:35]
	v_add_u32_e32 v159, 0xb000, v159
	s_waitcnt lgkmcnt(6)
	v_pk_mul_f32 v[144:145], v[72:73], v[80:81] op_sel_hi:[0,1]
	v_pk_fma_f32 v[144:145], v[72:73], v[82:83], v[144:145] op_sel:[1,0,0] op_sel_hi:[1,1,1]
	v_pk_fma_f32 v[144:145], v[74:75], v[84:85], v[144:145] op_sel_hi:[0,1,1]
	v_pk_fma_f32 v[144:145], v[74:75], v[86:87], v[144:145] op_sel:[1,0,0] op_sel_hi:[1,1,1]
	v_pk_mul_f32 v[152:153], v[92:93], v[96:97] op_sel_hi:[1,0]
	v_pk_mul_f32 v[154:155], v[94:95], v[96:97] op_sel_hi:[1,0]
	v_add_f32_dpp v150, v144, v144 quad_perm:[1,0,3,2] row_mask:0xf bank_mask:0xf bound_ctrl:1
	v_pk_fma_f32 v[152:153], v[72:73], v[76:77], v[152:153]
	v_pk_fma_f32 v[154:155], v[74:75], v[78:79], v[154:155]
	v_add_f32_dpp v150, v150, v150 quad_perm:[2,3,0,1] row_mask:0xf bank_mask:0xf bound_ctrl:1
	ds_read_b128 v[124:127], v160 offset:17152
	ds_read_b128 v[128:131], v160 offset:17168
	v_add_f32_dpp v150, v150, v150 row_half_mirror row_mask:0xf bank_mask:0xf bound_ctrl:1
	ds_read_b128 v[136:139], v198 offset:17920
	ds_read_b32 v140, v204 offset:18176
	v_add_f32_dpp v150, v150, v150 row_mirror row_mask:0xf bank_mask:0xf bound_ctrl:1
	v_pk_fma_f32 v[68:69], v[88:89], v[150:151], v[152:153] op_sel_hi:[1,0,1]
	v_pk_fma_f32 v[70:71], v[90:91], v[150:151], v[154:155] op_sel_hi:[1,0,1]
	ds_read_b128 v[120:123], v198 offset:16896
	ds_read_b128 v[132:135], v198 offset:17664
	s_waitcnt lgkmcnt(6)
	v_pk_mul_f32 v[146:147], v[68:69], v[102:103] op_sel_hi:[0,1]
	v_pk_fma_f32 v[146:147], v[68:69], v[104:105], v[146:147] op_sel:[1,0,0] op_sel_hi:[1,1,1]
	v_pk_fma_f32 v[146:147], v[70:71], v[106:107], v[146:147] op_sel_hi:[0,1,1]
	v_pk_fma_f32 v[146:147], v[70:71], v[108:109], v[146:147] op_sel:[1,0,0] op_sel_hi:[1,1,1]
	v_pk_mul_f32 v[152:153], v[114:115], v[118:119] op_sel_hi:[1,0]
	v_pk_mul_f32 v[154:155], v[116:117], v[118:119] op_sel_hi:[1,0]
	v_add_f32_dpp v150, v146, v146 quad_perm:[1,0,3,2] row_mask:0xf bank_mask:0xf bound_ctrl:1
	v_pk_fma_f32 v[152:153], v[68:69], v[98:99], v[152:153]
	v_pk_fma_f32 v[154:155], v[70:71], v[100:101], v[154:155]
	v_add_f32_dpp v150, v150, v150 quad_perm:[2,3,0,1] row_mask:0xf bank_mask:0xf bound_ctrl:1
	ds_read_b128 v[80:83], v160 offset:18688
	ds_read_b128 v[84:87], v160 offset:18704
	v_add_f32_dpp v150, v150, v150 row_half_mirror row_mask:0xf bank_mask:0xf bound_ctrl:1
	ds_read_b128 v[92:95], v198 offset:19456
	ds_read_b32 v96, v204 offset:19712
	v_add_f32_dpp v150, v150, v150 row_mirror row_mask:0xf bank_mask:0xf bound_ctrl:1
	v_pk_fma_f32 v[72:73], v[110:111], v[150:151], v[152:153] op_sel_hi:[1,0,1]
	v_pk_fma_f32 v[74:75], v[112:113], v[150:151], v[154:155] op_sel_hi:[1,0,1]
	ds_read_b128 v[76:79], v198 offset:18432
	ds_read_b128 v[88:91], v198 offset:19200
	s_waitcnt lgkmcnt(6)
; __device__ __forceinline__ void rwkv_scan(Frame& F, int wg, unsigned* shw, unsigned wait_target, int wait_blk) {
;     ...
;             RwOps R[4];
;             RW_LD(R[0], 0); RW_LD(R[1], 1); RW_LD(R[2], 2);
;             for (int s4 = 0; s4 < RW_TB; s4 += 4) {
;                 float pz[4], u[4];
; #pragma unroll
;                 for (int q = 0; q < 4; ++q) {
;                     RW_LD(R[(q + 3) & 3], s4 + q + 3);
;                     const RwOps& cur = R[q];
;                     const f32x2 slo = {st.x, st.y}, shi = {st.z, st.w};
;                     f32x2 ma = slo * (f32x2){cur.a.x, cur.a.y}; ma = __builtin_elementwise_fma(shi, (f32x2){cur.a.z, cur.a.w}, ma);
;                     f32x2 mz = slo * (f32x2){cur.wr.x, cur.wr.y}; mz = __builtin_elementwise_fma(shi, (f32x2){cur.wr.z, cur.wr.w}, mz);
;                     float psa = ma.x + ma.y; pz[q] = mz.x + mz.y;
;                     const f32x2 vb = {cur.vs.x, cur.vs.x};
;                     f32x2 tlo = (f32x2){cur.k.x, cur.k.y} * vb, thi = (f32x2){cur.k.z, cur.k.w} * vb;
;                     tlo = __builtin_elementwise_fma(slo, (f32x2){cur.w.x, cur.w.y}, tlo); thi = __builtin_elementwise_fma(shi, (f32x2){cur.w.z, cur.w.w}, thi);
;                     psa = red16(psa);
;                     const f32x2 pb = {psa, psa};
;                     tlo = __builtin_elementwise_fma((f32x2){cur.b.x, cur.b.y}, pb, tlo); thi = __builtin_elementwise_fma((f32x2){cur.b.z, cur.b.w}, pb, thi);
;                     st = (f32x4){tlo.x, tlo.y, thi.x, thi.y};
;                     u[q] = psa * cur.vs.z + cur.vs.y;
;                 }
;                 const float qa = (odd1 ? pz[1] : pz[0]) + dppf<0xB1>(odd1 ? pz[0] : pz[1]);
;                 const float qb = (odd1 ? pz[3] : pz[2]) + dppf<0xB1>(odd1 ? pz[2] : pz[3]);
;                 float r = (odd2 ? qb : qa) + dppf<0x4E>(odd2 ? qa : qb);
;                 r += dppf<0x124>(r); r += dppf<0x128>(r);
;                 const float us = odd2 ? (odd1 ? u[3] : u[2]) : (odd1 ? u[1] : u[0]);
;                 if (j < 4) { const int t = blk * RW_TB + s4 + j; ((float*)(Ub + (size_t)t * (PWP * 2) + URR * 2))[h * 64 + row] = r + us; }
;             }
	v_pk_mul_f32 v[148:149], v[72:73], v[124:125] op_sel_hi:[0,1]
	v_pk_fma_f32 v[148:149], v[72:73], v[126:127], v[148:149] op_sel:[1,0,0] op_sel_hi:[1,1,1]
	v_pk_fma_f32 v[148:149], v[74:75], v[128:129], v[148:149] op_sel_hi:[0,1,1]
	v_pk_fma_f32 v[148:149], v[74:75], v[130:131], v[148:149] op_sel:[1,0,0] op_sel_hi:[1,1,1]
	v_pk_mul_f32 v[152:153], v[136:137], v[140:141] op_sel_hi:[1,0]
	v_pk_mul_f32 v[154:155], v[138:139], v[140:141] op_sel_hi:[1,0]
	v_add_f32_dpp v150, v148, v148 quad_perm:[1,0,3,2] row_mask:0xf bank_mask:0xf bound_ctrl:1
	v_pk_fma_f32 v[152:153], v[72:73], v[120:121], v[152:153]
	v_pk_fma_f32 v[154:155], v[74:75], v[122:123], v[154:155]
	v_add_f32_dpp v150, v150, v150 quad_perm:[2,3,0,1] row_mask:0xf bank_mask:0xf bound_ctrl:1
	ds_read_b128 v[102:105], v160 offset:20224
	ds_read_b128 v[106:109], v160 offset:20240
	v_add_f32_dpp v150, v150, v150 row_half_mirror row_mask:0xf bank_mask:0xf bound_ctrl:1
	ds_read_b128 v[114:117], v198 offset:20992
	ds_read_b32 v118, v204 offset:21248
	v_add_f32_dpp v150, v150, v150 row_mirror row_mask:0xf bank_mask:0xf bound_ctrl:1
	v_pk_fma_f32 v[68:69], v[132:133], v[150:151], v[152:153] op_sel_hi:[1,0,1]
	v_pk_fma_f32 v[70:71], v[134:135], v[150:151], v[154:155] op_sel_hi:[1,0,1]
	ds_read_b128 v[98:101], v198 offset:19968
	ds_read_b128 v[110:113], v198 offset:20736
	s_waitcnt lgkmcnt(6)
	v_pk_mul_f32 v[142:143], v[68:69], v[80:81] op_sel_hi:[0,1]
	v_pk_fma_f32 v[142:143], v[68:69], v[82:83], v[142:143] op_sel:[1,0,0] op_sel_hi:[1,1,1]
	v_pk_fma_f32 v[142:143], v[70:71], v[84:85], v[142:143] op_sel_hi:[0,1,1]
	v_pk_fma_f32 v[142:143], v[70:71], v[86:87], v[142:143] op_sel:[1,0,0] op_sel_hi:[1,1,1]
	v_pk_mul_f32 v[152:153], v[92:93], v[96:97] op_sel_hi:[1,0]
	v_pk_mul_f32 v[154:155], v[94:95], v[96:97] op_sel_hi:[1,0]
	v_add_f32_dpp v150, v142, v142 quad_perm:[1,0,3,2] row_mask:0xf bank_mask:0xf bound_ctrl:1
	v_pk_fma_f32 v[152:153], v[68:69], v[76:77], v[152:153]
	v_pk_fma_f32 v[154:155], v[70:71], v[78:79], v[154:155]
	v_add_f32_dpp v150, v150, v150 quad_perm:[2,3,0,1] row_mask:0xf bank_mask:0xf bound_ctrl:1
	v_add_f32_dpp v156, v145, v145 row_ror:8 row_mask:0xf bank_mask:0xf
	v_add_f32_dpp v157, v147, v147 row_ror:8 row_mask:0xf bank_mask:0xf
	v_add_f32_dpp v150, v150, v150 row_half_mirror row_mask:0xf bank_mask:0xf bound_ctrl:1
	v_add_f32_dpp v156, v149, v149 row_ror:8 row_mask:0xf bank_mask:0xc
	v_add_f32_dpp v157, v143, v143 row_ror:8 row_mask:0xf bank_mask:0xc
	v_add_f32_dpp v150, v150, v150 row_mirror row_mask:0xf bank_mask:0xf bound_ctrl:1
	v_pk_fma_f32 v[72:73], v[88:89], v[150:151], v[152:153] op_sel_hi:[1,0,1]
	v_pk_fma_f32 v[74:75], v[90:91], v[150:151], v[154:155] op_sel_hi:[1,0,1]
	ds_read_b128 v[124:127], v160 offset:21760
	ds_read_b128 v[128:131], v160 offset:21776
	v_add_f32_dpp v158, v156, v156 row_half_mirror row_mask:0xf bank_mask:0xf
	v_add_f32_dpp v158, v157, v157 row_half_mirror row_mask:0xf bank_mask:0xa
	ds_read_b128 v[136:139], v198 offset:22528
	ds_read_b32 v140, v204 offset:22784
	v_add_f32_dpp v158, v158, v158 quad_perm:[1,0,3,2] row_mask:0xf bank_mask:0xf bound_ctrl:1
	ds_read_b128 v[120:123], v198 offset:21504
	ds_read_b128 v[132:135], v198 offset:22272
	v_add_f32_dpp v158, v158, v158 quad_perm:[2,3,0,1] row_mask:0xf bank_mask:0xf bound_ctrl:1
	global_store_dword v159, v158, s[34:35]
	v_add_u32_e32 v159, 0xb000, v159
	s_waitcnt lgkmcnt(6)
	v_pk_mul_f32 v[144:145], v[72:73], v[102:103] op_sel_hi:[0,1]
	v_pk_fma_f32 v[144:145], v[72:73], v[104:105], v[144:145] op_sel:[1,0,0] op_sel_hi:[1,1,1]
	v_pk_fma_f32 v[144:145], v[74:75], v[106:107], v[144:145] op_sel_hi:[0,1,1]
	v_pk_fma_f32 v[144:145], v[74:75], v[108:109], v[144:145] op_sel:[1,0,0] op_sel_hi:[1,1,1]
	v_pk_mul_f32 v[152:153], v[114:115], v[118:119] op_sel_hi:[1,0]
	v_pk_mul_f32 v[154:155], v[116:117], v[118:119] op_sel_hi:[1,0]
	v_add_f32_dpp v150, v144, v144 quad_perm:[1,0,3,2] row_mask:0xf bank_mask:0xf bound_ctrl:1
	v_pk_fma_f32 v[152:153], v[72:73], v[98:99], v[152:153]
	v_pk_fma_f32 v[154:155], v[74:75], v[100:101], v[154:155]
	v_add_f32_dpp v150, v150, v150 quad_perm:[2,3,0,1] row_mask:0xf bank_mask:0xf bound_ctrl:1
	ds_read_b128 v[80:83], v160 offset:23296
	ds_read_b128 v[84:87], v160 offset:23312
	v_add_f32_dpp v150, v150, v150 row_half_mirror row_mask:0xf bank_mask:0xf bound_ctrl:1
	ds_read_b128 v[92:95], v198 offset:24064
	ds_read_b32 v96, v204 offset:24320
	v_add_f32_dpp v150, v150, v150 row_mirror row_mask:0xf bank_mask:0xf bound_ctrl:1
	v_pk_fma_f32 v[68:69], v[110:111], v[150:151], v[152:153] op_sel_hi:[1,0,1]
	v_pk_fma_f32 v[70:71], v[112:113], v[150:151], v[154:155] op_sel_hi:[1,0,1]
	ds_read_b128 v[76:79], v198 offset:23040
	ds_read_b128 v[88:91], v198 offset:23808
	s_waitcnt lgkmcnt(6)
	v_pk_mul_f32 v[146:147], v[68:69], v[124:125] op_sel_hi:[0,1]
	v_pk_fma_f32 v[146:147], v[68:69], v[126:127], v[146:147] op_sel:[1,0,0] op_sel_hi:[1,1,1]
	v_pk_fma_f32 v[146:147], v[70:71], v[128:129], v[146:147] op_sel_hi:[0,1,1]
	v_pk_fma_f32 v[146:147], v[70:71], v[130:131], v[146:147] op_sel:[1,0,0] op_sel_hi:[1,1,1]
	v_pk_mul_f32 v[152:153], v[136:137], v[140:141] op_sel_hi:[1,0]
	v_pk_mul_f32 v[154:155], v[138:139], v[140:141] op_sel_hi:[1,0]
	v_add_f32_dpp v150, v146, v146 quad_perm:[1,0,3,2] row_mask:0xf bank_mask:0xf bound_ctrl:1
	v_pk_fma_f32 v[152:153], v[68:69], v[120:121], v[152:153]
	v_pk_fma_f32 v[154:155], v[70:71], v[122:123], v[154:155]
	v_add_f32_dpp v150, v150, v150 quad_perm:[2,3,0,1] row_mask:0xf bank_mask:0xf bound_ctrl:1
	ds_read_b128 v[102:105], v160 offset:24832
	ds_read_b128 v[106:109], v160 offset:24848
	v_add_f32_dpp v150, v150, v150 row_half_mirror row_mask:0xf bank_mask:0xf bound_ctrl:1
	ds_read_b128 v[114:117], v198 offset:25600
	ds_read_b32 v118, v204 offset:25856
	v_add_f32_dpp v150, v150, v150 row_mirror row_mask:0xf bank_mask:0xf bound_ctrl:1
	v_pk_fma_f32 v[72:73], v[132:133], v[150:151], v[152:153] op_sel_hi:[1,0,1]
	v_pk_fma_f32 v[74:75], v[134:135], v[150:151], v[154:155] op_sel_hi:[1,0,1]
	ds_read_b128 v[98:101], v198 offset:24576
	ds_read_b128 v[110:113], v198 offset:25344
	s_waitcnt lgkmcnt(6)
; __device__ __forceinline__ void rwkv_scan(Frame& F, int wg, unsigned* shw, unsigned wait_target, int wait_blk) {
;     ...
;             RwOps R[4];
;             RW_LD(R[0], 0); RW_LD(R[1], 1); RW_LD(R[2], 2);
;             for (int s4 = 0; s4 < RW_TB; s4 += 4) {
;                 float pz[4], u[4];
; #pragma unroll
;                 for (int q = 0; q < 4; ++q) {
;                     RW_LD(R[(q + 3) & 3], s4 + q + 3);
;                     const RwOps& cur = R[q];
;                     const f32x2 slo = {st.x, st.y}, shi = {st.z, st.w};
;                     f32x2 ma = slo * (f32x2){cur.a.x, cur.a.y}; ma = __builtin_elementwise_fma(shi, (f32x2){cur.a.z, cur.a.w}, ma);
;                     f32x2 mz = slo * (f32x2){cur.wr.x, cur.wr.y}; mz = __builtin_elementwise_fma(shi, (f32x2){cur.wr.z, cur.wr.w}, mz);
;                     float psa = ma.x + ma.y; pz[q] = mz.x + mz.y;
;                     const f32x2 vb = {cur.vs.x, cur.vs.x};
;                     f32x2 tlo = (f32x2){cur.k.x, cur.k.y} * vb, thi = (f32x2){cur.k.z, cur.k.w} * vb;
;                     tlo = __builtin_elementwise_fma(slo, (f32x2){cur.w.x, cur.w.y}, tlo); thi = __builtin_elementwise_fma(shi, (f32x2){cur.w.z, cur.w.w}, thi);
;                     psa = red16(psa);
;                     const f32x2 pb = {psa, psa};
;                     tlo = __builtin_elementwise_fma((f32x2){cur.b.x, cur.b.y}, pb, tlo); thi = __builtin_elementwise_fma((f32x2){cur.b.z, cur.b.w}, pb, thi);
;                     st = (f32x4){tlo.x, tlo.y, thi.x, thi.y};
;                     u[q] = psa * cur.vs.z + cur.vs.y;
;                 }
;                 const float qa = (odd1 ? pz[1] : pz[0]) + dppf<0xB1>(odd1 ? pz[0] : pz[1]);
;                 const float qb = (odd1 ? pz[3] : pz[2]) + dppf<0xB1>(odd1 ? pz[2] : pz[3]);
;                 float r = (odd2 ? qb : qa) + dppf<0x4E>(odd2 ? qa : qb);
;                 r += dppf<0x124>(r); r += dppf<0x128>(r);
;                 const float us = odd2 ? (odd1 ? u[3] : u[2]) : (odd1 ? u[1] : u[0]);
;                 if (j < 4) { const int t = blk * RW_TB + s4 + j; ((float*)(Ub + (size_t)t * (PWP * 2) + URR * 2))[h * 64 + row] = r + us; }
;             }
	v_pk_mul_f32 v[148:149], v[72:73], v[80:81] op_sel_hi:[0,1]
	v_pk_fma_f32 v[148:149], v[72:73], v[82:83], v[148:149] op_sel:[1,0,0] op_sel_hi:[1,1,1]
	v_pk_fma_f32 v[148:149], v[74:75], v[84:85], v[148:149] op_sel_hi:[0,1,1]
	v_pk_fma_f32 v[148:149], v[74:75], v[86:87], v[148:149] op_sel:[1,0,0] op_sel_hi:[1,1,1]
	v_pk_mul_f32 v[152:153], v[92:93], v[96:97] op_sel_hi:[1,0]
	v_pk_mul_f32 v[154:155], v[94:95], v[96:97] op_sel_hi:[1,0]
	v_add_f32_dpp v150, v148, v148 quad_perm:[1,0,3,2] row_mask:0xf bank_mask:0xf bound_ctrl:1
	v_pk_fma_f32 v[152:153], v[72:73], v[76:77], v[152:153]
	v_pk_fma_f32 v[154:155], v[74:75], v[78:79], v[154:155]
	v_add_f32_dpp v150, v150, v150 quad_perm:[2,3,0,1] row_mask:0xf bank_mask:0xf bound_ctrl:1
	ds_read_b128 v[124:127], v160 offset:26368
	ds_read_b128 v[128:131], v160 offset:26384
	v_add_f32_dpp v150, v150, v150 row_half_mirror row_mask:0xf bank_mask:0xf bound_ctrl:1
	ds_read_b128 v[136:139], v198 offset:27136
	ds_read_b32 v140, v204 offset:27392
	v_add_f32_dpp v150, v150, v150 row_mirror row_mask:0xf bank_mask:0xf bound_ctrl:1
	v_pk_fma_f32 v[68:69], v[88:89], v[150:151], v[152:153] op_sel_hi:[1,0,1]
	v_pk_fma_f32 v[70:71], v[90:91], v[150:151], v[154:155] op_sel_hi:[1,0,1]
	ds_read_b128 v[120:123], v198 offset:26112
	ds_read_b128 v[132:135], v198 offset:26880
	s_waitcnt lgkmcnt(6)
	v_pk_mul_f32 v[142:143], v[68:69], v[102:103] op_sel_hi:[0,1]
	v_pk_fma_f32 v[142:143], v[68:69], v[104:105], v[142:143] op_sel:[1,0,0] op_sel_hi:[1,1,1]
	v_pk_fma_f32 v[142:143], v[70:71], v[106:107], v[142:143] op_sel_hi:[0,1,1]
	v_pk_fma_f32 v[142:143], v[70:71], v[108:109], v[142:143] op_sel:[1,0,0] op_sel_hi:[1,1,1]
	v_pk_mul_f32 v[152:153], v[114:115], v[118:119] op_sel_hi:[1,0]
	v_pk_mul_f32 v[154:155], v[116:117], v[118:119] op_sel_hi:[1,0]
	v_add_f32_dpp v150, v142, v142 quad_perm:[1,0,3,2] row_mask:0xf bank_mask:0xf bound_ctrl:1
	v_pk_fma_f32 v[152:153], v[68:69], v[98:99], v[152:153]
	v_pk_fma_f32 v[154:155], v[70:71], v[100:101], v[154:155]
	v_add_f32_dpp v150, v150, v150 quad_perm:[2,3,0,1] row_mask:0xf bank_mask:0xf bound_ctrl:1
	v_add_f32_dpp v156, v145, v145 row_ror:8 row_mask:0xf bank_mask:0xf
	v_add_f32_dpp v157, v147, v147 row_ror:8 row_mask:0xf bank_mask:0xf
	v_add_f32_dpp v150, v150, v150 row_half_mirror row_mask:0xf bank_mask:0xf bound_ctrl:1
	v_add_f32_dpp v156, v149, v149 row_ror:8 row_mask:0xf bank_mask:0xc
	v_add_f32_dpp v157, v143, v143 row_ror:8 row_mask:0xf bank_mask:0xc
	v_add_f32_dpp v150, v150, v150 row_mirror row_mask:0xf bank_mask:0xf bound_ctrl:1
	v_pk_fma_f32 v[72:73], v[110:111], v[150:151], v[152:153] op_sel_hi:[1,0,1]
	v_pk_fma_f32 v[74:75], v[112:113], v[150:151], v[154:155] op_sel_hi:[1,0,1]
	ds_read_b128 v[80:83], v160 offset:27904
	ds_read_b128 v[84:87], v160 offset:27920
	v_add_f32_dpp v158, v156, v156 row_half_mirror row_mask:0xf bank_mask:0xf
	v_add_f32_dpp v158, v157, v157 row_half_mirror row_mask:0xf bank_mask:0xa
	ds_read_b128 v[92:95], v198 offset:28672
	ds_read_b32 v96, v204 offset:28928
	v_add_f32_dpp v158, v158, v158 quad_perm:[1,0,3,2] row_mask:0xf bank_mask:0xf bound_ctrl:1
	ds_read_b128 v[76:79], v198 offset:27648
	ds_read_b128 v[88:91], v198 offset:28416
	v_add_f32_dpp v158, v158, v158 quad_perm:[2,3,0,1] row_mask:0xf bank_mask:0xf bound_ctrl:1
	global_store_dword v159, v158, s[34:35]
	v_add_u32_e32 v159, 0xb000, v159
	s_waitcnt lgkmcnt(6)
	v_pk_mul_f32 v[144:145], v[72:73], v[124:125] op_sel_hi:[0,1]
	v_pk_fma_f32 v[144:145], v[72:73], v[126:127], v[144:145] op_sel:[1,0,0] op_sel_hi:[1,1,1]
	v_pk_fma_f32 v[144:145], v[74:75], v[128:129], v[144:145] op_sel_hi:[0,1,1]
	v_pk_fma_f32 v[144:145], v[74:75], v[130:131], v[144:145] op_sel:[1,0,0] op_sel_hi:[1,1,1]
	v_pk_mul_f32 v[152:153], v[136:137], v[140:141] op_sel_hi:[1,0]
	v_pk_mul_f32 v[154:155], v[138:139], v[140:141] op_sel_hi:[1,0]
	v_add_f32_dpp v150, v144, v144 quad_perm:[1,0,3,2] row_mask:0xf bank_mask:0xf bound_ctrl:1
	v_pk_fma_f32 v[152:153], v[72:73], v[120:121], v[152:153]
	v_pk_fma_f32 v[154:155], v[74:75], v[122:123], v[154:155]
	v_add_f32_dpp v150, v150, v150 quad_perm:[2,3,0,1] row_mask:0xf bank_mask:0xf bound_ctrl:1
	ds_read_b128 v[102:105], v160 offset:29440
	ds_read_b128 v[106:109], v160 offset:29456
	v_add_f32_dpp v150, v150, v150 row_half_mirror row_mask:0xf bank_mask:0xf bound_ctrl:1
	ds_read_b128 v[114:117], v198 offset:30208
	ds_read_b32 v118, v204 offset:30464
	v_add_f32_dpp v150, v150, v150 row_mirror row_mask:0xf bank_mask:0xf bound_ctrl:1
	v_pk_fma_f32 v[68:69], v[132:133], v[150:151], v[152:153] op_sel_hi:[1,0,1]
	v_pk_fma_f32 v[70:71], v[134:135], v[150:151], v[154:155] op_sel_hi:[1,0,1]
	ds_read_b128 v[98:101], v198 offset:29184
	ds_read_b128 v[110:113], v198 offset:29952
	s_waitcnt lgkmcnt(6)
	v_pk_mul_f32 v[146:147], v[68:69], v[80:81] op_sel_hi:[0,1]
	v_pk_fma_f32 v[146:147], v[68:69], v[82:83], v[146:147] op_sel:[1,0,0] op_sel_hi:[1,1,1]
	v_pk_fma_f32 v[146:147], v[70:71], v[84:85], v[146:147] op_sel_hi:[0,1,1]
	v_pk_fma_f32 v[146:147], v[70:71], v[86:87], v[146:147] op_sel:[1,0,0] op_sel_hi:[1,1,1]
	v_pk_mul_f32 v[152:153], v[92:93], v[96:97] op_sel_hi:[1,0]
	v_pk_mul_f32 v[154:155], v[94:95], v[96:97] op_sel_hi:[1,0]
	v_add_f32_dpp v150, v146, v146 quad_perm:[1,0,3,2] row_mask:0xf bank_mask:0xf bound_ctrl:1
	v_pk_fma_f32 v[152:153], v[68:69], v[76:77], v[152:153]
	v_pk_fma_f32 v[154:155], v[70:71], v[78:79], v[154:155]
	v_add_f32_dpp v150, v150, v150 quad_perm:[2,3,0,1] row_mask:0xf bank_mask:0xf bound_ctrl:1
	ds_read_b128 v[124:127], v160 offset:30976
	ds_read_b128 v[128:131], v160 offset:30992
	v_add_f32_dpp v150, v150, v150 row_half_mirror row_mask:0xf bank_mask:0xf bound_ctrl:1
	ds_read_b128 v[136:139], v198 offset:31744
	ds_read_b32 v140, v204 offset:32000
	v_add_f32_dpp v150, v150, v150 row_mirror row_mask:0xf bank_mask:0xf bound_ctrl:1
	v_pk_fma_f32 v[72:73], v[88:89], v[150:151], v[152:153] op_sel_hi:[1,0,1]
	v_pk_fma_f32 v[74:75], v[90:91], v[150:151], v[154:155] op_sel_hi:[1,0,1]
	ds_read_b128 v[120:123], v198 offset:30720
	ds_read_b128 v[132:135], v198 offset:31488
	s_waitcnt lgkmcnt(6)
; __device__ __forceinline__ void rwkv_scan(Frame& F, int wg, unsigned* shw, unsigned wait_target, int wait_blk) {
;     ...
;             RwOps R[4];
;             RW_LD(R[0], 0); RW_LD(R[1], 1); RW_LD(R[2], 2);
;             for (int s4 = 0; s4 < RW_TB; s4 += 4) {
;                 float pz[4], u[4];
; #pragma unroll
;                 for (int q = 0; q < 4; ++q) {
;                     RW_LD(R[(q + 3) & 3], s4 + q + 3);
;                     const RwOps& cur = R[q];
;                     const f32x2 slo = {st.x, st.y}, shi = {st.z, st.w};
;                     f32x2 ma = slo * (f32x2){cur.a.x, cur.a.y}; ma = __builtin_elementwise_fma(shi, (f32x2){cur.a.z, cur.a.w}, ma);
;                     f32x2 mz = slo * (f32x2){cur.wr.x, cur.wr.y}; mz = __builtin_elementwise_fma(shi, (f32x2){cur.wr.z, cur.wr.w}, mz);
;                     float psa = ma.x + ma.y; pz[q] = mz.x + mz.y;
;                     const f32x2 vb = {cur.vs.x, cur.vs.x};
;                     f32x2 tlo = (f32x2){cur.k.x, cur.k.y} * vb, thi = (f32x2){cur.k.z, cur.k.w} * vb;
;                     tlo = __builtin_elementwise_fma(slo, (f32x2){cur.w.x, cur.w.y}, tlo); thi = __builtin_elementwise_fma(shi, (f32x2){cur.w.z, cur.w.w}, thi);
;                     psa = red16(psa);
;                     const f32x2 pb = {psa, psa};
;                     tlo = __builtin_elementwise_fma((f32x2){cur.b.x, cur.b.y}, pb, tlo); thi = __builtin_elementwise_fma((f32x2){cur.b.z, cur.b.w}, pb, thi);
;                     st = (f32x4){tlo.x, tlo.y, thi.x, thi.y};
;                     u[q] = psa * cur.vs.z + cur.vs.y;
;                 }
;                 const float qa = (odd1 ? pz[1] : pz[0]) + dppf<0xB1>(odd1 ? pz[0] : pz[1]);
;                 const float qb = (odd1 ? pz[3] : pz[2]) + dppf<0xB1>(odd1 ? pz[2] : pz[3]);
;                 float r = (odd2 ? qb : qa) + dppf<0x4E>(odd2 ? qa : qb);
;                 r += dppf<0x124>(r); r += dppf<0x128>(r);
;                 const float us = odd2 ? (odd1 ? u[3] : u[2]) : (odd1 ? u[1] : u[0]);
;                 if (j < 4) { const int t = blk * RW_TB + s4 + j; ((float*)(Ub + (size_t)t * (PWP * 2) + URR * 2))[h * 64 + row] = r + us; }
;             }
	v_pk_mul_f32 v[148:149], v[72:73], v[102:103] op_sel_hi:[0,1]
	v_pk_fma_f32 v[148:149], v[72:73], v[104:105], v[148:149] op_sel:[1,0,0] op_sel_hi:[1,1,1]
	v_pk_fma_f32 v[148:149], v[74:75], v[106:107], v[148:149] op_sel_hi:[0,1,1]
	v_pk_fma_f32 v[148:149], v[74:75], v[108:109], v[148:149] op_sel:[1,0,0] op_sel_hi:[1,1,1]
	v_pk_mul_f32 v[152:153], v[114:115], v[118:119] op_sel_hi:[1,0]
	v_pk_mul_f32 v[154:155], v[116:117], v[118:119] op_sel_hi:[1,0]
	v_add_f32_dpp v150, v148, v148 quad_perm:[1,0,3,2] row_mask:0xf bank_mask:0xf bound_ctrl:1
	v_pk_fma_f32 v[152:153], v[72:73], v[98:99], v[152:153]
	v_pk_fma_f32 v[154:155], v[74:75], v[100:101], v[154:155]
	v_add_f32_dpp v150, v150, v150 quad_perm:[2,3,0,1] row_mask:0xf bank_mask:0xf bound_ctrl:1
	ds_read_b128 v[80:83], v160 offset:32512
	ds_read_b128 v[84:87], v160 offset:32528
	v_add_f32_dpp v150, v150, v150 row_half_mirror row_mask:0xf bank_mask:0xf bound_ctrl:1
	ds_read_b128 v[92:95], v198 offset:33280
	ds_read_b32 v96, v204 offset:33536
	v_add_f32_dpp v150, v150, v150 row_mirror row_mask:0xf bank_mask:0xf bound_ctrl:1
	v_pk_fma_f32 v[68:69], v[110:111], v[150:151], v[152:153] op_sel_hi:[1,0,1]
	v_pk_fma_f32 v[70:71], v[112:113], v[150:151], v[154:155] op_sel_hi:[1,0,1]
	ds_read_b128 v[76:79], v198 offset:32256
	ds_read_b128 v[88:91], v198 offset:33024
	s_waitcnt lgkmcnt(6)
	v_pk_mul_f32 v[142:143], v[68:69], v[124:125] op_sel_hi:[0,1]
	v_pk_fma_f32 v[142:143], v[68:69], v[126:127], v[142:143] op_sel:[1,0,0] op_sel_hi:[1,1,1]
	v_pk_fma_f32 v[142:143], v[70:71], v[128:129], v[142:143] op_sel_hi:[0,1,1]
	v_pk_fma_f32 v[142:143], v[70:71], v[130:131], v[142:143] op_sel:[1,0,0] op_sel_hi:[1,1,1]
	v_pk_mul_f32 v[152:153], v[136:137], v[140:141] op_sel_hi:[1,0]
	v_pk_mul_f32 v[154:155], v[138:139], v[140:141] op_sel_hi:[1,0]
	v_add_f32_dpp v150, v142, v142 quad_perm:[1,0,3,2] row_mask:0xf bank_mask:0xf bound_ctrl:1
	v_pk_fma_f32 v[152:153], v[68:69], v[120:121], v[152:153]
	v_pk_fma_f32 v[154:155], v[70:71], v[122:123], v[154:155]
	v_add_f32_dpp v150, v150, v150 quad_perm:[2,3,0,1] row_mask:0xf bank_mask:0xf bound_ctrl:1
	v_add_f32_dpp v156, v145, v145 row_ror:8 row_mask:0xf bank_mask:0xf
	v_add_f32_dpp v157, v147, v147 row_ror:8 row_mask:0xf bank_mask:0xf
	v_add_f32_dpp v150, v150, v150 row_half_mirror row_mask:0xf bank_mask:0xf bound_ctrl:1
	v_add_f32_dpp v156, v149, v149 row_ror:8 row_mask:0xf bank_mask:0xc
	v_add_f32_dpp v157, v143, v143 row_ror:8 row_mask:0xf bank_mask:0xc
	v_add_f32_dpp v150, v150, v150 row_mirror row_mask:0xf bank_mask:0xf bound_ctrl:1
	v_pk_fma_f32 v[72:73], v[132:133], v[150:151], v[152:153] op_sel_hi:[1,0,1]
	v_pk_fma_f32 v[74:75], v[134:135], v[150:151], v[154:155] op_sel_hi:[1,0,1]
	ds_read_b128 v[102:105], v160 offset:34048
	ds_read_b128 v[106:109], v160 offset:34064
	v_add_f32_dpp v158, v156, v156 row_half_mirror row_mask:0xf bank_mask:0xf
	v_add_f32_dpp v158, v157, v157 row_half_mirror row_mask:0xf bank_mask:0xa
	ds_read_b128 v[114:117], v198 offset:34816
	ds_read_b32 v118, v204 offset:35072
	v_add_f32_dpp v158, v158, v158 quad_perm:[1,0,3,2] row_mask:0xf bank_mask:0xf bound_ctrl:1
	ds_read_b128 v[98:101], v198 offset:33792
	ds_read_b128 v[110:113], v198 offset:34560
	v_add_f32_dpp v158, v158, v158 quad_perm:[2,3,0,1] row_mask:0xf bank_mask:0xf bound_ctrl:1
	global_store_dword v159, v158, s[34:35]
	v_add_u32_e32 v159, 0xb000, v159
	s_waitcnt lgkmcnt(6)
	v_pk_mul_f32 v[144:145], v[72:73], v[80:81] op_sel_hi:[0,1]
	v_pk_fma_f32 v[144:145], v[72:73], v[82:83], v[144:145] op_sel:[1,0,0] op_sel_hi:[1,1,1]
	v_pk_fma_f32 v[144:145], v[74:75], v[84:85], v[144:145] op_sel_hi:[0,1,1]
	v_pk_fma_f32 v[144:145], v[74:75], v[86:87], v[144:145] op_sel:[1,0,0] op_sel_hi:[1,1,1]
	v_pk_mul_f32 v[152:153], v[92:93], v[96:97] op_sel_hi:[1,0]
	v_pk_mul_f32 v[154:155], v[94:95], v[96:97] op_sel_hi:[1,0]
	v_add_f32_dpp v150, v144, v144 quad_perm:[1,0,3,2] row_mask:0xf bank_mask:0xf bound_ctrl:1
	v_pk_fma_f32 v[152:153], v[72:73], v[76:77], v[152:153]
	v_pk_fma_f32 v[154:155], v[74:75], v[78:79], v[154:155]
	v_add_f32_dpp v150, v150, v150 quad_perm:[2,3,0,1] row_mask:0xf bank_mask:0xf bound_ctrl:1
	ds_read_b128 v[124:127], v160 offset:35584
	ds_read_b128 v[128:131], v160 offset:35600
	v_add_f32_dpp v150, v150, v150 row_half_mirror row_mask:0xf bank_mask:0xf bound_ctrl:1
	ds_read_b128 v[136:139], v198 offset:36352
	ds_read_b32 v140, v204 offset:36608
	v_add_f32_dpp v150, v150, v150 row_mirror row_mask:0xf bank_mask:0xf bound_ctrl:1
	v_pk_fma_f32 v[68:69], v[88:89], v[150:151], v[152:153] op_sel_hi:[1,0,1]
	v_pk_fma_f32 v[70:71], v[90:91], v[150:151], v[154:155] op_sel_hi:[1,0,1]
	ds_read_b128 v[120:123], v198 offset:35328
	ds_read_b128 v[132:135], v198 offset:36096
	s_waitcnt lgkmcnt(6)
	v_pk_mul_f32 v[146:147], v[68:69], v[102:103] op_sel_hi:[0,1]
	v_pk_fma_f32 v[146:147], v[68:69], v[104:105], v[146:147] op_sel:[1,0,0] op_sel_hi:[1,1,1]
	v_pk_fma_f32 v[146:147], v[70:71], v[106:107], v[146:147] op_sel_hi:[0,1,1]
	v_pk_fma_f32 v[146:147], v[70:71], v[108:109], v[146:147] op_sel:[1,0,0] op_sel_hi:[1,1,1]
	v_pk_mul_f32 v[152:153], v[114:115], v[118:119] op_sel_hi:[1,0]
	v_pk_mul_f32 v[154:155], v[116:117], v[118:119] op_sel_hi:[1,0]
	v_add_f32_dpp v150, v146, v146 quad_perm:[1,0,3,2] row_mask:0xf bank_mask:0xf bound_ctrl:1
	v_pk_fma_f32 v[152:153], v[68:69], v[98:99], v[152:153]
	v_pk_fma_f32 v[154:155], v[70:71], v[100:101], v[154:155]
	v_add_f32_dpp v150, v150, v150 quad_perm:[2,3,0,1] row_mask:0xf bank_mask:0xf bound_ctrl:1
	ds_read_b128 v[80:83], v160 offset:37120
	ds_read_b128 v[84:87], v160 offset:37136
	v_add_f32_dpp v150, v150, v150 row_half_mirror row_mask:0xf bank_mask:0xf bound_ctrl:1
	ds_read_b128 v[92:95], v198 offset:37888
	ds_read_b32 v96, v204 offset:38144
	v_add_f32_dpp v150, v150, v150 row_mirror row_mask:0xf bank_mask:0xf bound_ctrl:1
	v_pk_fma_f32 v[72:73], v[110:111], v[150:151], v[152:153] op_sel_hi:[1,0,1]
	v_pk_fma_f32 v[74:75], v[112:113], v[150:151], v[154:155] op_sel_hi:[1,0,1]
	ds_read_b128 v[76:79], v198 offset:36864
	ds_read_b128 v[88:91], v198 offset:37632
	s_waitcnt lgkmcnt(6)
; __device__ __forceinline__ void rwkv_scan(Frame& F, int wg, unsigned* shw, unsigned wait_target, int wait_blk) {
;     ...
;             RwOps R[4];
;             RW_LD(R[0], 0); RW_LD(R[1], 1); RW_LD(R[2], 2);
;             for (int s4 = 0; s4 < RW_TB; s4 += 4) {
;                 float pz[4], u[4];
; #pragma unroll
;                 for (int q = 0; q < 4; ++q) {
;                     RW_LD(R[(q + 3) & 3], s4 + q + 3);
;                     const RwOps& cur = R[q];
;                     const f32x2 slo = {st.x, st.y}, shi = {st.z, st.w};
;                     f32x2 ma = slo * (f32x2){cur.a.x, cur.a.y}; ma = __builtin_elementwise_fma(shi, (f32x2){cur.a.z, cur.a.w}, ma);
;                     f32x2 mz = slo * (f32x2){cur.wr.x, cur.wr.y}; mz = __builtin_elementwise_fma(shi, (f32x2){cur.wr.z, cur.wr.w}, mz);
;                     float psa = ma.x + ma.y; pz[q] = mz.x + mz.y;
;                     const f32x2 vb = {cur.vs.x, cur.vs.x};
;                     f32x2 tlo = (f32x2){cur.k.x, cur.k.y} * vb, thi = (f32x2){cur.k.z, cur.k.w} * vb;
;                     tlo = __builtin_elementwise_fma(slo, (f32x2){cur.w.x, cur.w.y}, tlo); thi = __builtin_elementwise_fma(shi, (f32x2){cur.w.z, cur.w.w}, thi);
;                     psa = red16(psa);
;                     const f32x2 pb = {psa, psa};
;                     tlo = __builtin_elementwise_fma((f32x2){cur.b.x, cur.b.y}, pb, tlo); thi = __builtin_elementwise_fma((f32x2){cur.b.z, cur.b.w}, pb, thi);
;                     st = (f32x4){tlo.x, tlo.y, thi.x, thi.y};
;                     u[q] = psa * cur.vs.z + cur.vs.y;
;                 }
;                 const float qa = (odd1 ? pz[1] : pz[0]) + dppf<0xB1>(odd1 ? pz[0] : pz[1]);
;                 const float qb = (odd1 ? pz[3] : pz[2]) + dppf<0xB1>(odd1 ? pz[2] : pz[3]);
;                 float r = (odd2 ? qb : qa) + dppf<0x4E>(odd2 ? qa : qb);
;                 r += dppf<0x124>(r); r += dppf<0x128>(r);
;                 const float us = odd2 ? (odd1 ? u[3] : u[2]) : (odd1 ? u[1] : u[0]);
;                 if (j < 4) { const int t = blk * RW_TB + s4 + j; ((float*)(Ub + (size_t)t * (PWP * 2) + URR * 2))[h * 64 + row] = r + us; }
;             }
	v_pk_mul_f32 v[148:149], v[72:73], v[124:125] op_sel_hi:[0,1]
	v_pk_fma_f32 v[148:149], v[72:73], v[126:127], v[148:149] op_sel:[1,0,0] op_sel_hi:[1,1,1]
	v_pk_fma_f32 v[148:149], v[74:75], v[128:129], v[148:149] op_sel_hi:[0,1,1]
	v_pk_fma_f32 v[148:149], v[74:75], v[130:131], v[148:149] op_sel:[1,0,0] op_sel_hi:[1,1,1]
	v_pk_mul_f32 v[152:153], v[136:137], v[140:141] op_sel_hi:[1,0]
	v_pk_mul_f32 v[154:155], v[138:139], v[140:141] op_sel_hi:[1,0]
	v_add_f32_dpp v150, v148, v148 quad_perm:[1,0,3,2] row_mask:0xf bank_mask:0xf bound_ctrl:1
	v_pk_fma_f32 v[152:153], v[72:73], v[120:121], v[152:153]
	v_pk_fma_f32 v[154:155], v[74:75], v[122:123], v[154:155]
	v_add_f32_dpp v150, v150, v150 quad_perm:[2,3,0,1] row_mask:0xf bank_mask:0xf bound_ctrl:1
	ds_read_b128 v[102:105], v160 offset:38656
	ds_read_b128 v[106:109], v160 offset:38672
	v_add_f32_dpp v150, v150, v150 row_half_mirror row_mask:0xf bank_mask:0xf bound_ctrl:1
	ds_read_b128 v[114:117], v198 offset:39424
	ds_read_b32 v118, v204 offset:39680
	v_add_f32_dpp v150, v150, v150 row_mirror row_mask:0xf bank_mask:0xf bound_ctrl:1
	v_pk_fma_f32 v[68:69], v[132:133], v[150:151], v[152:153] op_sel_hi:[1,0,1]
	v_pk_fma_f32 v[70:71], v[134:135], v[150:151], v[154:155] op_sel_hi:[1,0,1]
	ds_read_b128 v[98:101], v198 offset:38400
	ds_read_b128 v[110:113], v198 offset:39168
	s_waitcnt lgkmcnt(6)
	v_pk_mul_f32 v[142:143], v[68:69], v[80:81] op_sel_hi:[0,1]
	v_pk_fma_f32 v[142:143], v[68:69], v[82:83], v[142:143] op_sel:[1,0,0] op_sel_hi:[1,1,1]
	v_pk_fma_f32 v[142:143], v[70:71], v[84:85], v[142:143] op_sel_hi:[0,1,1]
	v_pk_fma_f32 v[142:143], v[70:71], v[86:87], v[142:143] op_sel:[1,0,0] op_sel_hi:[1,1,1]
	v_pk_mul_f32 v[152:153], v[92:93], v[96:97] op_sel_hi:[1,0]
	v_pk_mul_f32 v[154:155], v[94:95], v[96:97] op_sel_hi:[1,0]
	v_add_f32_dpp v150, v142, v142 quad_perm:[1,0,3,2] row_mask:0xf bank_mask:0xf bound_ctrl:1
	v_pk_fma_f32 v[152:153], v[68:69], v[76:77], v[152:153]
	v_pk_fma_f32 v[154:155], v[70:71], v[78:79], v[154:155]
	v_add_f32_dpp v150, v150, v150 quad_perm:[2,3,0,1] row_mask:0xf bank_mask:0xf bound_ctrl:1
	v_add_f32_dpp v156, v145, v145 row_ror:8 row_mask:0xf bank_mask:0xf
	v_add_f32_dpp v157, v147, v147 row_ror:8 row_mask:0xf bank_mask:0xf
	v_add_f32_dpp v150, v150, v150 row_half_mirror row_mask:0xf bank_mask:0xf bound_ctrl:1
	v_add_f32_dpp v156, v149, v149 row_ror:8 row_mask:0xf bank_mask:0xc
	v_add_f32_dpp v157, v143, v143 row_ror:8 row_mask:0xf bank_mask:0xc
	v_add_f32_dpp v150, v150, v150 row_mirror row_mask:0xf bank_mask:0xf bound_ctrl:1
	v_pk_fma_f32 v[72:73], v[88:89], v[150:151], v[152:153] op_sel_hi:[1,0,1]
	v_pk_fma_f32 v[74:75], v[90:91], v[150:151], v[154:155] op_sel_hi:[1,0,1]
	ds_read_b128 v[124:127], v160 offset:40192
	ds_read_b128 v[128:131], v160 offset:40208
	v_add_f32_dpp v158, v156, v156 row_half_mirror row_mask:0xf bank_mask:0xf
	v_add_f32_dpp v158, v157, v157 row_half_mirror row_mask:0xf bank_mask:0xa
	ds_read_b128 v[136:139], v198 offset:40960
	ds_read_b32 v140, v204 offset:41216
	v_add_f32_dpp v158, v158, v158 quad_perm:[1,0,3,2] row_mask:0xf bank_mask:0xf bound_ctrl:1
	ds_read_b128 v[120:123], v198 offset:39936
	ds_read_b128 v[132:135], v198 offset:40704
	v_add_f32_dpp v158, v158, v158 quad_perm:[2,3,0,1] row_mask:0xf bank_mask:0xf bound_ctrl:1
	global_store_dword v159, v158, s[34:35]
	v_add_u32_e32 v159, 0xb000, v159
	s_waitcnt lgkmcnt(6)
	v_pk_mul_f32 v[144:145], v[72:73], v[102:103] op_sel_hi:[0,1]
	v_pk_fma_f32 v[144:145], v[72:73], v[104:105], v[144:145] op_sel:[1,0,0] op_sel_hi:[1,1,1]
	v_pk_fma_f32 v[144:145], v[74:75], v[106:107], v[144:145] op_sel_hi:[0,1,1]
	v_pk_fma_f32 v[144:145], v[74:75], v[108:109], v[144:145] op_sel:[1,0,0] op_sel_hi:[1,1,1]
	v_pk_mul_f32 v[152:153], v[114:115], v[118:119] op_sel_hi:[1,0]
	v_pk_mul_f32 v[154:155], v[116:117], v[118:119] op_sel_hi:[1,0]
	v_add_f32_dpp v150, v144, v144 quad_perm:[1,0,3,2] row_mask:0xf bank_mask:0xf bound_ctrl:1
	v_pk_fma_f32 v[152:153], v[72:73], v[98:99], v[152:153]
	v_pk_fma_f32 v[154:155], v[74:75], v[100:101], v[154:155]
	v_add_f32_dpp v150, v150, v150 quad_perm:[2,3,0,1] row_mask:0xf bank_mask:0xf bound_ctrl:1
	ds_read_b128 v[80:83], v160 offset:41728
	ds_read_b128 v[84:87], v160 offset:41744
	v_add_f32_dpp v150, v150, v150 row_half_mirror row_mask:0xf bank_mask:0xf bound_ctrl:1
	ds_read_b128 v[92:95], v198 offset:42496
	ds_read_b32 v96, v204 offset:42752
	v_add_f32_dpp v150, v150, v150 row_mirror row_mask:0xf bank_mask:0xf bound_ctrl:1
	v_pk_fma_f32 v[68:69], v[110:111], v[150:151], v[152:153] op_sel_hi:[1,0,1]
	v_pk_fma_f32 v[70:71], v[112:113], v[150:151], v[154:155] op_sel_hi:[1,0,1]
	ds_read_b128 v[76:79], v198 offset:41472
	ds_read_b128 v[88:91], v198 offset:42240
	s_waitcnt lgkmcnt(6)
	v_pk_mul_f32 v[146:147], v[68:69], v[124:125] op_sel_hi:[0,1]
	v_pk_fma_f32 v[146:147], v[68:69], v[126:127], v[146:147] op_sel:[1,0,0] op_sel_hi:[1,1,1]
	v_pk_fma_f32 v[146:147], v[70:71], v[128:129], v[146:147] op_sel_hi:[0,1,1]
	v_pk_fma_f32 v[146:147], v[70:71], v[130:131], v[146:147] op_sel:[1,0,0] op_sel_hi:[1,1,1]
	v_pk_mul_f32 v[152:153], v[136:137], v[140:141] op_sel_hi:[1,0]
	v_pk_mul_f32 v[154:155], v[138:139], v[140:141] op_sel_hi:[1,0]
	v_add_f32_dpp v150, v146, v146 quad_perm:[1,0,3,2] row_mask:0xf bank_mask:0xf bound_ctrl:1
	v_pk_fma_f32 v[152:153], v[68:69], v[120:121], v[152:153]
	v_pk_fma_f32 v[154:155], v[70:71], v[122:123], v[154:155]
	v_add_f32_dpp v150, v150, v150 quad_perm:[2,3,0,1] row_mask:0xf bank_mask:0xf bound_ctrl:1
	ds_read_b128 v[102:105], v160 offset:43264
	ds_read_b128 v[106:109], v160 offset:43280
	v_add_f32_dpp v150, v150, v150 row_half_mirror row_mask:0xf bank_mask:0xf bound_ctrl:1
	ds_read_b128 v[114:117], v198 offset:44032
	ds_read_b32 v118, v204 offset:44288
	v_add_f32_dpp v150, v150, v150 row_mirror row_mask:0xf bank_mask:0xf bound_ctrl:1
	v_pk_fma_f32 v[72:73], v[132:133], v[150:151], v[152:153] op_sel_hi:[1,0,1]
	v_pk_fma_f32 v[74:75], v[134:135], v[150:151], v[154:155] op_sel_hi:[1,0,1]
	ds_read_b128 v[98:101], v198 offset:43008
	ds_read_b128 v[110:113], v198 offset:43776
	s_waitcnt lgkmcnt(6)
; __device__ __forceinline__ void rwkv_scan(Frame& F, int wg, unsigned* shw, unsigned wait_target, int wait_blk) {
;     ...
;             RwOps R[4];
;             RW_LD(R[0], 0); RW_LD(R[1], 1); RW_LD(R[2], 2);
;             for (int s4 = 0; s4 < RW_TB; s4 += 4) {
;                 float pz[4], u[4];
; #pragma unroll
;                 for (int q = 0; q < 4; ++q) {
;                     RW_LD(R[(q + 3) & 3], s4 + q + 3);
;                     const RwOps& cur = R[q];
;                     const f32x2 slo = {st.x, st.y}, shi = {st.z, st.w};
;                     f32x2 ma = slo * (f32x2){cur.a.x, cur.a.y}; ma = __builtin_elementwise_fma(shi, (f32x2){cur.a.z, cur.a.w}, ma);
;                     f32x2 mz = slo * (f32x2){cur.wr.x, cur.wr.y}; mz = __builtin_elementwise_fma(shi, (f32x2){cur.wr.z, cur.wr.w}, mz);
;                     float psa = ma.x + ma.y; pz[q] = mz.x + mz.y;
;                     const f32x2 vb = {cur.vs.x, cur.vs.x};
;                     f32x2 tlo = (f32x2){cur.k.x, cur.k.y} * vb, thi = (f32x2){cur.k.z, cur.k.w} * vb;
;                     tlo = __builtin_elementwise_fma(slo, (f32x2){cur.w.x, cur.w.y}, tlo); thi = __builtin_elementwise_fma(shi, (f32x2){cur.w.z, cur.w.w}, thi);
;                     psa = red16(psa);
;                     const f32x2 pb = {psa, psa};
;                     tlo = __builtin_elementwise_fma((f32x2){cur.b.x, cur.b.y}, pb, tlo); thi = __builtin_elementwise_fma((f32x2){cur.b.z, cur.b.w}, pb, thi);
;                     st = (f32x4){tlo.x, tlo.y, thi.x, thi.y};
;                     u[q] = psa * cur.vs.z + cur.vs.y;
;                 }
;                 const float qa = (odd1 ? pz[1] : pz[0]) + dppf<0xB1>(odd1 ? pz[0] : pz[1]);
;                 const float qb = (odd1 ? pz[3] : pz[2]) + dppf<0xB1>(odd1 ? pz[2] : pz[3]);
;                 float r = (odd2 ? qb : qa) + dppf<0x4E>(odd2 ? qa : qb);
;                 r += dppf<0x124>(r); r += dppf<0x128>(r);
;                 const float us = odd2 ? (odd1 ? u[3] : u[2]) : (odd1 ? u[1] : u[0]);
;                 if (j < 4) { const int t = blk * RW_TB + s4 + j; ((float*)(Ub + (size_t)t * (PWP * 2) + URR * 2))[h * 64 + row] = r + us; }
;             }
	v_pk_mul_f32 v[148:149], v[72:73], v[80:81] op_sel_hi:[0,1]
	v_pk_fma_f32 v[148:149], v[72:73], v[82:83], v[148:149] op_sel:[1,0,0] op_sel_hi:[1,1,1]
	v_pk_fma_f32 v[148:149], v[74:75], v[84:85], v[148:149] op_sel_hi:[0,1,1]
	v_pk_fma_f32 v[148:149], v[74:75], v[86:87], v[148:149] op_sel:[1,0,0] op_sel_hi:[1,1,1]
	v_pk_mul_f32 v[152:153], v[92:93], v[96:97] op_sel_hi:[1,0]
	v_pk_mul_f32 v[154:155], v[94:95], v[96:97] op_sel_hi:[1,0]
	v_add_f32_dpp v150, v148, v148 quad_perm:[1,0,3,2] row_mask:0xf bank_mask:0xf bound_ctrl:1
	v_pk_fma_f32 v[152:153], v[72:73], v[76:77], v[152:153]
	v_pk_fma_f32 v[154:155], v[74:75], v[78:79], v[154:155]
	v_add_f32_dpp v150, v150, v150 quad_perm:[2,3,0,1] row_mask:0xf bank_mask:0xf bound_ctrl:1
	ds_read_b128 v[124:127], v160 offset:44800
	ds_read_b128 v[128:131], v160 offset:44816
	v_add_f32_dpp v150, v150, v150 row_half_mirror row_mask:0xf bank_mask:0xf bound_ctrl:1
	ds_read_b128 v[136:139], v198 offset:45568
	ds_read_b32 v140, v204 offset:45824
	v_add_f32_dpp v150, v150, v150 row_mirror row_mask:0xf bank_mask:0xf bound_ctrl:1
	v_pk_fma_f32 v[68:69], v[88:89], v[150:151], v[152:153] op_sel_hi:[1,0,1]
	v_pk_fma_f32 v[70:71], v[90:91], v[150:151], v[154:155] op_sel_hi:[1,0,1]
	ds_read_b128 v[120:123], v198 offset:44544
	ds_read_b128 v[132:135], v198 offset:45312
	s_waitcnt lgkmcnt(6)
	v_pk_mul_f32 v[142:143], v[68:69], v[102:103] op_sel_hi:[0,1]
	v_pk_fma_f32 v[142:143], v[68:69], v[104:105], v[142:143] op_sel:[1,0,0] op_sel_hi:[1,1,1]
	v_pk_fma_f32 v[142:143], v[70:71], v[106:107], v[142:143] op_sel_hi:[0,1,1]
	v_pk_fma_f32 v[142:143], v[70:71], v[108:109], v[142:143] op_sel:[1,0,0] op_sel_hi:[1,1,1]
	v_pk_mul_f32 v[152:153], v[114:115], v[118:119] op_sel_hi:[1,0]
	v_pk_mul_f32 v[154:155], v[116:117], v[118:119] op_sel_hi:[1,0]
	v_add_f32_dpp v150, v142, v142 quad_perm:[1,0,3,2] row_mask:0xf bank_mask:0xf bound_ctrl:1
	v_pk_fma_f32 v[152:153], v[68:69], v[98:99], v[152:153]
	v_pk_fma_f32 v[154:155], v[70:71], v[100:101], v[154:155]
	v_add_f32_dpp v150, v150, v150 quad_perm:[2,3,0,1] row_mask:0xf bank_mask:0xf bound_ctrl:1
	v_add_f32_dpp v156, v145, v145 row_ror:8 row_mask:0xf bank_mask:0xf
	v_add_f32_dpp v157, v147, v147 row_ror:8 row_mask:0xf bank_mask:0xf
	v_add_f32_dpp v150, v150, v150 row_half_mirror row_mask:0xf bank_mask:0xf bound_ctrl:1
	v_add_f32_dpp v156, v149, v149 row_ror:8 row_mask:0xf bank_mask:0xc
	v_add_f32_dpp v157, v143, v143 row_ror:8 row_mask:0xf bank_mask:0xc
	v_add_f32_dpp v150, v150, v150 row_mirror row_mask:0xf bank_mask:0xf bound_ctrl:1
	v_pk_fma_f32 v[72:73], v[110:111], v[150:151], v[152:153] op_sel_hi:[1,0,1]
	v_pk_fma_f32 v[74:75], v[112:113], v[150:151], v[154:155] op_sel_hi:[1,0,1]
	ds_read_b128 v[80:83], v160 offset:46336
	ds_read_b128 v[84:87], v160 offset:46352
	v_add_f32_dpp v158, v156, v156 row_half_mirror row_mask:0xf bank_mask:0xf
	v_add_f32_dpp v158, v157, v157 row_half_mirror row_mask:0xf bank_mask:0xa
	ds_read_b128 v[92:95], v198 offset:47104
	ds_read_b32 v96, v204 offset:47360
	v_add_f32_dpp v158, v158, v158 quad_perm:[1,0,3,2] row_mask:0xf bank_mask:0xf bound_ctrl:1
	ds_read_b128 v[76:79], v198 offset:46080
	ds_read_b128 v[88:91], v198 offset:46848
	v_add_f32_dpp v158, v158, v158 quad_perm:[2,3,0,1] row_mask:0xf bank_mask:0xf bound_ctrl:1
	global_store_dword v159, v158, s[34:35]
	v_add_u32_e32 v159, 0xb000, v159
	s_waitcnt lgkmcnt(6)
	v_pk_mul_f32 v[144:145], v[72:73], v[124:125] op_sel_hi:[0,1]
	v_pk_fma_f32 v[144:145], v[72:73], v[126:127], v[144:145] op_sel:[1,0,0] op_sel_hi:[1,1,1]
	v_pk_fma_f32 v[144:145], v[74:75], v[128:129], v[144:145] op_sel_hi:[0,1,1]
	v_pk_fma_f32 v[144:145], v[74:75], v[130:131], v[144:145] op_sel:[1,0,0] op_sel_hi:[1,1,1]
	v_pk_mul_f32 v[152:153], v[136:137], v[140:141] op_sel_hi:[1,0]
	v_pk_mul_f32 v[154:155], v[138:139], v[140:141] op_sel_hi:[1,0]
	v_add_f32_dpp v150, v144, v144 quad_perm:[1,0,3,2] row_mask:0xf bank_mask:0xf bound_ctrl:1
	v_pk_fma_f32 v[152:153], v[72:73], v[120:121], v[152:153]
	v_pk_fma_f32 v[154:155], v[74:75], v[122:123], v[154:155]
	v_add_f32_dpp v150, v150, v150 quad_perm:[2,3,0,1] row_mask:0xf bank_mask:0xf bound_ctrl:1
	ds_read_b128 v[102:105], v160 offset:47872
	ds_read_b128 v[106:109], v160 offset:47888
	v_add_f32_dpp v150, v150, v150 row_half_mirror row_mask:0xf bank_mask:0xf bound_ctrl:1
	ds_read_b128 v[114:117], v198 offset:48640
	ds_read_b32 v118, v204 offset:48896
	v_add_f32_dpp v150, v150, v150 row_mirror row_mask:0xf bank_mask:0xf bound_ctrl:1
	v_pk_fma_f32 v[68:69], v[132:133], v[150:151], v[152:153] op_sel_hi:[1,0,1]
	v_pk_fma_f32 v[70:71], v[134:135], v[150:151], v[154:155] op_sel_hi:[1,0,1]
	ds_read_b128 v[98:101], v198 offset:47616
	ds_read_b128 v[110:113], v198 offset:48384
	s_waitcnt lgkmcnt(6)
	v_pk_mul_f32 v[146:147], v[68:69], v[80:81] op_sel_hi:[0,1]
	v_pk_fma_f32 v[146:147], v[68:69], v[82:83], v[146:147] op_sel:[1,0,0] op_sel_hi:[1,1,1]
	v_pk_fma_f32 v[146:147], v[70:71], v[84:85], v[146:147] op_sel_hi:[0,1,1]
	v_pk_fma_f32 v[146:147], v[70:71], v[86:87], v[146:147] op_sel:[1,0,0] op_sel_hi:[1,1,1]
	v_pk_mul_f32 v[152:153], v[92:93], v[96:97] op_sel_hi:[1,0]
	v_pk_mul_f32 v[154:155], v[94:95], v[96:97] op_sel_hi:[1,0]
	v_add_f32_dpp v150, v146, v146 quad_perm:[1,0,3,2] row_mask:0xf bank_mask:0xf bound_ctrl:1
	v_pk_fma_f32 v[152:153], v[68:69], v[76:77], v[152:153]
	v_pk_fma_f32 v[154:155], v[70:71], v[78:79], v[154:155]
	v_add_f32_dpp v150, v150, v150 quad_perm:[2,3,0,1] row_mask:0xf bank_mask:0xf bound_ctrl:1
	s_nop 0
	s_nop 0
	v_add_f32_dpp v150, v150, v150 row_half_mirror row_mask:0xf bank_mask:0xf bound_ctrl:1
	s_nop 0
	s_nop 0
	v_add_f32_dpp v150, v150, v150 row_mirror row_mask:0xf bank_mask:0xf bound_ctrl:1
	v_pk_fma_f32 v[72:73], v[88:89], v[150:151], v[152:153] op_sel_hi:[1,0,1]
	v_pk_fma_f32 v[74:75], v[90:91], v[150:151], v[154:155] op_sel_hi:[1,0,1]
	s_waitcnt lgkmcnt(0)
	v_pk_mul_f32 v[148:149], v[72:73], v[102:103] op_sel_hi:[0,1]
	v_pk_fma_f32 v[148:149], v[72:73], v[104:105], v[148:149] op_sel:[1,0,0] op_sel_hi:[1,1,1]
	v_pk_fma_f32 v[148:149], v[74:75], v[106:107], v[148:149] op_sel_hi:[0,1,1]
	v_pk_fma_f32 v[148:149], v[74:75], v[108:109], v[148:149] op_sel:[1,0,0] op_sel_hi:[1,1,1]
	v_pk_mul_f32 v[152:153], v[114:115], v[118:119] op_sel_hi:[1,0]
	v_pk_mul_f32 v[154:155], v[116:117], v[118:119] op_sel_hi:[1,0]
	v_add_f32_dpp v150, v148, v148 quad_perm:[1,0,3,2] row_mask:0xf bank_mask:0xf bound_ctrl:1
	v_pk_fma_f32 v[152:153], v[72:73], v[98:99], v[152:153]
	v_pk_fma_f32 v[154:155], v[74:75], v[100:101], v[154:155]
	v_add_f32_dpp v150, v150, v150 quad_perm:[2,3,0,1] row_mask:0xf bank_mask:0xf bound_ctrl:1
	s_nop 0
	s_nop 0
	v_add_f32_dpp v150, v150, v150 row_half_mirror row_mask:0xf bank_mask:0xf bound_ctrl:1
	s_nop 0
	s_nop 0
	v_add_f32_dpp v150, v150, v150 row_mirror row_mask:0xf bank_mask:0xf bound_ctrl:1
	v_pk_fma_f32 v[68:69], v[110:111], v[150:151], v[152:153] op_sel_hi:[1,0,1]
	v_pk_fma_f32 v[70:71], v[112:113], v[150:151], v[154:155] op_sel_hi:[1,0,1]
	s_branch .LBB0_891

; __device__ __forceinline__ void rwkv_scan(Frame& F, int wg, unsigned* shw, unsigned wait_target, int wait_blk) {
;     ...
;             RwOps R[4];
;             RW_LD(R[0], 0); RW_LD(R[1], 1); RW_LD(R[2], 2);
;             for (int s4 = 0; s4 < RW_TB; s4 += 4) {
;                 float pz[4], u[4];
; #pragma unroll
;                 for (int q = 0; q < 4; ++q) {
;                     RW_LD(R[(q + 3) & 3], s4 + q + 3);
;                     const RwOps& cur = R[q];
;                     const f32x2 slo = {st.x, st.y}, shi = {st.z, st.w};
;                     f32x2 ma = slo * (f32x2){cur.a.x, cur.a.y}; ma = __builtin_elementwise_fma(shi, (f32x2){cur.a.z, cur.a.w}, ma);
;                     f32x2 mz = slo * (f32x2){cur.wr.x, cur.wr.y}; mz = __builtin_elementwise_fma(shi, (f32x2){cur.wr.z, cur.wr.w}, mz);
;                     float psa = ma.x + ma.y; pz[q] = mz.x + mz.y;
;                     const f32x2 vb = {cur.vs.x, cur.vs.x};
;                     f32x2 tlo = (f32x2){cur.k.x, cur.k.y} * vb, thi = (f32x2){cur.k.z, cur.k.w} * vb;
;                     tlo = __builtin_elementwise_fma(slo, (f32x2){cur.w.x, cur.w.y}, tlo); thi = __builtin_elementwise_fma(shi, (f32x2){cur.w.z, cur.w.w}, thi);
;                     psa = red16(psa);
;                     const f32x2 pb = {psa, psa};
;                     tlo = __builtin_elementwise_fma((f32x2){cur.b.x, cur.b.y}, pb, tlo); thi = __builtin_elementwise_fma((f32x2){cur.b.z, cur.b.w}, pb, thi);
;                     st = (f32x4){tlo.x, tlo.y, thi.x, thi.y};
;                     u[q] = psa * cur.vs.z + cur.vs.y;
;                 }
;                 const float qa = (odd1 ? pz[1] : pz[0]) + dppf<0xB1>(odd1 ? pz[0] : pz[1]);
;                 const float qb = (odd1 ? pz[3] : pz[2]) + dppf<0xB1>(odd1 ? pz[2] : pz[3]);
;                 float r = (odd2 ? qb : qa) + dppf<0x4E>(odd2 ? qa : qb);
;                 r += dppf<0x124>(r); r += dppf<0x128>(r);
;                 const float us = odd2 ? (odd1 ? u[3] : u[2]) : (odd1 ? u[1] : u[0]);
;                 if (j < 4) { const int t = blk * RW_TB + s4 + j; ((float*)(Ub + (size_t)t * (PWP * 2) + URR * 2))[h * 64 + row] = r + us; }
;             }
;     ...
;         __syncthreads();
;         if (loader) { if (blk + 2 < NBLK) { lstore(L1, 0); if (blk + 4 < NBLK) gload(L1, blk + 4); } }
;         else scan_block(blk + 1);
.LBB0_891:
	s_mov_b64 s[50:51], -1
	s_and_b64 vcc, exec, s[26:27]
	s_waitcnt lgkmcnt(0)
	s_barrier
	s_cbranch_vccz .LBB0_909
	s_mul_i32 s50, s59, 0x58000
	s_add_i32 s50, s50, 0x4d000
	v_add_u32_e32 v160, v198, v202
	ds_read_b128 v[80:83], v160 offset:256
	ds_read_b128 v[84:87], v160 offset:272
	ds_read_b128 v[92:95], v202 offset:1024
	ds_read_b32 v96, v206 offset:0
	ds_read_b128 v[76:79], v202 offset:0
	ds_read_b128 v[88:91], v202 offset:768
	ds_read_b128 v[102:105], v160 offset:1792
	ds_read_b128 v[106:109], v160 offset:1808
	ds_read_b128 v[114:117], v202 offset:2560
	ds_read_b32 v118, v206 offset:1536
	ds_read_b128 v[98:101], v202 offset:1536
	ds_read_b128 v[110:113], v202 offset:2304
	v_lshrrev_b32_e32 v159, 2, v194
	v_mul_u32_u24_e32 v159, 0x2c00, v159
	v_lshl_add_u32 v159, v186, 2, v159
	v_add_u32_e32 v159, s50, v159
	s_waitcnt lgkmcnt(6)
	v_pk_mul_f32 v[142:143], v[68:69], v[80:81] op_sel_hi:[0,1]
	v_pk_fma_f32 v[142:143], v[68:69], v[82:83], v[142:143] op_sel:[1,0,0] op_sel_hi:[1,1,1]
	v_pk_fma_f32 v[142:143], v[70:71], v[84:85], v[142:143] op_sel_hi:[0,1,1]
	v_pk_fma_f32 v[142:143], v[70:71], v[86:87], v[142:143] op_sel:[1,0,0] op_sel_hi:[1,1,1]
	v_pk_mul_f32 v[152:153], v[92:93], v[96:97] op_sel_hi:[1,0]
	v_pk_mul_f32 v[154:155], v[94:95], v[96:97] op_sel_hi:[1,0]
	v_add_f32_dpp v150, v142, v142 quad_perm:[1,0,3,2] row_mask:0xf bank_mask:0xf bound_ctrl:1
	v_pk_fma_f32 v[152:153], v[68:69], v[76:77], v[152:153]
	v_pk_fma_f32 v[154:155], v[70:71], v[78:79], v[154:155]
	v_add_f32_dpp v150, v150, v150 quad_perm:[2,3,0,1] row_mask:0xf bank_mask:0xf bound_ctrl:1
	v_add_f32_dpp v156, v145, v145 row_ror:8 row_mask:0xf bank_mask:0xf
	v_add_f32_dpp v157, v147, v147 row_ror:8 row_mask:0xf bank_mask:0xf
	v_add_f32_dpp v150, v150, v150 row_half_mirror row_mask:0xf bank_mask:0xf bound_ctrl:1
	v_add_f32_dpp v156, v149, v149 row_ror:8 row_mask:0xf bank_mask:0xc
	v_add_f32_dpp v157, v143, v143 row_ror:8 row_mask:0xf bank_mask:0xc
	v_add_f32_dpp v150, v150, v150 row_mirror row_mask:0xf bank_mask:0xf bound_ctrl:1
	v_pk_fma_f32 v[72:73], v[88:89], v[150:151], v[152:153] op_sel_hi:[1,0,1]
	v_pk_fma_f32 v[74:75], v[90:91], v[150:151], v[154:155] op_sel_hi:[1,0,1]
	ds_read_b128 v[124:127], v160 offset:3328
	ds_read_b128 v[128:131], v160 offset:3344
	v_add_f32_dpp v158, v156, v156 row_half_mirror row_mask:0xf bank_mask:0xf
	v_add_f32_dpp v158, v157, v157 row_half_mirror row_mask:0xf bank_mask:0xa
	ds_read_b128 v[136:139], v202 offset:4096
	ds_read_b32 v140, v206 offset:3072
	v_add_f32_dpp v158, v158, v158 quad_perm:[1,0,3,2] row_mask:0xf bank_mask:0xf bound_ctrl:1
	ds_read_b128 v[120:123], v202 offset:3072
	ds_read_b128 v[132:135], v202 offset:3840
	v_add_f32_dpp v158, v158, v158 quad_perm:[2,3,0,1] row_mask:0xf bank_mask:0xf bound_ctrl:1
	global_store_dword v159, v158, s[34:35]
	v_add_u32_e32 v159, 0xb000, v159
	s_waitcnt lgkmcnt(6)
	v_pk_mul_f32 v[144:145], v[72:73], v[102:103] op_sel_hi:[0,1]
	v_pk_fma_f32 v[144:145], v[72:73], v[104:105], v[144:145] op_sel:[1,0,0] op_sel_hi:[1,1,1]
	v_pk_fma_f32 v[144:145], v[74:75], v[106:107], v[144:145] op_sel_hi:[0,1,1]
	v_pk_fma_f32 v[144:145], v[74:75], v[108:109], v[144:145] op_sel:[1,0,0] op_sel_hi:[1,1,1]
	v_pk_mul_f32 v[152:153], v[114:115], v[118:119] op_sel_hi:[1,0]
	v_pk_mul_f32 v[154:155], v[116:117], v[118:119] op_sel_hi:[1,0]
	v_add_f32_dpp v150, v144, v144 quad_perm:[1,0,3,2] row_mask:0xf bank_mask:0xf bound_ctrl:1
	v_pk_fma_f32 v[152:153], v[72:73], v[98:99], v[152:153]
	v_pk_fma_f32 v[154:155], v[74:75], v[100:101], v[154:155]
	v_add_f32_dpp v150, v150, v150 quad_perm:[2,3,0,1] row_mask:0xf bank_mask:0xf bound_ctrl:1
	ds_read_b128 v[80:83], v160 offset:4864
	ds_read_b128 v[84:87], v160 offset:4880
	v_add_f32_dpp v150, v150, v150 row_half_mirror row_mask:0xf bank_mask:0xf bound_ctrl:1
	ds_read_b128 v[92:95], v202 offset:5632
	ds_read_b32 v96, v206 offset:4608
	v_add_f32_dpp v150, v150, v150 row_mirror row_mask:0xf bank_mask:0xf bound_ctrl:1
	v_pk_fma_f32 v[68:69], v[110:111], v[150:151], v[152:153] op_sel_hi:[1,0,1]
	v_pk_fma_f32 v[70:71], v[112:113], v[150:151], v[154:155] op_sel_hi:[1,0,1]
	ds_read_b128 v[76:79], v202 offset:4608
	ds_read_b128 v[88:91], v202 offset:5376
	s_waitcnt lgkmcnt(6)
	v_pk_mul_f32 v[146:147], v[68:69], v[124:125] op_sel_hi:[0,1]
	v_pk_fma_f32 v[146:147], v[68:69], v[126:127], v[146:147] op_sel:[1,0,0] op_sel_hi:[1,1,1]
	v_pk_fma_f32 v[146:147], v[70:71], v[128:129], v[146:147] op_sel_hi:[0,1,1]
	v_pk_fma_f32 v[146:147], v[70:71], v[130:131], v[146:147] op_sel:[1,0,0] op_sel_hi:[1,1,1]
	v_pk_mul_f32 v[152:153], v[136:137], v[140:141] op_sel_hi:[1,0]
	v_pk_mul_f32 v[154:155], v[138:139], v[140:141] op_sel_hi:[1,0]
	v_add_f32_dpp v150, v146, v146 quad_perm:[1,0,3,2] row_mask:0xf bank_mask:0xf bound_ctrl:1
	v_pk_fma_f32 v[152:153], v[68:69], v[120:121], v[152:153]
	v_pk_fma_f32 v[154:155], v[70:71], v[122:123], v[154:155]
	v_add_f32_dpp v150, v150, v150 quad_perm:[2,3,0,1] row_mask:0xf bank_mask:0xf bound_ctrl:1
	ds_read_b128 v[102:105], v160 offset:6400
	ds_read_b128 v[106:109], v160 offset:6416
	v_add_f32_dpp v150, v150, v150 row_half_mirror row_mask:0xf bank_mask:0xf bound_ctrl:1
	ds_read_b128 v[114:117], v202 offset:7168
	ds_read_b32 v118, v206 offset:6144
	v_add_f32_dpp v150, v150, v150 row_mirror row_mask:0xf bank_mask:0xf bound_ctrl:1
	v_pk_fma_f32 v[72:73], v[132:133], v[150:151], v[152:153] op_sel_hi:[1,0,1]
	v_pk_fma_f32 v[74:75], v[134:135], v[150:151], v[154:155] op_sel_hi:[1,0,1]
	ds_read_b128 v[98:101], v202 offset:6144
	ds_read_b128 v[110:113], v202 offset:6912
	s_waitcnt lgkmcnt(6)
; __device__ __forceinline__ void rwkv_scan(Frame& F, int wg, unsigned* shw, unsigned wait_target, int wait_blk) {
;     ...
;             RwOps R[4];
;             RW_LD(R[0], 0); RW_LD(R[1], 1); RW_LD(R[2], 2);
;             for (int s4 = 0; s4 < RW_TB; s4 += 4) {
;                 float pz[4], u[4];
; #pragma unroll
;                 for (int q = 0; q < 4; ++q) {
;                     RW_LD(R[(q + 3) & 3], s4 + q + 3);
;                     const RwOps& cur = R[q];
;                     const f32x2 slo = {st.x, st.y}, shi = {st.z, st.w};
;                     f32x2 ma = slo * (f32x2){cur.a.x, cur.a.y}; ma = __builtin_elementwise_fma(shi, (f32x2){cur.a.z, cur.a.w}, ma);
;                     f32x2 mz = slo * (f32x2){cur.wr.x, cur.wr.y}; mz = __builtin_elementwise_fma(shi, (f32x2){cur.wr.z, cur.wr.w}, mz);
;                     float psa = ma.x + ma.y; pz[q] = mz.x + mz.y;
;                     const f32x2 vb = {cur.vs.x, cur.vs.x};
;                     f32x2 tlo = (f32x2){cur.k.x, cur.k.y} * vb, thi = (f32x2){cur.k.z, cur.k.w} * vb;
;                     tlo = __builtin_elementwise_fma(slo, (f32x2){cur.w.x, cur.w.y}, tlo); thi = __builtin_elementwise_fma(shi, (f32x2){cur.w.z, cur.w.w}, thi);
;                     psa = red16(psa);
;                     const f32x2 pb = {psa, psa};
;                     tlo = __builtin_elementwise_fma((f32x2){cur.b.x, cur.b.y}, pb, tlo); thi = __builtin_elementwise_fma((f32x2){cur.b.z, cur.b.w}, pb, thi);
;                     st = (f32x4){tlo.x, tlo.y, thi.x, thi.y};
;                     u[q] = psa * cur.vs.z + cur.vs.y;
;                 }
;                 const float qa = (odd1 ? pz[1] : pz[0]) + dppf<0xB1>(odd1 ? pz[0] : pz[1]);
;                 const float qb = (odd1 ? pz[3] : pz[2]) + dppf<0xB1>(odd1 ? pz[2] : pz[3]);
;                 float r = (odd2 ? qb : qa) + dppf<0x4E>(odd2 ? qa : qb);
;                 r += dppf<0x124>(r); r += dppf<0x128>(r);
;                 const float us = odd2 ? (odd1 ? u[3] : u[2]) : (odd1 ? u[1] : u[0]);
;                 if (j < 4) { const int t = blk * RW_TB + s4 + j; ((float*)(Ub + (size_t)t * (PWP * 2) + URR * 2))[h * 64 + row] = r + us; }
	v_pk_mul_f32 v[148:149], v[72:73], v[80:81] op_sel_hi:[0,1]
	v_pk_fma_f32 v[148:149], v[72:73], v[82:83], v[148:149] op_sel:[1,0,0] op_sel_hi:[1,1,1]
	v_pk_fma_f32 v[148:149], v[74:75], v[84:85], v[148:149] op_sel_hi:[0,1,1]
	v_pk_fma_f32 v[148:149], v[74:75], v[86:87], v[148:149] op_sel:[1,0,0] op_sel_hi:[1,1,1]
	v_pk_mul_f32 v[152:153], v[92:93], v[96:97] op_sel_hi:[1,0]
	v_pk_mul_f32 v[154:155], v[94:95], v[96:97] op_sel_hi:[1,0]
	v_add_f32_dpp v150, v148, v148 quad_perm:[1,0,3,2] row_mask:0xf bank_mask:0xf bound_ctrl:1
	v_pk_fma_f32 v[152:153], v[72:73], v[76:77], v[152:153]
	v_pk_fma_f32 v[154:155], v[74:75], v[78:79], v[154:155]
	v_add_f32_dpp v150, v150, v150 quad_perm:[2,3,0,1] row_mask:0xf bank_mask:0xf bound_ctrl:1
	ds_read_b128 v[124:127], v160 offset:7936
	ds_read_b128 v[128:131], v160 offset:7952
	v_add_f32_dpp v150, v150, v150 row_half_mirror row_mask:0xf bank_mask:0xf bound_ctrl:1
	ds_read_b128 v[136:139], v202 offset:8704
	ds_read_b32 v140, v206 offset:7680
	v_add_f32_dpp v150, v150, v150 row_mirror row_mask:0xf bank_mask:0xf bound_ctrl:1
	v_pk_fma_f32 v[68:69], v[88:89], v[150:151], v[152:153] op_sel_hi:[1,0,1]
	v_pk_fma_f32 v[70:71], v[90:91], v[150:151], v[154:155] op_sel_hi:[1,0,1]
	ds_read_b128 v[120:123], v202 offset:7680
	ds_read_b128 v[132:135], v202 offset:8448
	s_waitcnt lgkmcnt(6)
	v_pk_mul_f32 v[142:143], v[68:69], v[102:103] op_sel_hi:[0,1]
	v_pk_fma_f32 v[142:143], v[68:69], v[104:105], v[142:143] op_sel:[1,0,0] op_sel_hi:[1,1,1]
	v_pk_fma_f32 v[142:143], v[70:71], v[106:107], v[142:143] op_sel_hi:[0,1,1]
	v_pk_fma_f32 v[142:143], v[70:71], v[108:109], v[142:143] op_sel:[1,0,0] op_sel_hi:[1,1,1]
	v_pk_mul_f32 v[152:153], v[114:115], v[118:119] op_sel_hi:[1,0]
	v_pk_mul_f32 v[154:155], v[116:117], v[118:119] op_sel_hi:[1,0]
	v_add_f32_dpp v150, v142, v142 quad_perm:[1,0,3,2] row_mask:0xf bank_mask:0xf bound_ctrl:1
	v_pk_fma_f32 v[152:153], v[68:69], v[98:99], v[152:153]
	v_pk_fma_f32 v[154:155], v[70:71], v[100:101], v[154:155]
	v_add_f32_dpp v150, v150, v150 quad_perm:[2,3,0,1] row_mask:0xf bank_mask:0xf bound_ctrl:1
	v_add_f32_dpp v156, v145, v145 row_ror:8 row_mask:0xf bank_mask:0xf
	v_add_f32_dpp v157, v147, v147 row_ror:8 row_mask:0xf bank_mask:0xf
	v_add_f32_dpp v150, v150, v150 row_half_mirror row_mask:0xf bank_mask:0xf bound_ctrl:1
	v_add_f32_dpp v156, v149, v149 row_ror:8 row_mask:0xf bank_mask:0xc
	v_add_f32_dpp v157, v143, v143 row_ror:8 row_mask:0xf bank_mask:0xc
	v_add_f32_dpp v150, v150, v150 row_mirror row_mask:0xf bank_mask:0xf bound_ctrl:1
	v_pk_fma_f32 v[72:73], v[110:111], v[150:151], v[152:153] op_sel_hi:[1,0,1]
	v_pk_fma_f32 v[74:75], v[112:113], v[150:151], v[154:155] op_sel_hi:[1,0,1]
	ds_read_b128 v[80:83], v160 offset:9472
	ds_read_b128 v[84:87], v160 offset:9488
	v_add_f32_dpp v158, v156, v156 row_half_mirror row_mask:0xf bank_mask:0xf
	v_add_f32_dpp v158, v157, v157 row_half_mirror row_mask:0xf bank_mask:0xa
	ds_read_b128 v[92:95], v202 offset:10240
	ds_read_b32 v96, v206 offset:9216
	v_add_f32_dpp v158, v158, v158 quad_perm:[1,0,3,2] row_mask:0xf bank_mask:0xf bound_ctrl:1
	ds_read_b128 v[76:79], v202 offset:9216
	ds_read_b128 v[88:91], v202 offset:9984
	v_add_f32_dpp v158, v158, v158 quad_perm:[2,3,0,1] row_mask:0xf bank_mask:0xf bound_ctrl:1
	global_store_dword v159, v158, s[34:35]
	v_add_u32_e32 v159, 0xb000, v159
	s_waitcnt lgkmcnt(6)
	v_pk_mul_f32 v[144:145], v[72:73], v[124:125] op_sel_hi:[0,1]
	v_pk_fma_f32 v[144:145], v[72:73], v[126:127], v[144:145] op_sel:[1,0,0] op_sel_hi:[1,1,1]
	v_pk_fma_f32 v[144:145], v[74:75], v[128:129], v[144:145] op_sel_hi:[0,1,1]
	v_pk_fma_f32 v[144:145], v[74:75], v[130:131], v[144:145] op_sel:[1,0,0] op_sel_hi:[1,1,1]
	v_pk_mul_f32 v[152:153], v[136:137], v[140:141] op_sel_hi:[1,0]
	v_pk_mul_f32 v[154:155], v[138:139], v[140:141] op_sel_hi:[1,0]
	v_add_f32_dpp v150, v144, v144 quad_perm:[1,0,3,2] row_mask:0xf bank_mask:0xf bound_ctrl:1
	v_pk_fma_f32 v[152:153], v[72:73], v[120:121], v[152:153]
	v_pk_fma_f32 v[154:155], v[74:75], v[122:123], v[154:155]
	v_add_f32_dpp v150, v150, v150 quad_perm:[2,3,0,1] row_mask:0xf bank_mask:0xf bound_ctrl:1
	ds_read_b128 v[102:105], v160 offset:11008
	ds_read_b128 v[106:109], v160 offset:11024
	v_add_f32_dpp v150, v150, v150 row_half_mirror row_mask:0xf bank_mask:0xf bound_ctrl:1
	ds_read_b128 v[114:117], v202 offset:11776
	ds_read_b32 v118, v206 offset:10752
	v_add_f32_dpp v150, v150, v150 row_mirror row_mask:0xf bank_mask:0xf bound_ctrl:1
	v_pk_fma_f32 v[68:69], v[132:133], v[150:151], v[152:153] op_sel_hi:[1,0,1]
	v_pk_fma_f32 v[70:71], v[134:135], v[150:151], v[154:155] op_sel_hi:[1,0,1]
	ds_read_b128 v[98:101], v202 offset:10752
	ds_read_b128 v[110:113], v202 offset:11520
	s_waitcnt lgkmcnt(6)
	v_pk_mul_f32 v[146:147], v[68:69], v[80:81] op_sel_hi:[0,1]
	v_pk_fma_f32 v[146:147], v[68:69], v[82:83], v[146:147] op_sel:[1,0,0] op_sel_hi:[1,1,1]
	v_pk_fma_f32 v[146:147], v[70:71], v[84:85], v[146:147] op_sel_hi:[0,1,1]
	v_pk_fma_f32 v[146:147], v[70:71], v[86:87], v[146:147] op_sel:[1,0,0] op_sel_hi:[1,1,1]
	v_pk_mul_f32 v[152:153], v[92:93], v[96:97] op_sel_hi:[1,0]
	v_pk_mul_f32 v[154:155], v[94:95], v[96:97] op_sel_hi:[1,0]
	v_add_f32_dpp v150, v146, v146 quad_perm:[1,0,3,2] row_mask:0xf bank_mask:0xf bound_ctrl:1
	v_pk_fma_f32 v[152:153], v[68:69], v[76:77], v[152:153]
	v_pk_fma_f32 v[154:155], v[70:71], v[78:79], v[154:155]
	v_add_f32_dpp v150, v150, v150 quad_perm:[2,3,0,1] row_mask:0xf bank_mask:0xf bound_ctrl:1
	ds_read_b128 v[124:127], v160 offset:12544
	ds_read_b128 v[128:131], v160 offset:12560
	v_add_f32_dpp v150, v150, v150 row_half_mirror row_mask:0xf bank_mask:0xf bound_ctrl:1
	ds_read_b128 v[136:139], v202 offset:13312
	ds_read_b32 v140, v206 offset:12288
	v_add_f32_dpp v150, v150, v150 row_mirror row_mask:0xf bank_mask:0xf bound_ctrl:1
	v_pk_fma_f32 v[72:73], v[88:89], v[150:151], v[152:153] op_sel_hi:[1,0,1]
	v_pk_fma_f32 v[74:75], v[90:91], v[150:151], v[154:155] op_sel_hi:[1,0,1]
	ds_read_b128 v[120:123], v202 offset:12288
	ds_read_b128 v[132:135], v202 offset:13056
	s_waitcnt lgkmcnt(6)
; __device__ __forceinline__ void rwkv_scan(Frame& F, int wg, unsigned* shw, unsigned wait_target, int wait_blk) {
;     ...
;             RwOps R[4];
;             RW_LD(R[0], 0); RW_LD(R[1], 1); RW_LD(R[2], 2);
;             for (int s4 = 0; s4 < RW_TB; s4 += 4) {
;                 float pz[4], u[4];
; #pragma unroll
;                 for (int q = 0; q < 4; ++q) {
;                     RW_LD(R[(q + 3) & 3], s4 + q + 3);
;                     const RwOps& cur = R[q];
;                     const f32x2 slo = {st.x, st.y}, shi = {st.z, st.w};
;                     f32x2 ma = slo * (f32x2){cur.a.x, cur.a.y}; ma = __builtin_elementwise_fma(shi, (f32x2){cur.a.z, cur.a.w}, ma);
;                     f32x2 mz = slo * (f32x2){cur.wr.x, cur.wr.y}; mz = __builtin_elementwise_fma(shi, (f32x2){cur.wr.z, cur.wr.w}, mz);
;                     float psa = ma.x + ma.y; pz[q] = mz.x + mz.y;
;                     const f32x2 vb = {cur.vs.x, cur.vs.x};
;                     f32x2 tlo = (f32x2){cur.k.x, cur.k.y} * vb, thi = (f32x2){cur.k.z, cur.k.w} * vb;
;                     tlo = __builtin_elementwise_fma(slo, (f32x2){cur.w.x, cur.w.y}, tlo); thi = __builtin_elementwise_fma(shi, (f32x2){cur.w.z, cur.w.w}, thi);
;                     psa = red16(psa);
;                     const f32x2 pb = {psa, psa};
;                     tlo = __builtin_elementwise_fma((f32x2){cur.b.x, cur.b.y}, pb, tlo); thi = __builtin_elementwise_fma((f32x2){cur.b.z, cur.b.w}, pb, thi);
;                     st = (f32x4){tlo.x, tlo.y, thi.x, thi.y};
;                     u[q] = psa * cur.vs.z + cur.vs.y;
;                 }
;                 const float qa = (odd1 ? pz[1] : pz[0]) + dppf<0xB1>(odd1 ? pz[0] : pz[1]);
;                 const float qb = (odd1 ? pz[3] : pz[2]) + dppf<0xB1>(odd1 ? pz[2] : pz[3]);
;                 float r = (odd2 ? qb : qa) + dppf<0x4E>(odd2 ? qa : qb);
;                 r += dppf<0x124>(r); r += dppf<0x128>(r);
;                 const float us = odd2 ? (odd1 ? u[3] : u[2]) : (odd1 ? u[1] : u[0]);
;                 if (j < 4) { const int t = blk * RW_TB + s4 + j; ((float*)(Ub + (size_t)t * (PWP * 2) + URR * 2))[h * 64 + row] = r + us; }
	v_pk_mul_f32 v[148:149], v[72:73], v[102:103] op_sel_hi:[0,1]
	v_pk_fma_f32 v[148:149], v[72:73], v[104:105], v[148:149] op_sel:[1,0,0] op_sel_hi:[1,1,1]
	v_pk_fma_f32 v[148:149], v[74:75], v[106:107], v[148:149] op_sel_hi:[0,1,1]
	v_pk_fma_f32 v[148:149], v[74:75], v[108:109], v[148:149] op_sel:[1,0,0] op_sel_hi:[1,1,1]
	v_pk_mul_f32 v[152:153], v[114:115], v[118:119] op_sel_hi:[1,0]
	v_pk_mul_f32 v[154:155], v[116:117], v[118:119] op_sel_hi:[1,0]
	v_add_f32_dpp v150, v148, v148 quad_perm:[1,0,3,2] row_mask:0xf bank_mask:0xf bound_ctrl:1
	v_pk_fma_f32 v[152:153], v[72:73], v[98:99], v[152:153]
	v_pk_fma_f32 v[154:155], v[74:75], v[100:101], v[154:155]
	v_add_f32_dpp v150, v150, v150 quad_perm:[2,3,0,1] row_mask:0xf bank_mask:0xf bound_ctrl:1
	ds_read_b128 v[80:83], v160 offset:14080
	ds_read_b128 v[84:87], v160 offset:14096
	v_add_f32_dpp v150, v150, v150 row_half_mirror row_mask:0xf bank_mask:0xf bound_ctrl:1
	ds_read_b128 v[92:95], v202 offset:14848
	ds_read_b32 v96, v206 offset:13824
	v_add_f32_dpp v150, v150, v150 row_mirror row_mask:0xf bank_mask:0xf bound_ctrl:1
	v_pk_fma_f32 v[68:69], v[110:111], v[150:151], v[152:153] op_sel_hi:[1,0,1]
	v_pk_fma_f32 v[70:71], v[112:113], v[150:151], v[154:155] op_sel_hi:[1,0,1]
	ds_read_b128 v[76:79], v202 offset:13824
	ds_read_b128 v[88:91], v202 offset:14592
	s_waitcnt lgkmcnt(6)
	v_pk_mul_f32 v[142:143], v[68:69], v[124:125] op_sel_hi:[0,1]
	v_pk_fma_f32 v[142:143], v[68:69], v[126:127], v[142:143] op_sel:[1,0,0] op_sel_hi:[1,1,1]
	v_pk_fma_f32 v[142:143], v[70:71], v[128:129], v[142:143] op_sel_hi:[0,1,1]
	v_pk_fma_f32 v[142:143], v[70:71], v[130:131], v[142:143] op_sel:[1,0,0] op_sel_hi:[1,1,1]
	v_pk_mul_f32 v[152:153], v[136:137], v[140:141] op_sel_hi:[1,0]
	v_pk_mul_f32 v[154:155], v[138:139], v[140:141] op_sel_hi:[1,0]
	v_add_f32_dpp v150, v142, v142 quad_perm:[1,0,3,2] row_mask:0xf bank_mask:0xf bound_ctrl:1
	v_pk_fma_f32 v[152:153], v[68:69], v[120:121], v[152:153]
	v_pk_fma_f32 v[154:155], v[70:71], v[122:123], v[154:155]
	v_add_f32_dpp v150, v150, v150 quad_perm:[2,3,0,1] row_mask:0xf bank_mask:0xf bound_ctrl:1
	v_add_f32_dpp v156, v145, v145 row_ror:8 row_mask:0xf bank_mask:0xf
	v_add_f32_dpp v157, v147, v147 row_ror:8 row_mask:0xf bank_mask:0xf
	v_add_f32_dpp v150, v150, v150 row_half_mirror row_mask:0xf bank_mask:0xf bound_ctrl:1
	v_add_f32_dpp v156, v149, v149 row_ror:8 row_mask:0xf bank_mask:0xc
	v_add_f32_dpp v157, v143, v143 row_ror:8 row_mask:0xf bank_mask:0xc
	v_add_f32_dpp v150, v150, v150 row_mirror row_mask:0xf bank_mask:0xf bound_ctrl:1
	v_pk_fma_f32 v[72:73], v[132:133], v[150:151], v[152:153] op_sel_hi:[1,0,1]
	v_pk_fma_f32 v[74:75], v[134:135], v[150:151], v[154:155] op_sel_hi:[1,0,1]
	ds_read_b128 v[102:105], v160 offset:15616
	ds_read_b128 v[106:109], v160 offset:15632
	v_add_f32_dpp v158, v156, v156 row_half_mirror row_mask:0xf bank_mask:0xf
	v_add_f32_dpp v158, v157, v157 row_half_mirror row_mask:0xf bank_mask:0xa
	ds_read_b128 v[114:117], v202 offset:16384
	ds_read_b32 v118, v206 offset:15360
	v_add_f32_dpp v158, v158, v158 quad_perm:[1,0,3,2] row_mask:0xf bank_mask:0xf bound_ctrl:1
	ds_read_b128 v[98:101], v202 offset:15360
	ds_read_b128 v[110:113], v202 offset:16128
	v_add_f32_dpp v158, v158, v158 quad_perm:[2,3,0,1] row_mask:0xf bank_mask:0xf bound_ctrl:1
	global_store_dword v159, v158, s[34:35]
	v_add_u32_e32 v159, 0xb000, v159
	s_waitcnt lgkmcnt(6)
	v_pk_mul_f32 v[144:145], v[72:73], v[80:81] op_sel_hi:[0,1]
	v_pk_fma_f32 v[144:145], v[72:73], v[82:83], v[144:145] op_sel:[1,0,0] op_sel_hi:[1,1,1]
	v_pk_fma_f32 v[144:145], v[74:75], v[84:85], v[144:145] op_sel_hi:[0,1,1]
	v_pk_fma_f32 v[144:145], v[74:75], v[86:87], v[144:145] op_sel:[1,0,0] op_sel_hi:[1,1,1]
	v_pk_mul_f32 v[152:153], v[92:93], v[96:97] op_sel_hi:[1,0]
	v_pk_mul_f32 v[154:155], v[94:95], v[96:97] op_sel_hi:[1,0]
	v_add_f32_dpp v150, v144, v144 quad_perm:[1,0,3,2] row_mask:0xf bank_mask:0xf bound_ctrl:1
	v_pk_fma_f32 v[152:153], v[72:73], v[76:77], v[152:153]
	v_pk_fma_f32 v[154:155], v[74:75], v[78:79], v[154:155]
	v_add_f32_dpp v150, v150, v150 quad_perm:[2,3,0,1] row_mask:0xf bank_mask:0xf bound_ctrl:1
	ds_read_b128 v[124:127], v160 offset:17152
	ds_read_b128 v[128:131], v160 offset:17168
	v_add_f32_dpp v150, v150, v150 row_half_mirror row_mask:0xf bank_mask:0xf bound_ctrl:1
	ds_read_b128 v[136:139], v202 offset:17920
	ds_read_b32 v140, v206 offset:16896
	v_add_f32_dpp v150, v150, v150 row_mirror row_mask:0xf bank_mask:0xf bound_ctrl:1
	v_pk_fma_f32 v[68:69], v[88:89], v[150:151], v[152:153] op_sel_hi:[1,0,1]
	v_pk_fma_f32 v[70:71], v[90:91], v[150:151], v[154:155] op_sel_hi:[1,0,1]
	ds_read_b128 v[120:123], v202 offset:16896
	ds_read_b128 v[132:135], v202 offset:17664
	s_waitcnt lgkmcnt(6)
	v_pk_mul_f32 v[146:147], v[68:69], v[102:103] op_sel_hi:[0,1]
	v_pk_fma_f32 v[146:147], v[68:69], v[104:105], v[146:147] op_sel:[1,0,0] op_sel_hi:[1,1,1]
	v_pk_fma_f32 v[146:147], v[70:71], v[106:107], v[146:147] op_sel_hi:[0,1,1]
	v_pk_fma_f32 v[146:147], v[70:71], v[108:109], v[146:147] op_sel:[1,0,0] op_sel_hi:[1,1,1]
	v_pk_mul_f32 v[152:153], v[114:115], v[118:119] op_sel_hi:[1,0]
	v_pk_mul_f32 v[154:155], v[116:117], v[118:119] op_sel_hi:[1,0]
	v_add_f32_dpp v150, v146, v146 quad_perm:[1,0,3,2] row_mask:0xf bank_mask:0xf bound_ctrl:1
	v_pk_fma_f32 v[152:153], v[68:69], v[98:99], v[152:153]
	v_pk_fma_f32 v[154:155], v[70:71], v[100:101], v[154:155]
	v_add_f32_dpp v150, v150, v150 quad_perm:[2,3,0,1] row_mask:0xf bank_mask:0xf bound_ctrl:1
	ds_read_b128 v[80:83], v160 offset:18688
	ds_read_b128 v[84:87], v160 offset:18704
	v_add_f32_dpp v150, v150, v150 row_half_mirror row_mask:0xf bank_mask:0xf bound_ctrl:1
	ds_read_b128 v[92:95], v202 offset:19456
	ds_read_b32 v96, v206 offset:18432
	v_add_f32_dpp v150, v150, v150 row_mirror row_mask:0xf bank_mask:0xf bound_ctrl:1
	v_pk_fma_f32 v[72:73], v[110:111], v[150:151], v[152:153] op_sel_hi:[1,0,1]
	v_pk_fma_f32 v[74:75], v[112:113], v[150:151], v[154:155] op_sel_hi:[1,0,1]
	ds_read_b128 v[76:79], v202 offset:18432
	ds_read_b128 v[88:91], v202 offset:19200
	s_waitcnt lgkmcnt(6)
; __device__ __forceinline__ void rwkv_scan(Frame& F, int wg, unsigned* shw, unsigned wait_target, int wait_blk) {
;     ...
;             RwOps R[4];
;             RW_LD(R[0], 0); RW_LD(R[1], 1); RW_LD(R[2], 2);
;             for (int s4 = 0; s4 < RW_TB; s4 += 4) {
;                 float pz[4], u[4];
; #pragma unroll
;                 for (int q = 0; q < 4; ++q) {
;                     RW_LD(R[(q + 3) & 3], s4 + q + 3);
;                     const RwOps& cur = R[q];
;                     const f32x2 slo = {st.x, st.y}, shi = {st.z, st.w};
;                     f32x2 ma = slo * (f32x2){cur.a.x, cur.a.y}; ma = __builtin_elementwise_fma(shi, (f32x2){cur.a.z, cur.a.w}, ma);
;                     f32x2 mz = slo * (f32x2){cur.wr.x, cur.wr.y}; mz = __builtin_elementwise_fma(shi, (f32x2){cur.wr.z, cur.wr.w}, mz);
;                     float psa = ma.x + ma.y; pz[q] = mz.x + mz.y;
;                     const f32x2 vb = {cur.vs.x, cur.vs.x};
;                     f32x2 tlo = (f32x2){cur.k.x, cur.k.y} * vb, thi = (f32x2){cur.k.z, cur.k.w} * vb;
;                     tlo = __builtin_elementwise_fma(slo, (f32x2){cur.w.x, cur.w.y}, tlo); thi = __builtin_elementwise_fma(shi, (f32x2){cur.w.z, cur.w.w}, thi);
;                     psa = red16(psa);
;                     const f32x2 pb = {psa, psa};
;                     tlo = __builtin_elementwise_fma((f32x2){cur.b.x, cur.b.y}, pb, tlo); thi = __builtin_elementwise_fma((f32x2){cur.b.z, cur.b.w}, pb, thi);
;                     st = (f32x4){tlo.x, tlo.y, thi.x, thi.y};
;                     u[q] = psa * cur.vs.z + cur.vs.y;
;                 }
;                 const float qa = (odd1 ? pz[1] : pz[0]) + dppf<0xB1>(odd1 ? pz[0] : pz[1]);
;                 const float qb = (odd1 ? pz[3] : pz[2]) + dppf<0xB1>(odd1 ? pz[2] : pz[3]);
;                 float r = (odd2 ? qb : qa) + dppf<0x4E>(odd2 ? qa : qb);
;                 r += dppf<0x124>(r); r += dppf<0x128>(r);
;                 const float us = odd2 ? (odd1 ? u[3] : u[2]) : (odd1 ? u[1] : u[0]);
;                 if (j < 4) { const int t = blk * RW_TB + s4 + j; ((float*)(Ub + (size_t)t * (PWP * 2) + URR * 2))[h * 64 + row] = r + us; }
	v_pk_mul_f32 v[148:149], v[72:73], v[124:125] op_sel_hi:[0,1]
	v_pk_fma_f32 v[148:149], v[72:73], v[126:127], v[148:149] op_sel:[1,0,0] op_sel_hi:[1,1,1]
	v_pk_fma_f32 v[148:149], v[74:75], v[128:129], v[148:149] op_sel_hi:[0,1,1]
	v_pk_fma_f32 v[148:149], v[74:75], v[130:131], v[148:149] op_sel:[1,0,0] op_sel_hi:[1,1,1]
	v_pk_mul_f32 v[152:153], v[136:137], v[140:141] op_sel_hi:[1,0]
	v_pk_mul_f32 v[154:155], v[138:139], v[140:141] op_sel_hi:[1,0]
	v_add_f32_dpp v150, v148, v148 quad_perm:[1,0,3,2] row_mask:0xf bank_mask:0xf bound_ctrl:1
	v_pk_fma_f32 v[152:153], v[72:73], v[120:121], v[152:153]
	v_pk_fma_f32 v[154:155], v[74:75], v[122:123], v[154:155]
	v_add_f32_dpp v150, v150, v150 quad_perm:[2,3,0,1] row_mask:0xf bank_mask:0xf bound_ctrl:1
	ds_read_b128 v[102:105], v160 offset:20224
	ds_read_b128 v[106:109], v160 offset:20240
	v_add_f32_dpp v150, v150, v150 row_half_mirror row_mask:0xf bank_mask:0xf bound_ctrl:1
	ds_read_b128 v[114:117], v202 offset:20992
	ds_read_b32 v118, v206 offset:19968
	v_add_f32_dpp v150, v150, v150 row_mirror row_mask:0xf bank_mask:0xf bound_ctrl:1
	v_pk_fma_f32 v[68:69], v[132:133], v[150:151], v[152:153] op_sel_hi:[1,0,1]
	v_pk_fma_f32 v[70:71], v[134:135], v[150:151], v[154:155] op_sel_hi:[1,0,1]
	ds_read_b128 v[98:101], v202 offset:19968
	ds_read_b128 v[110:113], v202 offset:20736
	s_waitcnt lgkmcnt(6)
	v_pk_mul_f32 v[142:143], v[68:69], v[80:81] op_sel_hi:[0,1]
	v_pk_fma_f32 v[142:143], v[68:69], v[82:83], v[142:143] op_sel:[1,0,0] op_sel_hi:[1,1,1]
	v_pk_fma_f32 v[142:143], v[70:71], v[84:85], v[142:143] op_sel_hi:[0,1,1]
	v_pk_fma_f32 v[142:143], v[70:71], v[86:87], v[142:143] op_sel:[1,0,0] op_sel_hi:[1,1,1]
	v_pk_mul_f32 v[152:153], v[92:93], v[96:97] op_sel_hi:[1,0]
	v_pk_mul_f32 v[154:155], v[94:95], v[96:97] op_sel_hi:[1,0]
	v_add_f32_dpp v150, v142, v142 quad_perm:[1,0,3,2] row_mask:0xf bank_mask:0xf bound_ctrl:1
	v_pk_fma_f32 v[152:153], v[68:69], v[76:77], v[152:153]
	v_pk_fma_f32 v[154:155], v[70:71], v[78:79], v[154:155]
	v_add_f32_dpp v150, v150, v150 quad_perm:[2,3,0,1] row_mask:0xf bank_mask:0xf bound_ctrl:1
	v_add_f32_dpp v156, v145, v145 row_ror:8 row_mask:0xf bank_mask:0xf
	v_add_f32_dpp v157, v147, v147 row_ror:8 row_mask:0xf bank_mask:0xf
	v_add_f32_dpp v150, v150, v150 row_half_mirror row_mask:0xf bank_mask:0xf bound_ctrl:1
	v_add_f32_dpp v156, v149, v149 row_ror:8 row_mask:0xf bank_mask:0xc
	v_add_f32_dpp v157, v143, v143 row_ror:8 row_mask:0xf bank_mask:0xc
	v_add_f32_dpp v150, v150, v150 row_mirror row_mask:0xf bank_mask:0xf bound_ctrl:1
	v_pk_fma_f32 v[72:73], v[88:89], v[150:151], v[152:153] op_sel_hi:[1,0,1]
	v_pk_fma_f32 v[74:75], v[90:91], v[150:151], v[154:155] op_sel_hi:[1,0,1]
	ds_read_b128 v[124:127], v160 offset:21760
	ds_read_b128 v[128:131], v160 offset:21776
	v_add_f32_dpp v158, v156, v156 row_half_mirror row_mask:0xf bank_mask:0xf
	v_add_f32_dpp v158, v157, v157 row_half_mirror row_mask:0xf bank_mask:0xa
	ds_read_b128 v[136:139], v202 offset:22528
	ds_read_b32 v140, v206 offset:21504
	v_add_f32_dpp v158, v158, v158 quad_perm:[1,0,3,2] row_mask:0xf bank_mask:0xf bound_ctrl:1
	ds_read_b128 v[120:123], v202 offset:21504
	ds_read_b128 v[132:135], v202 offset:22272
	v_add_f32_dpp v158, v158, v158 quad_perm:[2,3,0,1] row_mask:0xf bank_mask:0xf bound_ctrl:1
	global_store_dword v159, v158, s[34:35]
	v_add_u32_e32 v159, 0xb000, v159
	s_waitcnt lgkmcnt(6)
	v_pk_mul_f32 v[144:145], v[72:73], v[102:103] op_sel_hi:[0,1]
	v_pk_fma_f32 v[144:145], v[72:73], v[104:105], v[144:145] op_sel:[1,0,0] op_sel_hi:[1,1,1]
	v_pk_fma_f32 v[144:145], v[74:75], v[106:107], v[144:145] op_sel_hi:[0,1,1]
	v_pk_fma_f32 v[144:145], v[74:75], v[108:109], v[144:145] op_sel:[1,0,0] op_sel_hi:[1,1,1]
	v_pk_mul_f32 v[152:153], v[114:115], v[118:119] op_sel_hi:[1,0]
	v_pk_mul_f32 v[154:155], v[116:117], v[118:119] op_sel_hi:[1,0]
	v_add_f32_dpp v150, v144, v144 quad_perm:[1,0,3,2] row_mask:0xf bank_mask:0xf bound_ctrl:1
	v_pk_fma_f32 v[152:153], v[72:73], v[98:99], v[152:153]
	v_pk_fma_f32 v[154:155], v[74:75], v[100:101], v[154:155]
	v_add_f32_dpp v150, v150, v150 quad_perm:[2,3,0,1] row_mask:0xf bank_mask:0xf bound_ctrl:1
	ds_read_b128 v[80:83], v160 offset:23296
	ds_read_b128 v[84:87], v160 offset:23312
	v_add_f32_dpp v150, v150, v150 row_half_mirror row_mask:0xf bank_mask:0xf bound_ctrl:1
	ds_read_b128 v[92:95], v202 offset:24064
	ds_read_b32 v96, v206 offset:23040
	v_add_f32_dpp v150, v150, v150 row_mirror row_mask:0xf bank_mask:0xf bound_ctrl:1
	v_pk_fma_f32 v[68:69], v[110:111], v[150:151], v[152:153] op_sel_hi:[1,0,1]
	v_pk_fma_f32 v[70:71], v[112:113], v[150:151], v[154:155] op_sel_hi:[1,0,1]
	ds_read_b128 v[76:79], v202 offset:23040
	ds_read_b128 v[88:91], v202 offset:23808
	s_waitcnt lgkmcnt(6)
	v_pk_mul_f32 v[146:147], v[68:69], v[124:125] op_sel_hi:[0,1]
	v_pk_fma_f32 v[146:147], v[68:69], v[126:127], v[146:147] op_sel:[1,0,0] op_sel_hi:[1,1,1]
	v_pk_fma_f32 v[146:147], v[70:71], v[128:129], v[146:147] op_sel_hi:[0,1,1]
	v_pk_fma_f32 v[146:147], v[70:71], v[130:131], v[146:147] op_sel:[1,0,0] op_sel_hi:[1,1,1]
	v_pk_mul_f32 v[152:153], v[136:137], v[140:141] op_sel_hi:[1,0]
	v_pk_mul_f32 v[154:155], v[138:139], v[140:141] op_sel_hi:[1,0]
	v_add_f32_dpp v150, v146, v146 quad_perm:[1,0,3,2] row_mask:0xf bank_mask:0xf bound_ctrl:1
	v_pk_fma_f32 v[152:153], v[68:69], v[120:121], v[152:153]
	v_pk_fma_f32 v[154:155], v[70:71], v[122:123], v[154:155]
	v_add_f32_dpp v150, v150, v150 quad_perm:[2,3,0,1] row_mask:0xf bank_mask:0xf bound_ctrl:1
	ds_read_b128 v[102:105], v160 offset:24832
	ds_read_b128 v[106:109], v160 offset:24848
	v_add_f32_dpp v150, v150, v150 row_half_mirror row_mask:0xf bank_mask:0xf bound_ctrl:1
	ds_read_b128 v[114:117], v202 offset:25600
	ds_read_b32 v118, v206 offset:24576
	v_add_f32_dpp v150, v150, v150 row_mirror row_mask:0xf bank_mask:0xf bound_ctrl:1
	v_pk_fma_f32 v[72:73], v[132:133], v[150:151], v[152:153] op_sel_hi:[1,0,1]
	v_pk_fma_f32 v[74:75], v[134:135], v[150:151], v[154:155] op_sel_hi:[1,0,1]
	ds_read_b128 v[98:101], v202 offset:24576
	ds_read_b128 v[110:113], v202 offset:25344
	s_waitcnt lgkmcnt(6)
; __device__ __forceinline__ void rwkv_scan(Frame& F, int wg, unsigned* shw, unsigned wait_target, int wait_blk) {
;     ...
;             RwOps R[4];
;             RW_LD(R[0], 0); RW_LD(R[1], 1); RW_LD(R[2], 2);
;             for (int s4 = 0; s4 < RW_TB; s4 += 4) {
;                 float pz[4], u[4];
; #pragma unroll
;                 for (int q = 0; q < 4; ++q) {
;                     RW_LD(R[(q + 3) & 3], s4 + q + 3);
;                     const RwOps& cur = R[q];
;                     const f32x2 slo = {st.x, st.y}, shi = {st.z, st.w};
;                     f32x2 ma = slo * (f32x2){cur.a.x, cur.a.y}; ma = __builtin_elementwise_fma(shi, (f32x2){cur.a.z, cur.a.w}, ma);
;                     f32x2 mz = slo * (f32x2){cur.wr.x, cur.wr.y}; mz = __builtin_elementwise_fma(shi, (f32x2){cur.wr.z, cur.wr.w}, mz);
;                     float psa = ma.x + ma.y; pz[q] = mz.x + mz.y;
;                     const f32x2 vb = {cur.vs.x, cur.vs.x};
;                     f32x2 tlo = (f32x2){cur.k.x, cur.k.y} * vb, thi = (f32x2){cur.k.z, cur.k.w} * vb;
;                     tlo = __builtin_elementwise_fma(slo, (f32x2){cur.w.x, cur.w.y}, tlo); thi = __builtin_elementwise_fma(shi, (f32x2){cur.w.z, cur.w.w}, thi);
;                     psa = red16(psa);
;                     const f32x2 pb = {psa, psa};
;                     tlo = __builtin_elementwise_fma((f32x2){cur.b.x, cur.b.y}, pb, tlo); thi = __builtin_elementwise_fma((f32x2){cur.b.z, cur.b.w}, pb, thi);
;                     st = (f32x4){tlo.x, tlo.y, thi.x, thi.y};
;                     u[q] = psa * cur.vs.z + cur.vs.y;
;                 }
;                 const float qa = (odd1 ? pz[1] : pz[0]) + dppf<0xB1>(odd1 ? pz[0] : pz[1]);
;                 const float qb = (odd1 ? pz[3] : pz[2]) + dppf<0xB1>(odd1 ? pz[2] : pz[3]);
;                 float r = (odd2 ? qb : qa) + dppf<0x4E>(odd2 ? qa : qb);
;                 r += dppf<0x124>(r); r += dppf<0x128>(r);
;                 const float us = odd2 ? (odd1 ? u[3] : u[2]) : (odd1 ? u[1] : u[0]);
;                 if (j < 4) { const int t = blk * RW_TB + s4 + j; ((float*)(Ub + (size_t)t * (PWP * 2) + URR * 2))[h * 64 + row] = r + us; }
	v_pk_mul_f32 v[148:149], v[72:73], v[80:81] op_sel_hi:[0,1]
	v_pk_fma_f32 v[148:149], v[72:73], v[82:83], v[148:149] op_sel:[1,0,0] op_sel_hi:[1,1,1]
	v_pk_fma_f32 v[148:149], v[74:75], v[84:85], v[148:149] op_sel_hi:[0,1,1]
	v_pk_fma_f32 v[148:149], v[74:75], v[86:87], v[148:149] op_sel:[1,0,0] op_sel_hi:[1,1,1]
	v_pk_mul_f32 v[152:153], v[92:93], v[96:97] op_sel_hi:[1,0]
	v_pk_mul_f32 v[154:155], v[94:95], v[96:97] op_sel_hi:[1,0]
	v_add_f32_dpp v150, v148, v148 quad_perm:[1,0,3,2] row_mask:0xf bank_mask:0xf bound_ctrl:1
	v_pk_fma_f32 v[152:153], v[72:73], v[76:77], v[152:153]
	v_pk_fma_f32 v[154:155], v[74:75], v[78:79], v[154:155]
	v_add_f32_dpp v150, v150, v150 quad_perm:[2,3,0,1] row_mask:0xf bank_mask:0xf bound_ctrl:1
	ds_read_b128 v[124:127], v160 offset:26368
	ds_read_b128 v[128:131], v160 offset:26384
	v_add_f32_dpp v150, v150, v150 row_half_mirror row_mask:0xf bank_mask:0xf bound_ctrl:1
	ds_read_b128 v[136:139], v202 offset:27136
	ds_read_b32 v140, v206 offset:26112
	v_add_f32_dpp v150, v150, v150 row_mirror row_mask:0xf bank_mask:0xf bound_ctrl:1
	v_pk_fma_f32 v[68:69], v[88:89], v[150:151], v[152:153] op_sel_hi:[1,0,1]
	v_pk_fma_f32 v[70:71], v[90:91], v[150:151], v[154:155] op_sel_hi:[1,0,1]
	ds_read_b128 v[120:123], v202 offset:26112
	ds_read_b128 v[132:135], v202 offset:26880
	s_waitcnt lgkmcnt(6)
	v_pk_mul_f32 v[142:143], v[68:69], v[102:103] op_sel_hi:[0,1]
	v_pk_fma_f32 v[142:143], v[68:69], v[104:105], v[142:143] op_sel:[1,0,0] op_sel_hi:[1,1,1]
	v_pk_fma_f32 v[142:143], v[70:71], v[106:107], v[142:143] op_sel_hi:[0,1,1]
	v_pk_fma_f32 v[142:143], v[70:71], v[108:109], v[142:143] op_sel:[1,0,0] op_sel_hi:[1,1,1]
	v_pk_mul_f32 v[152:153], v[114:115], v[118:119] op_sel_hi:[1,0]
	v_pk_mul_f32 v[154:155], v[116:117], v[118:119] op_sel_hi:[1,0]
	v_add_f32_dpp v150, v142, v142 quad_perm:[1,0,3,2] row_mask:0xf bank_mask:0xf bound_ctrl:1
	v_pk_fma_f32 v[152:153], v[68:69], v[98:99], v[152:153]
	v_pk_fma_f32 v[154:155], v[70:71], v[100:101], v[154:155]
	v_add_f32_dpp v150, v150, v150 quad_perm:[2,3,0,1] row_mask:0xf bank_mask:0xf bound_ctrl:1
	v_add_f32_dpp v156, v145, v145 row_ror:8 row_mask:0xf bank_mask:0xf
	v_add_f32_dpp v157, v147, v147 row_ror:8 row_mask:0xf bank_mask:0xf
	v_add_f32_dpp v150, v150, v150 row_half_mirror row_mask:0xf bank_mask:0xf bound_ctrl:1
	v_add_f32_dpp v156, v149, v149 row_ror:8 row_mask:0xf bank_mask:0xc
	v_add_f32_dpp v157, v143, v143 row_ror:8 row_mask:0xf bank_mask:0xc
	v_add_f32_dpp v150, v150, v150 row_mirror row_mask:0xf bank_mask:0xf bound_ctrl:1
	v_pk_fma_f32 v[72:73], v[110:111], v[150:151], v[152:153] op_sel_hi:[1,0,1]
	v_pk_fma_f32 v[74:75], v[112:113], v[150:151], v[154:155] op_sel_hi:[1,0,1]
	ds_read_b128 v[80:83], v160 offset:27904
	ds_read_b128 v[84:87], v160 offset:27920
	v_add_f32_dpp v158, v156, v156 row_half_mirror row_mask:0xf bank_mask:0xf
	v_add_f32_dpp v158, v157, v157 row_half_mirror row_mask:0xf bank_mask:0xa
	ds_read_b128 v[92:95], v202 offset:28672
	ds_read_b32 v96, v206 offset:27648
	v_add_f32_dpp v158, v158, v158 quad_perm:[1,0,3,2] row_mask:0xf bank_mask:0xf bound_ctrl:1
	ds_read_b128 v[76:79], v202 offset:27648
	ds_read_b128 v[88:91], v202 offset:28416
	v_add_f32_dpp v158, v158, v158 quad_perm:[2,3,0,1] row_mask:0xf bank_mask:0xf bound_ctrl:1
	global_store_dword v159, v158, s[34:35]
	v_add_u32_e32 v159, 0xb000, v159
	s_waitcnt lgkmcnt(6)
	v_pk_mul_f32 v[144:145], v[72:73], v[124:125] op_sel_hi:[0,1]
	v_pk_fma_f32 v[144:145], v[72:73], v[126:127], v[144:145] op_sel:[1,0,0] op_sel_hi:[1,1,1]
	v_pk_fma_f32 v[144:145], v[74:75], v[128:129], v[144:145] op_sel_hi:[0,1,1]
	v_pk_fma_f32 v[144:145], v[74:75], v[130:131], v[144:145] op_sel:[1,0,0] op_sel_hi:[1,1,1]
	v_pk_mul_f32 v[152:153], v[136:137], v[140:141] op_sel_hi:[1,0]
	v_pk_mul_f32 v[154:155], v[138:139], v[140:141] op_sel_hi:[1,0]
	v_add_f32_dpp v150, v144, v144 quad_perm:[1,0,3,2] row_mask:0xf bank_mask:0xf bound_ctrl:1
	v_pk_fma_f32 v[152:153], v[72:73], v[120:121], v[152:153]
	v_pk_fma_f32 v[154:155], v[74:75], v[122:123], v[154:155]
	v_add_f32_dpp v150, v150, v150 quad_perm:[2,3,0,1] row_mask:0xf bank_mask:0xf bound_ctrl:1
	ds_read_b128 v[102:105], v160 offset:29440
	ds_read_b128 v[106:109], v160 offset:29456
	v_add_f32_dpp v150, v150, v150 row_half_mirror row_mask:0xf bank_mask:0xf bound_ctrl:1
	ds_read_b128 v[114:117], v202 offset:30208
	ds_read_b32 v118, v206 offset:29184
	v_add_f32_dpp v150, v150, v150 row_mirror row_mask:0xf bank_mask:0xf bound_ctrl:1
	v_pk_fma_f32 v[68:69], v[132:133], v[150:151], v[152:153] op_sel_hi:[1,0,1]
	v_pk_fma_f32 v[70:71], v[134:135], v[150:151], v[154:155] op_sel_hi:[1,0,1]
	ds_read_b128 v[98:101], v202 offset:29184
	ds_read_b128 v[110:113], v202 offset:29952
	s_waitcnt lgkmcnt(6)
	v_pk_mul_f32 v[146:147], v[68:69], v[80:81] op_sel_hi:[0,1]
	v_pk_fma_f32 v[146:147], v[68:69], v[82:83], v[146:147] op_sel:[1,0,0] op_sel_hi:[1,1,1]
	v_pk_fma_f32 v[146:147], v[70:71], v[84:85], v[146:147] op_sel_hi:[0,1,1]
	v_pk_fma_f32 v[146:147], v[70:71], v[86:87], v[146:147] op_sel:[1,0,0] op_sel_hi:[1,1,1]
	v_pk_mul_f32 v[152:153], v[92:93], v[96:97] op_sel_hi:[1,0]
	v_pk_mul_f32 v[154:155], v[94:95], v[96:97] op_sel_hi:[1,0]
	v_add_f32_dpp v150, v146, v146 quad_perm:[1,0,3,2] row_mask:0xf bank_mask:0xf bound_ctrl:1
	v_pk_fma_f32 v[152:153], v[68:69], v[76:77], v[152:153]
	v_pk_fma_f32 v[154:155], v[70:71], v[78:79], v[154:155]
	v_add_f32_dpp v150, v150, v150 quad_perm:[2,3,0,1] row_mask:0xf bank_mask:0xf bound_ctrl:1
	ds_read_b128 v[124:127], v160 offset:30976
	ds_read_b128 v[128:131], v160 offset:30992
	v_add_f32_dpp v150, v150, v150 row_half_mirror row_mask:0xf bank_mask:0xf bound_ctrl:1
	ds_read_b128 v[136:139], v202 offset:31744
	ds_read_b32 v140, v206 offset:30720
	v_add_f32_dpp v150, v150, v150 row_mirror row_mask:0xf bank_mask:0xf bound_ctrl:1
	v_pk_fma_f32 v[72:73], v[88:89], v[150:151], v[152:153] op_sel_hi:[1,0,1]
	v_pk_fma_f32 v[74:75], v[90:91], v[150:151], v[154:155] op_sel_hi:[1,0,1]
	ds_read_b128 v[120:123], v202 offset:30720
	ds_read_b128 v[132:135], v202 offset:31488
	s_waitcnt lgkmcnt(6)
; __device__ __forceinline__ void rwkv_scan(Frame& F, int wg, unsigned* shw, unsigned wait_target, int wait_blk) {
;     ...
;             RwOps R[4];
;             RW_LD(R[0], 0); RW_LD(R[1], 1); RW_LD(R[2], 2);
;             for (int s4 = 0; s4 < RW_TB; s4 += 4) {
;                 float pz[4], u[4];
; #pragma unroll
;                 for (int q = 0; q < 4; ++q) {
;                     RW_LD(R[(q + 3) & 3], s4 + q + 3);
;                     const RwOps& cur = R[q];
;                     const f32x2 slo = {st.x, st.y}, shi = {st.z, st.w};
;                     f32x2 ma = slo * (f32x2){cur.a.x, cur.a.y}; ma = __builtin_elementwise_fma(shi, (f32x2){cur.a.z, cur.a.w}, ma);
;                     f32x2 mz = slo * (f32x2){cur.wr.x, cur.wr.y}; mz = __builtin_elementwise_fma(shi, (f32x2){cur.wr.z, cur.wr.w}, mz);
;                     float psa = ma.x + ma.y; pz[q] = mz.x + mz.y;
;                     const f32x2 vb = {cur.vs.x, cur.vs.x};
;                     f32x2 tlo = (f32x2){cur.k.x, cur.k.y} * vb, thi = (f32x2){cur.k.z, cur.k.w} * vb;
;                     tlo = __builtin_elementwise_fma(slo, (f32x2){cur.w.x, cur.w.y}, tlo); thi = __builtin_elementwise_fma(shi, (f32x2){cur.w.z, cur.w.w}, thi);
;                     psa = red16(psa);
;                     const f32x2 pb = {psa, psa};
;                     tlo = __builtin_elementwise_fma((f32x2){cur.b.x, cur.b.y}, pb, tlo); thi = __builtin_elementwise_fma((f32x2){cur.b.z, cur.b.w}, pb, thi);
;                     st = (f32x4){tlo.x, tlo.y, thi.x, thi.y};
;                     u[q] = psa * cur.vs.z + cur.vs.y;
;                 }
;                 const float qa = (odd1 ? pz[1] : pz[0]) + dppf<0xB1>(odd1 ? pz[0] : pz[1]);
;                 const float qb = (odd1 ? pz[3] : pz[2]) + dppf<0xB1>(odd1 ? pz[2] : pz[3]);
;                 float r = (odd2 ? qb : qa) + dppf<0x4E>(odd2 ? qa : qb);
;                 r += dppf<0x124>(r); r += dppf<0x128>(r);
;                 const float us = odd2 ? (odd1 ? u[3] : u[2]) : (odd1 ? u[1] : u[0]);
;                 if (j < 4) { const int t = blk * RW_TB + s4 + j; ((float*)(Ub + (size_t)t * (PWP * 2) + URR * 2))[h * 64 + row] = r + us; }
	v_pk_mul_f32 v[148:149], v[72:73], v[102:103] op_sel_hi:[0,1]
	v_pk_fma_f32 v[148:149], v[72:73], v[104:105], v[148:149] op_sel:[1,0,0] op_sel_hi:[1,1,1]
	v_pk_fma_f32 v[148:149], v[74:75], v[106:107], v[148:149] op_sel_hi:[0,1,1]
	v_pk_fma_f32 v[148:149], v[74:75], v[108:109], v[148:149] op_sel:[1,0,0] op_sel_hi:[1,1,1]
	v_pk_mul_f32 v[152:153], v[114:115], v[118:119] op_sel_hi:[1,0]
	v_pk_mul_f32 v[154:155], v[116:117], v[118:119] op_sel_hi:[1,0]
	v_add_f32_dpp v150, v148, v148 quad_perm:[1,0,3,2] row_mask:0xf bank_mask:0xf bound_ctrl:1
	v_pk_fma_f32 v[152:153], v[72:73], v[98:99], v[152:153]
	v_pk_fma_f32 v[154:155], v[74:75], v[100:101], v[154:155]
	v_add_f32_dpp v150, v150, v150 quad_perm:[2,3,0,1] row_mask:0xf bank_mask:0xf bound_ctrl:1
	ds_read_b128 v[80:83], v160 offset:32512
	ds_read_b128 v[84:87], v160 offset:32528
	v_add_f32_dpp v150, v150, v150 row_half_mirror row_mask:0xf bank_mask:0xf bound_ctrl:1
	ds_read_b128 v[92:95], v202 offset:33280
	ds_read_b32 v96, v206 offset:32256
	v_add_f32_dpp v150, v150, v150 row_mirror row_mask:0xf bank_mask:0xf bound_ctrl:1
	v_pk_fma_f32 v[68:69], v[110:111], v[150:151], v[152:153] op_sel_hi:[1,0,1]
	v_pk_fma_f32 v[70:71], v[112:113], v[150:151], v[154:155] op_sel_hi:[1,0,1]
	ds_read_b128 v[76:79], v202 offset:32256
	ds_read_b128 v[88:91], v202 offset:33024
	s_waitcnt lgkmcnt(6)
	v_pk_mul_f32 v[142:143], v[68:69], v[124:125] op_sel_hi:[0,1]
	v_pk_fma_f32 v[142:143], v[68:69], v[126:127], v[142:143] op_sel:[1,0,0] op_sel_hi:[1,1,1]
	v_pk_fma_f32 v[142:143], v[70:71], v[128:129], v[142:143] op_sel_hi:[0,1,1]
	v_pk_fma_f32 v[142:143], v[70:71], v[130:131], v[142:143] op_sel:[1,0,0] op_sel_hi:[1,1,1]
	v_pk_mul_f32 v[152:153], v[136:137], v[140:141] op_sel_hi:[1,0]
	v_pk_mul_f32 v[154:155], v[138:139], v[140:141] op_sel_hi:[1,0]
	v_add_f32_dpp v150, v142, v142 quad_perm:[1,0,3,2] row_mask:0xf bank_mask:0xf bound_ctrl:1
	v_pk_fma_f32 v[152:153], v[68:69], v[120:121], v[152:153]
	v_pk_fma_f32 v[154:155], v[70:71], v[122:123], v[154:155]
	v_add_f32_dpp v150, v150, v150 quad_perm:[2,3,0,1] row_mask:0xf bank_mask:0xf bound_ctrl:1
	v_add_f32_dpp v156, v145, v145 row_ror:8 row_mask:0xf bank_mask:0xf
	v_add_f32_dpp v157, v147, v147 row_ror:8 row_mask:0xf bank_mask:0xf
	v_add_f32_dpp v150, v150, v150 row_half_mirror row_mask:0xf bank_mask:0xf bound_ctrl:1
	v_add_f32_dpp v156, v149, v149 row_ror:8 row_mask:0xf bank_mask:0xc
	v_add_f32_dpp v157, v143, v143 row_ror:8 row_mask:0xf bank_mask:0xc
	v_add_f32_dpp v150, v150, v150 row_mirror row_mask:0xf bank_mask:0xf bound_ctrl:1
	v_pk_fma_f32 v[72:73], v[132:133], v[150:151], v[152:153] op_sel_hi:[1,0,1]
	v_pk_fma_f32 v[74:75], v[134:135], v[150:151], v[154:155] op_sel_hi:[1,0,1]
	ds_read_b128 v[102:105], v160 offset:34048
	ds_read_b128 v[106:109], v160 offset:34064
	v_add_f32_dpp v158, v156, v156 row_half_mirror row_mask:0xf bank_mask:0xf
	v_add_f32_dpp v158, v157, v157 row_half_mirror row_mask:0xf bank_mask:0xa
	ds_read_b128 v[114:117], v202 offset:34816
	ds_read_b32 v118, v206 offset:33792
	v_add_f32_dpp v158, v158, v158 quad_perm:[1,0,3,2] row_mask:0xf bank_mask:0xf bound_ctrl:1
	ds_read_b128 v[98:101], v202 offset:33792
	ds_read_b128 v[110:113], v202 offset:34560
	v_add_f32_dpp v158, v158, v158 quad_perm:[2,3,0,1] row_mask:0xf bank_mask:0xf bound_ctrl:1
	global_store_dword v159, v158, s[34:35]
	v_add_u32_e32 v159, 0xb000, v159
	s_waitcnt lgkmcnt(6)
	v_pk_mul_f32 v[144:145], v[72:73], v[80:81] op_sel_hi:[0,1]
	v_pk_fma_f32 v[144:145], v[72:73], v[82:83], v[144:145] op_sel:[1,0,0] op_sel_hi:[1,1,1]
	v_pk_fma_f32 v[144:145], v[74:75], v[84:85], v[144:145] op_sel_hi:[0,1,1]
	v_pk_fma_f32 v[144:145], v[74:75], v[86:87], v[144:145] op_sel:[1,0,0] op_sel_hi:[1,1,1]
	v_pk_mul_f32 v[152:153], v[92:93], v[96:97] op_sel_hi:[1,0]
	v_pk_mul_f32 v[154:155], v[94:95], v[96:97] op_sel_hi:[1,0]
	v_add_f32_dpp v150, v144, v144 quad_perm:[1,0,3,2] row_mask:0xf bank_mask:0xf bound_ctrl:1
	v_pk_fma_f32 v[152:153], v[72:73], v[76:77], v[152:153]
	v_pk_fma_f32 v[154:155], v[74:75], v[78:79], v[154:155]
	v_add_f32_dpp v150, v150, v150 quad_perm:[2,3,0,1] row_mask:0xf bank_mask:0xf bound_ctrl:1
	ds_read_b128 v[124:127], v160 offset:35584
	ds_read_b128 v[128:131], v160 offset:35600
	v_add_f32_dpp v150, v150, v150 row_half_mirror row_mask:0xf bank_mask:0xf bound_ctrl:1
	ds_read_b128 v[136:139], v202 offset:36352
	ds_read_b32 v140, v206 offset:35328
	v_add_f32_dpp v150, v150, v150 row_mirror row_mask:0xf bank_mask:0xf bound_ctrl:1
	v_pk_fma_f32 v[68:69], v[88:89], v[150:151], v[152:153] op_sel_hi:[1,0,1]
	v_pk_fma_f32 v[70:71], v[90:91], v[150:151], v[154:155] op_sel_hi:[1,0,1]
	ds_read_b128 v[120:123], v202 offset:35328
	ds_read_b128 v[132:135], v202 offset:36096
	s_waitcnt lgkmcnt(6)
	v_pk_mul_f32 v[146:147], v[68:69], v[102:103] op_sel_hi:[0,1]
	v_pk_fma_f32 v[146:147], v[68:69], v[104:105], v[146:147] op_sel:[1,0,0] op_sel_hi:[1,1,1]
	v_pk_fma_f32 v[146:147], v[70:71], v[106:107], v[146:147] op_sel_hi:[0,1,1]
	v_pk_fma_f32 v[146:147], v[70:71], v[108:109], v[146:147] op_sel:[1,0,0] op_sel_hi:[1,1,1]
	v_pk_mul_f32 v[152:153], v[114:115], v[118:119] op_sel_hi:[1,0]
	v_pk_mul_f32 v[154:155], v[116:117], v[118:119] op_sel_hi:[1,0]
	v_add_f32_dpp v150, v146, v146 quad_perm:[1,0,3,2] row_mask:0xf bank_mask:0xf bound_ctrl:1
	v_pk_fma_f32 v[152:153], v[68:69], v[98:99], v[152:153]
	v_pk_fma_f32 v[154:155], v[70:71], v[100:101], v[154:155]
	v_add_f32_dpp v150, v150, v150 quad_perm:[2,3,0,1] row_mask:0xf bank_mask:0xf bound_ctrl:1
	ds_read_b128 v[80:83], v160 offset:37120
	ds_read_b128 v[84:87], v160 offset:37136
	v_add_f32_dpp v150, v150, v150 row_half_mirror row_mask:0xf bank_mask:0xf bound_ctrl:1
	ds_read_b128 v[92:95], v202 offset:37888
	ds_read_b32 v96, v206 offset:36864
	v_add_f32_dpp v150, v150, v150 row_mirror row_mask:0xf bank_mask:0xf bound_ctrl:1
	v_pk_fma_f32 v[72:73], v[110:111], v[150:151], v[152:153] op_sel_hi:[1,0,1]
	v_pk_fma_f32 v[74:75], v[112:113], v[150:151], v[154:155] op_sel_hi:[1,0,1]
	ds_read_b128 v[76:79], v202 offset:36864
	ds_read_b128 v[88:91], v202 offset:37632
	s_waitcnt lgkmcnt(6)
; __device__ __forceinline__ void rwkv_scan(Frame& F, int wg, unsigned* shw, unsigned wait_target, int wait_blk) {
;     ...
;             RwOps R[4];
;             RW_LD(R[0], 0); RW_LD(R[1], 1); RW_LD(R[2], 2);
;             for (int s4 = 0; s4 < RW_TB; s4 += 4) {
;                 float pz[4], u[4];
; #pragma unroll
;                 for (int q = 0; q < 4; ++q) {
;                     RW_LD(R[(q + 3) & 3], s4 + q + 3);
;                     const RwOps& cur = R[q];
;                     const f32x2 slo = {st.x, st.y}, shi = {st.z, st.w};
;                     f32x2 ma = slo * (f32x2){cur.a.x, cur.a.y}; ma = __builtin_elementwise_fma(shi, (f32x2){cur.a.z, cur.a.w}, ma);
;                     f32x2 mz = slo * (f32x2){cur.wr.x, cur.wr.y}; mz = __builtin_elementwise_fma(shi, (f32x2){cur.wr.z, cur.wr.w}, mz);
;                     float psa = ma.x + ma.y; pz[q] = mz.x + mz.y;
;                     const f32x2 vb = {cur.vs.x, cur.vs.x};
;                     f32x2 tlo = (f32x2){cur.k.x, cur.k.y} * vb, thi = (f32x2){cur.k.z, cur.k.w} * vb;
;                     tlo = __builtin_elementwise_fma(slo, (f32x2){cur.w.x, cur.w.y}, tlo); thi = __builtin_elementwise_fma(shi, (f32x2){cur.w.z, cur.w.w}, thi);
;                     psa = red16(psa);
;                     const f32x2 pb = {psa, psa};
;                     tlo = __builtin_elementwise_fma((f32x2){cur.b.x, cur.b.y}, pb, tlo); thi = __builtin_elementwise_fma((f32x2){cur.b.z, cur.b.w}, pb, thi);
;                     st = (f32x4){tlo.x, tlo.y, thi.x, thi.y};
;                     u[q] = psa * cur.vs.z + cur.vs.y;
;                 }
;                 const float qa = (odd1 ? pz[1] : pz[0]) + dppf<0xB1>(odd1 ? pz[0] : pz[1]);
;                 const float qb = (odd1 ? pz[3] : pz[2]) + dppf<0xB1>(odd1 ? pz[2] : pz[3]);
;                 float r = (odd2 ? qb : qa) + dppf<0x4E>(odd2 ? qa : qb);
;                 r += dppf<0x124>(r); r += dppf<0x128>(r);
;                 const float us = odd2 ? (odd1 ? u[3] : u[2]) : (odd1 ? u[1] : u[0]);
;                 if (j < 4) { const int t = blk * RW_TB + s4 + j; ((float*)(Ub + (size_t)t * (PWP * 2) + URR * 2))[h * 64 + row] = r + us; }
	v_pk_mul_f32 v[148:149], v[72:73], v[124:125] op_sel_hi:[0,1]
	v_pk_fma_f32 v[148:149], v[72:73], v[126:127], v[148:149] op_sel:[1,0,0] op_sel_hi:[1,1,1]
	v_pk_fma_f32 v[148:149], v[74:75], v[128:129], v[148:149] op_sel_hi:[0,1,1]
	v_pk_fma_f32 v[148:149], v[74:75], v[130:131], v[148:149] op_sel:[1,0,0] op_sel_hi:[1,1,1]
	v_pk_mul_f32 v[152:153], v[136:137], v[140:141] op_sel_hi:[1,0]
	v_pk_mul_f32 v[154:155], v[138:139], v[140:141] op_sel_hi:[1,0]
	v_add_f32_dpp v150, v148, v148 quad_perm:[1,0,3,2] row_mask:0xf bank_mask:0xf bound_ctrl:1
	v_pk_fma_f32 v[152:153], v[72:73], v[120:121], v[152:153]
	v_pk_fma_f32 v[154:155], v[74:75], v[122:123], v[154:155]
	v_add_f32_dpp v150, v150, v150 quad_perm:[2,3,0,1] row_mask:0xf bank_mask:0xf bound_ctrl:1
	ds_read_b128 v[102:105], v160 offset:38656
	ds_read_b128 v[106:109], v160 offset:38672
	v_add_f32_dpp v150, v150, v150 row_half_mirror row_mask:0xf bank_mask:0xf bound_ctrl:1
	ds_read_b128 v[114:117], v202 offset:39424
	ds_read_b32 v118, v206 offset:38400
	v_add_f32_dpp v150, v150, v150 row_mirror row_mask:0xf bank_mask:0xf bound_ctrl:1
	v_pk_fma_f32 v[68:69], v[132:133], v[150:151], v[152:153] op_sel_hi:[1,0,1]
	v_pk_fma_f32 v[70:71], v[134:135], v[150:151], v[154:155] op_sel_hi:[1,0,1]
	ds_read_b128 v[98:101], v202 offset:38400
	ds_read_b128 v[110:113], v202 offset:39168
	s_waitcnt lgkmcnt(6)
	v_pk_mul_f32 v[142:143], v[68:69], v[80:81] op_sel_hi:[0,1]
	v_pk_fma_f32 v[142:143], v[68:69], v[82:83], v[142:143] op_sel:[1,0,0] op_sel_hi:[1,1,1]
	v_pk_fma_f32 v[142:143], v[70:71], v[84:85], v[142:143] op_sel_hi:[0,1,1]
	v_pk_fma_f32 v[142:143], v[70:71], v[86:87], v[142:143] op_sel:[1,0,0] op_sel_hi:[1,1,1]
	v_pk_mul_f32 v[152:153], v[92:93], v[96:97] op_sel_hi:[1,0]
	v_pk_mul_f32 v[154:155], v[94:95], v[96:97] op_sel_hi:[1,0]
	v_add_f32_dpp v150, v142, v142 quad_perm:[1,0,3,2] row_mask:0xf bank_mask:0xf bound_ctrl:1
	v_pk_fma_f32 v[152:153], v[68:69], v[76:77], v[152:153]
	v_pk_fma_f32 v[154:155], v[70:71], v[78:79], v[154:155]
	v_add_f32_dpp v150, v150, v150 quad_perm:[2,3,0,1] row_mask:0xf bank_mask:0xf bound_ctrl:1
	v_add_f32_dpp v156, v145, v145 row_ror:8 row_mask:0xf bank_mask:0xf
	v_add_f32_dpp v157, v147, v147 row_ror:8 row_mask:0xf bank_mask:0xf
	v_add_f32_dpp v150, v150, v150 row_half_mirror row_mask:0xf bank_mask:0xf bound_ctrl:1
	v_add_f32_dpp v156, v149, v149 row_ror:8 row_mask:0xf bank_mask:0xc
	v_add_f32_dpp v157, v143, v143 row_ror:8 row_mask:0xf bank_mask:0xc
	v_add_f32_dpp v150, v150, v150 row_mirror row_mask:0xf bank_mask:0xf bound_ctrl:1
	v_pk_fma_f32 v[72:73], v[88:89], v[150:151], v[152:153] op_sel_hi:[1,0,1]
	v_pk_fma_f32 v[74:75], v[90:91], v[150:151], v[154:155] op_sel_hi:[1,0,1]
	ds_read_b128 v[124:127], v160 offset:40192
	ds_read_b128 v[128:131], v160 offset:40208
	v_add_f32_dpp v158, v156, v156 row_half_mirror row_mask:0xf bank_mask:0xf
	v_add_f32_dpp v158, v157, v157 row_half_mirror row_mask:0xf bank_mask:0xa
	ds_read_b128 v[136:139], v202 offset:40960
	ds_read_b32 v140, v206 offset:39936
	v_add_f32_dpp v158, v158, v158 quad_perm:[1,0,3,2] row_mask:0xf bank_mask:0xf bound_ctrl:1
	ds_read_b128 v[120:123], v202 offset:39936
	ds_read_b128 v[132:135], v202 offset:40704
	v_add_f32_dpp v158, v158, v158 quad_perm:[2,3,0,1] row_mask:0xf bank_mask:0xf bound_ctrl:1
	global_store_dword v159, v158, s[34:35]
	v_add_u32_e32 v159, 0xb000, v159
	s_waitcnt lgkmcnt(6)
	v_pk_mul_f32 v[144:145], v[72:73], v[102:103] op_sel_hi:[0,1]
	v_pk_fma_f32 v[144:145], v[72:73], v[104:105], v[144:145] op_sel:[1,0,0] op_sel_hi:[1,1,1]
	v_pk_fma_f32 v[144:145], v[74:75], v[106:107], v[144:145] op_sel_hi:[0,1,1]
	v_pk_fma_f32 v[144:145], v[74:75], v[108:109], v[144:145] op_sel:[1,0,0] op_sel_hi:[1,1,1]
	v_pk_mul_f32 v[152:153], v[114:115], v[118:119] op_sel_hi:[1,0]
	v_pk_mul_f32 v[154:155], v[116:117], v[118:119] op_sel_hi:[1,0]
	v_add_f32_dpp v150, v144, v144 quad_perm:[1,0,3,2] row_mask:0xf bank_mask:0xf bound_ctrl:1
	v_pk_fma_f32 v[152:153], v[72:73], v[98:99], v[152:153]
	v_pk_fma_f32 v[154:155], v[74:75], v[100:101], v[154:155]
	v_add_f32_dpp v150, v150, v150 quad_perm:[2,3,0,1] row_mask:0xf bank_mask:0xf bound_ctrl:1
	ds_read_b128 v[80:83], v160 offset:41728
	ds_read_b128 v[84:87], v160 offset:41744
	v_add_f32_dpp v150, v150, v150 row_half_mirror row_mask:0xf bank_mask:0xf bound_ctrl:1
	ds_read_b128 v[92:95], v202 offset:42496
	ds_read_b32 v96, v206 offset:41472
	v_add_f32_dpp v150, v150, v150 row_mirror row_mask:0xf bank_mask:0xf bound_ctrl:1
	v_pk_fma_f32 v[68:69], v[110:111], v[150:151], v[152:153] op_sel_hi:[1,0,1]
	v_pk_fma_f32 v[70:71], v[112:113], v[150:151], v[154:155] op_sel_hi:[1,0,1]
	ds_read_b128 v[76:79], v202 offset:41472
	ds_read_b128 v[88:91], v202 offset:42240
	s_waitcnt lgkmcnt(6)
	v_pk_mul_f32 v[146:147], v[68:69], v[124:125] op_sel_hi:[0,1]
	v_pk_fma_f32 v[146:147], v[68:69], v[126:127], v[146:147] op_sel:[1,0,0] op_sel_hi:[1,1,1]
	v_pk_fma_f32 v[146:147], v[70:71], v[128:129], v[146:147] op_sel_hi:[0,1,1]
	v_pk_fma_f32 v[146:147], v[70:71], v[130:131], v[146:147] op_sel:[1,0,0] op_sel_hi:[1,1,1]
	v_pk_mul_f32 v[152:153], v[136:137], v[140:141] op_sel_hi:[1,0]
	v_pk_mul_f32 v[154:155], v[138:139], v[140:141] op_sel_hi:[1,0]
	v_add_f32_dpp v150, v146, v146 quad_perm:[1,0,3,2] row_mask:0xf bank_mask:0xf bound_ctrl:1
	v_pk_fma_f32 v[152:153], v[68:69], v[120:121], v[152:153]
	v_pk_fma_f32 v[154:155], v[70:71], v[122:123], v[154:155]
	v_add_f32_dpp v150, v150, v150 quad_perm:[2,3,0,1] row_mask:0xf bank_mask:0xf bound_ctrl:1
	ds_read_b128 v[102:105], v160 offset:43264
	ds_read_b128 v[106:109], v160 offset:43280
	v_add_f32_dpp v150, v150, v150 row_half_mirror row_mask:0xf bank_mask:0xf bound_ctrl:1
	ds_read_b128 v[114:117], v202 offset:44032
	ds_read_b32 v118, v206 offset:43008
	v_add_f32_dpp v150, v150, v150 row_mirror row_mask:0xf bank_mask:0xf bound_ctrl:1
	v_pk_fma_f32 v[72:73], v[132:133], v[150:151], v[152:153] op_sel_hi:[1,0,1]
	v_pk_fma_f32 v[74:75], v[134:135], v[150:151], v[154:155] op_sel_hi:[1,0,1]
	ds_read_b128 v[98:101], v202 offset:43008
	ds_read_b128 v[110:113], v202 offset:43776
	s_waitcnt lgkmcnt(6)
; __device__ __forceinline__ void rwkv_scan(Frame& F, int wg, unsigned* shw, unsigned wait_target, int wait_blk) {
;     ...
;             RwOps R[4];
;             RW_LD(R[0], 0); RW_LD(R[1], 1); RW_LD(R[2], 2);
;             for (int s4 = 0; s4 < RW_TB; s4 += 4) {
;                 float pz[4], u[4];
; #pragma unroll
;                 for (int q = 0; q < 4; ++q) {
;                     RW_LD(R[(q + 3) & 3], s4 + q + 3);
;                     const RwOps& cur = R[q];
;                     const f32x2 slo = {st.x, st.y}, shi = {st.z, st.w};
;                     f32x2 ma = slo * (f32x2){cur.a.x, cur.a.y}; ma = __builtin_elementwise_fma(shi, (f32x2){cur.a.z, cur.a.w}, ma);
;                     f32x2 mz = slo * (f32x2){cur.wr.x, cur.wr.y}; mz = __builtin_elementwise_fma(shi, (f32x2){cur.wr.z, cur.wr.w}, mz);
;                     float psa = ma.x + ma.y; pz[q] = mz.x + mz.y;
;                     const f32x2 vb = {cur.vs.x, cur.vs.x};
;                     f32x2 tlo = (f32x2){cur.k.x, cur.k.y} * vb, thi = (f32x2){cur.k.z, cur.k.w} * vb;
;                     tlo = __builtin_elementwise_fma(slo, (f32x2){cur.w.x, cur.w.y}, tlo); thi = __builtin_elementwise_fma(shi, (f32x2){cur.w.z, cur.w.w}, thi);
;                     psa = red16(psa);
;                     const f32x2 pb = {psa, psa};
;                     tlo = __builtin_elementwise_fma((f32x2){cur.b.x, cur.b.y}, pb, tlo); thi = __builtin_elementwise_fma((f32x2){cur.b.z, cur.b.w}, pb, thi);
;                     st = (f32x4){tlo.x, tlo.y, thi.x, thi.y};
;                     u[q] = psa * cur.vs.z + cur.vs.y;
;                 }
;                 const float qa = (odd1 ? pz[1] : pz[0]) + dppf<0xB1>(odd1 ? pz[0] : pz[1]);
;                 const float qb = (odd1 ? pz[3] : pz[2]) + dppf<0xB1>(odd1 ? pz[2] : pz[3]);
;                 float r = (odd2 ? qb : qa) + dppf<0x4E>(odd2 ? qa : qb);
;                 r += dppf<0x124>(r); r += dppf<0x128>(r);
;                 const float us = odd2 ? (odd1 ? u[3] : u[2]) : (odd1 ? u[1] : u[0]);
;                 if (j < 4) { const int t = blk * RW_TB + s4 + j; ((float*)(Ub + (size_t)t * (PWP * 2) + URR * 2))[h * 64 + row] = r + us; }
	v_pk_mul_f32 v[148:149], v[72:73], v[80:81] op_sel_hi:[0,1]
	v_pk_fma_f32 v[148:149], v[72:73], v[82:83], v[148:149] op_sel:[1,0,0] op_sel_hi:[1,1,1]
	v_pk_fma_f32 v[148:149], v[74:75], v[84:85], v[148:149] op_sel_hi:[0,1,1]
	v_pk_fma_f32 v[148:149], v[74:75], v[86:87], v[148:149] op_sel:[1,0,0] op_sel_hi:[1,1,1]
	v_pk_mul_f32 v[152:153], v[92:93], v[96:97] op_sel_hi:[1,0]
	v_pk_mul_f32 v[154:155], v[94:95], v[96:97] op_sel_hi:[1,0]
	v_add_f32_dpp v150, v148, v148 quad_perm:[1,0,3,2] row_mask:0xf bank_mask:0xf bound_ctrl:1
	v_pk_fma_f32 v[152:153], v[72:73], v[76:77], v[152:153]
	v_pk_fma_f32 v[154:155], v[74:75], v[78:79], v[154:155]
	v_add_f32_dpp v150, v150, v150 quad_perm:[2,3,0,1] row_mask:0xf bank_mask:0xf bound_ctrl:1
	ds_read_b128 v[124:127], v160 offset:44800
	ds_read_b128 v[128:131], v160 offset:44816
	v_add_f32_dpp v150, v150, v150 row_half_mirror row_mask:0xf bank_mask:0xf bound_ctrl:1
	ds_read_b128 v[136:139], v202 offset:45568
	ds_read_b32 v140, v206 offset:44544
	v_add_f32_dpp v150, v150, v150 row_mirror row_mask:0xf bank_mask:0xf bound_ctrl:1
	v_pk_fma_f32 v[68:69], v[88:89], v[150:151], v[152:153] op_sel_hi:[1,0,1]
	v_pk_fma_f32 v[70:71], v[90:91], v[150:151], v[154:155] op_sel_hi:[1,0,1]
	ds_read_b128 v[120:123], v202 offset:44544
	ds_read_b128 v[132:135], v202 offset:45312
	s_waitcnt lgkmcnt(6)
	v_pk_mul_f32 v[142:143], v[68:69], v[102:103] op_sel_hi:[0,1]
	v_pk_fma_f32 v[142:143], v[68:69], v[104:105], v[142:143] op_sel:[1,0,0] op_sel_hi:[1,1,1]
	v_pk_fma_f32 v[142:143], v[70:71], v[106:107], v[142:143] op_sel_hi:[0,1,1]
	v_pk_fma_f32 v[142:143], v[70:71], v[108:109], v[142:143] op_sel:[1,0,0] op_sel_hi:[1,1,1]
	v_pk_mul_f32 v[152:153], v[114:115], v[118:119] op_sel_hi:[1,0]
	v_pk_mul_f32 v[154:155], v[116:117], v[118:119] op_sel_hi:[1,0]
	v_add_f32_dpp v150, v142, v142 quad_perm:[1,0,3,2] row_mask:0xf bank_mask:0xf bound_ctrl:1
	v_pk_fma_f32 v[152:153], v[68:69], v[98:99], v[152:153]
	v_pk_fma_f32 v[154:155], v[70:71], v[100:101], v[154:155]
	v_add_f32_dpp v150, v150, v150 quad_perm:[2,3,0,1] row_mask:0xf bank_mask:0xf bound_ctrl:1
	v_add_f32_dpp v156, v145, v145 row_ror:8 row_mask:0xf bank_mask:0xf
	v_add_f32_dpp v157, v147, v147 row_ror:8 row_mask:0xf bank_mask:0xf
	v_add_f32_dpp v150, v150, v150 row_half_mirror row_mask:0xf bank_mask:0xf bound_ctrl:1
	v_add_f32_dpp v156, v149, v149 row_ror:8 row_mask:0xf bank_mask:0xc
	v_add_f32_dpp v157, v143, v143 row_ror:8 row_mask:0xf bank_mask:0xc
	v_add_f32_dpp v150, v150, v150 row_mirror row_mask:0xf bank_mask:0xf bound_ctrl:1
	v_pk_fma_f32 v[72:73], v[110:111], v[150:151], v[152:153] op_sel_hi:[1,0,1]
	v_pk_fma_f32 v[74:75], v[112:113], v[150:151], v[154:155] op_sel_hi:[1,0,1]
	ds_read_b128 v[80:83], v160 offset:46336
	ds_read_b128 v[84:87], v160 offset:46352
	v_add_f32_dpp v158, v156, v156 row_half_mirror row_mask:0xf bank_mask:0xf
	v_add_f32_dpp v158, v157, v157 row_half_mirror row_mask:0xf bank_mask:0xa
	ds_read_b128 v[92:95], v202 offset:47104
	ds_read_b32 v96, v206 offset:46080
	v_add_f32_dpp v158, v158, v158 quad_perm:[1,0,3,2] row_mask:0xf bank_mask:0xf bound_ctrl:1
	ds_read_b128 v[76:79], v202 offset:46080
	ds_read_b128 v[88:91], v202 offset:46848
	v_add_f32_dpp v158, v158, v158 quad_perm:[2,3,0,1] row_mask:0xf bank_mask:0xf bound_ctrl:1
	global_store_dword v159, v158, s[34:35]
	v_add_u32_e32 v159, 0xb000, v159
	s_waitcnt lgkmcnt(6)
	v_pk_mul_f32 v[144:145], v[72:73], v[124:125] op_sel_hi:[0,1]
	v_pk_fma_f32 v[144:145], v[72:73], v[126:127], v[144:145] op_sel:[1,0,0] op_sel_hi:[1,1,1]
	v_pk_fma_f32 v[144:145], v[74:75], v[128:129], v[144:145] op_sel_hi:[0,1,1]
	v_pk_fma_f32 v[144:145], v[74:75], v[130:131], v[144:145] op_sel:[1,0,0] op_sel_hi:[1,1,1]
	v_pk_mul_f32 v[152:153], v[136:137], v[140:141] op_sel_hi:[1,0]
	v_pk_mul_f32 v[154:155], v[138:139], v[140:141] op_sel_hi:[1,0]
	v_add_f32_dpp v150, v144, v144 quad_perm:[1,0,3,2] row_mask:0xf bank_mask:0xf bound_ctrl:1
	v_pk_fma_f32 v[152:153], v[72:73], v[120:121], v[152:153]
	v_pk_fma_f32 v[154:155], v[74:75], v[122:123], v[154:155]
	v_add_f32_dpp v150, v150, v150 quad_perm:[2,3,0,1] row_mask:0xf bank_mask:0xf bound_ctrl:1
	ds_read_b128 v[102:105], v160 offset:47872
	ds_read_b128 v[106:109], v160 offset:47888
	v_add_f32_dpp v150, v150, v150 row_half_mirror row_mask:0xf bank_mask:0xf bound_ctrl:1
	ds_read_b128 v[114:117], v202 offset:48640
	ds_read_b32 v118, v206 offset:47616
	v_add_f32_dpp v150, v150, v150 row_mirror row_mask:0xf bank_mask:0xf bound_ctrl:1
	v_pk_fma_f32 v[68:69], v[132:133], v[150:151], v[152:153] op_sel_hi:[1,0,1]
	v_pk_fma_f32 v[70:71], v[134:135], v[150:151], v[154:155] op_sel_hi:[1,0,1]
	ds_read_b128 v[98:101], v202 offset:47616
	ds_read_b128 v[110:113], v202 offset:48384
	s_waitcnt lgkmcnt(6)
	v_pk_mul_f32 v[146:147], v[68:69], v[80:81] op_sel_hi:[0,1]
	v_pk_fma_f32 v[146:147], v[68:69], v[82:83], v[146:147] op_sel:[1,0,0] op_sel_hi:[1,1,1]
	v_pk_fma_f32 v[146:147], v[70:71], v[84:85], v[146:147] op_sel_hi:[0,1,1]
	v_pk_fma_f32 v[146:147], v[70:71], v[86:87], v[146:147] op_sel:[1,0,0] op_sel_hi:[1,1,1]
	v_pk_mul_f32 v[152:153], v[92:93], v[96:97] op_sel_hi:[1,0]
	v_pk_mul_f32 v[154:155], v[94:95], v[96:97] op_sel_hi:[1,0]
	v_add_f32_dpp v150, v146, v146 quad_perm:[1,0,3,2] row_mask:0xf bank_mask:0xf bound_ctrl:1
	v_pk_fma_f32 v[152:153], v[68:69], v[76:77], v[152:153]
	v_pk_fma_f32 v[154:155], v[70:71], v[78:79], v[154:155]
	v_add_f32_dpp v150, v150, v150 quad_perm:[2,3,0,1] row_mask:0xf bank_mask:0xf bound_ctrl:1
	s_nop 0
	s_nop 0
	v_add_f32_dpp v150, v150, v150 row_half_mirror row_mask:0xf bank_mask:0xf bound_ctrl:1
	s_nop 0
	s_nop 0
	v_add_f32_dpp v150, v150, v150 row_mirror row_mask:0xf bank_mask:0xf bound_ctrl:1
	v_pk_fma_f32 v[72:73], v[88:89], v[150:151], v[152:153] op_sel_hi:[1,0,1]
	v_pk_fma_f32 v[74:75], v[90:91], v[150:151], v[154:155] op_sel_hi:[1,0,1]
	s_waitcnt lgkmcnt(0)
	v_pk_mul_f32 v[148:149], v[72:73], v[102:103] op_sel_hi:[0,1]
	v_pk_fma_f32 v[148:149], v[72:73], v[104:105], v[148:149] op_sel:[1,0,0] op_sel_hi:[1,1,1]
	v_pk_fma_f32 v[148:149], v[74:75], v[106:107], v[148:149] op_sel_hi:[0,1,1]
	v_pk_fma_f32 v[148:149], v[74:75], v[108:109], v[148:149] op_sel:[1,0,0] op_sel_hi:[1,1,1]
	v_pk_mul_f32 v[152:153], v[114:115], v[118:119] op_sel_hi:[1,0]
	v_pk_mul_f32 v[154:155], v[116:117], v[118:119] op_sel_hi:[1,0]
	v_add_f32_dpp v150, v148, v148 quad_perm:[1,0,3,2] row_mask:0xf bank_mask:0xf bound_ctrl:1
	v_pk_fma_f32 v[152:153], v[72:73], v[98:99], v[152:153]
	v_pk_fma_f32 v[154:155], v[74:75], v[100:101], v[154:155]
	v_add_f32_dpp v150, v150, v150 quad_perm:[2,3,0,1] row_mask:0xf bank_mask:0xf bound_ctrl:1
	s_nop 0
	s_nop 0
	v_add_f32_dpp v150, v150, v150 row_half_mirror row_mask:0xf bank_mask:0xf bound_ctrl:1
	s_nop 0
	s_nop 0
	v_add_f32_dpp v150, v150, v150 row_mirror row_mask:0xf bank_mask:0xf bound_ctrl:1
	v_pk_fma_f32 v[68:69], v[110:111], v[150:151], v[152:153] op_sel_hi:[1,0,1]
	v_pk_fma_f32 v[70:71], v[112:113], v[150:151], v[154:155] op_sel_hi:[1,0,1]
	s_branch .LBB0_847
; #define LAS __attribute__((address_space(3)))
; __device__ __forceinline__ void rwkv_scan(Frame& F, int wg, unsigned* shw, unsigned wait_target, int wait_blk) {
;     ...
;     auto gload = [&](LdRegs& L, int blk) {
;         const int t = blk * RW_TB + lstep; const size_t o = (size_t)t * 1024 + h * 64 + 8 * part;
;         L.w0 = *(const f32x4*)(Wd + o); L.w1 = *(const f32x4*)(Wd + o + 4);
;         L.a = *(const u32x4*)(Ab + o); L.b = *(const u32x4*)(Bb + o); L.k = *(const u32x4*)(Kp + o); L.r = *(const u32x4*)(Rb + o);
;         if (part < 2) { L.v = *(const u32x4*)(Vb + (size_t)t * 1024 + h * 64 + 16 * rq + 8 * part); L.br = BR[t * 16 + h]; L.kr = KR[t * 16 + h]; }
;     ...
;     auto lstore = [&](const LdRegs& L, int b) {
;         LAS float* rec = buf + (b * RW_TB + lstep) * RW_REC;
;         const u32x4 av = L.a, bv = L.b, kv = L.k, rv = L.r;
;         f32x4 a_0 = {bflo(av.x), bfhi(av.x), bflo(av.y), bfhi(av.y)}, a_1 = {bflo(av.z), bfhi(av.z), bflo(av.w), bfhi(av.w)};
;         f32x4 b_0 = {bflo(bv.x), bfhi(bv.x), bflo(bv.y), bfhi(bv.y)}, b_1 = {bflo(bv.z), bfhi(bv.z), bflo(bv.w), bfhi(bv.w)};
;         f32x4 k_0 = {bflo(kv.x), bfhi(kv.x), bflo(kv.y), bfhi(kv.y)}, k_1 = {bflo(kv.z), bfhi(kv.z), bflo(kv.w), bfhi(kv.w)};
;         f32x4 r_0 = {bflo(rv.x), bfhi(rv.x), bflo(rv.y), bfhi(rv.y)}, r_1 = {bflo(rv.z), bfhi(rv.z), bflo(rv.w), bfhi(rv.w)};
;         *(LAS f32x4*)(rec + 8 * part) = L.w0; *(LAS f32x4*)(rec + 8 * part + 4) = L.w1;
;         *(LAS f32x4*)(rec + 64 + 8 * part) = a_0; *(LAS f32x4*)(rec + 64 + 8 * part + 4) = a_1;
;         *(LAS f32x4*)(rec + 128 + 8 * part) = b_0; *(LAS f32x4*)(rec + 128 + 8 * part + 4) = b_1;
;         *(LAS f32x4*)(rec + 192 + 8 * part) = k_0; *(LAS f32x4*)(rec + 192 + 8 * part + 4) = k_1;
;         *(LAS f32x4*)(rec + 256 + 8 * part) = L.w0 * r_0; *(LAS f32x4*)(rec + 256 + 8 * part + 4) = L.w1 * r_1;
;         if (part < 2) { const u32x4 vv = L.v;
;             const float v8[8] = {bflo(vv.x), bfhi(vv.x), bflo(vv.y), bfhi(vv.y), bflo(vv.z), bfhi(vv.z), bflo(vv.w), bfhi(vv.w)};
; #pragma unroll
;             for (int e = 0; e < 8; ++e) *(LAS f32x4*)(rec + 320 + (8 * part + e) * 4) = (f32x4){v8[e], v8[e] * L.kr, L.br, 0.f}; }
.LBB0_909:
	s_and_b64 vcc, exec, s[50:51]
	s_cbranch_vccz .LBB0_846
	s_cmpk_gt_u32 s59, 0x1fd
	s_cbranch_scc1 .LBB0_847
	s_waitcnt vmcnt(0)
	v_add_u32_e32 v100, v199, v195
	v_lshl_add_u32 v101, v195, 1, v199
	v_lshlrev_b32_e32 v104, 16, v44
	v_and_b32_e32 v105, 0xffff0000, v44
	v_lshlrev_b32_e32 v106, 16, v45
	v_and_b32_e32 v107, 0xffff0000, v45
	v_lshlrev_b32_e32 v108, 16, v46
	v_and_b32_e32 v109, 0xffff0000, v46
	v_lshlrev_b32_e32 v110, 16, v47
	v_and_b32_e32 v111, 0xffff0000, v47
	ds_write_b128 v100, v[104:107] offset:768
	ds_write_b128 v100, v[108:111] offset:784
	v_lshlrev_b32_e32 v112, 16, v48
	v_and_b32_e32 v113, 0xffff0000, v48
	v_lshlrev_b32_e32 v114, 16, v49
	v_and_b32_e32 v115, 0xffff0000, v49
	v_lshlrev_b32_e32 v116, 16, v50
	v_and_b32_e32 v117, 0xffff0000, v50
	v_lshlrev_b32_e32 v118, 16, v51
	v_and_b32_e32 v119, 0xffff0000, v51
	ds_write_b128 v100, v[112:115] offset:1024
	ds_write_b128 v100, v[116:119] offset:1040
	v_lshlrev_b32_e32 v120, 16, v40
	v_lshlrev_b32_e32 v121, 16, v52
	v_and_b32_e32 v122, 0xffff0000, v40
	v_and_b32_e32 v123, 0xffff0000, v52
	ds_write_b128 v101, v[120:123] offset:256
	v_lshlrev_b32_e32 v124, 16, v41
	v_lshlrev_b32_e32 v125, 16, v53
	v_and_b32_e32 v126, 0xffff0000, v41
	v_and_b32_e32 v127, 0xffff0000, v53
	ds_write_b128 v101, v[124:127] offset:272
	v_lshlrev_b32_e32 v128, 16, v42
	v_lshlrev_b32_e32 v129, 16, v54
	v_and_b32_e32 v130, 0xffff0000, v42
	v_and_b32_e32 v131, 0xffff0000, v54
	ds_write_b128 v101, v[128:131] offset:288
	v_lshlrev_b32_e32 v132, 16, v43
	v_lshlrev_b32_e32 v133, 16, v55
	v_and_b32_e32 v134, 0xffff0000, v43
	v_and_b32_e32 v135, 0xffff0000, v55
	ds_write_b128 v101, v[132:135] offset:304
	ds_write_b128 v100, v[36:39] offset:0
	ds_write_b128 v100, v[32:35] offset:16
	s_and_saveexec_b64 s[50:51], s[10:11]
	s_cbranch_execz .LBB0_913
	v_lshlrev_b32_e32 v60, 16, v56
	v_and_b32_e32 v64, 0xffff0000, v56
	v_lshlrev_b32_e32 v72, 16, v57
	v_and_b32_e32 v76, 0xffff0000, v57
	v_lshlrev_b32_e32 v80, 16, v58
	v_and_b32_e32 v84, 0xffff0000, v58
	v_lshlrev_b32_e32 v88, 16, v59
	v_and_b32_e32 v92, 0xffff0000, v59
	v_mul_f32_e32 v61, v197, v60
	v_add_u32_e32 v4, v199, v200
	v_mov_b32_e32 v63, v67
	v_mul_f32_e32 v65, v197, v64
	v_mov_b32_e32 v66, v62
	v_mul_f32_e32 v73, v197, v72
	v_mov_b32_e32 v74, v62
	v_mov_b32_e32 v75, v67
	v_mul_f32_e32 v77, v197, v76
	v_mov_b32_e32 v78, v62
	v_mov_b32_e32 v79, v67
	v_mul_f32_e32 v81, v197, v80
	v_mov_b32_e32 v82, v62
	v_mov_b32_e32 v83, v67
	v_mul_f32_e32 v85, v197, v84
	v_mov_b32_e32 v86, v62
	v_mov_b32_e32 v87, v67
	v_mul_f32_e32 v89, v197, v88
	v_mov_b32_e32 v90, v62
	v_mov_b32_e32 v91, v67
	v_mul_f32_e32 v93, v197, v92
	v_mov_b32_e32 v94, v62
	v_mov_b32_e32 v95, v67
	ds_write_b128 v4, v[60:63] offset:1280
	ds_write_b128 v4, v[64:67] offset:1296
	ds_write_b128 v4, v[72:75] offset:1312
	ds_write_b128 v4, v[76:79] offset:1328
	ds_write_b128 v4, v[80:83] offset:1344
	ds_write_b128 v4, v[84:87] offset:1360
	ds_write_b128 v4, v[88:91] offset:1376
	ds_write_b128 v4, v[92:95] offset:1392
.LBB0_913:
	s_or_b64 exec, exec, s[50:51]
	s_cmpk_gt_u32 s59, 0x1fb
	s_cbranch_scc1 .LBB0_847
	v_lshl_add_u32 v66, s59, 5, v203
	v_lshlrev_b64 v[4:5], 10, v[66:67]
	v_lshl_add_u64 v[40:41], v[4:5], 0, v[190:191]
	v_lshlrev_b64 v[48:49], 1, v[40:41]
	v_lshl_add_u64 v[36:37], v[40:41], 2, s[12:13]
	v_lshl_add_u64 v[40:41], s[14:15], 0, v[48:49]
	v_lshl_add_u64 v[44:45], s[16:17], 0, v[48:49]
	v_lshl_add_u64 v[50:51], s[18:19], 0, v[48:49]
	v_lshl_add_u64 v[52:53], s[40:41], 0, v[48:49]
	global_load_dwordx4 v[32:35], v[36:37], off offset:16
	s_nop 0
	global_load_dwordx4 v[36:39], v[36:37], off
	s_nop 0
	global_load_dwordx4 v[40:43], v[40:41], off
	s_nop 0
	global_load_dwordx4 v[44:47], v[44:45], off
	s_nop 0
	global_load_dwordx4 v[48:51], v[50:51], off
	s_nop 0
	global_load_dwordx4 v[52:55], v[52:53], off offset:-2048
	s_and_saveexec_b64 s[50:51], s[10:11]
	s_cbranch_execz .LBB0_916
	v_lshl_add_u32 v56, v66, 4, s58
	v_ashrrev_i32_e32 v57, 31, v56
	v_lshlrev_b64 v[56:57], 2, v[56:57]
	v_lshl_add_u64 v[62:63], s[22:23], 0, v[56:57]
	v_lshl_add_u64 v[4:5], v[4:5], 1, v[192:193]
	v_lshl_add_u64 v[60:61], s[24:25], 0, v[56:57]
	global_load_dwordx4 v[56:59], v[4:5], off
	s_nop 0
	global_load_dword v62, v[62:63], off
	s_nop 0
	global_load_dword v197, v[60:61], off

; __device__ __forceinline__ void rwkv_scan(Frame& F, int wg, unsigned* shw, unsigned wait_target, int wait_blk) {
;     ...
;                     f32x2 mz = slo * (f32x2){cur.wr.x, cur.wr.y}; mz = __builtin_elementwise_fma(shi, (f32x2){cur.wr.z, cur.wr.w}, mz);
;                     float psa = ma.x + ma.y; pz[q] = mz.x + mz.y;
;                     const f32x2 vb = {cur.vs.x, cur.vs.x};
;                     f32x2 tlo = (f32x2){cur.k.x, cur.k.y} * vb, thi = (f32x2){cur.k.z, cur.k.w} * vb;
;                     tlo = __builtin_elementwise_fma(slo, (f32x2){cur.w.x, cur.w.y}, tlo); thi = __builtin_elementwise_fma(shi, (f32x2){cur.w.z, cur.w.w}, thi);
;                     psa = red16(psa);
;                     const f32x2 pb = {psa, psa};
;                     tlo = __builtin_elementwise_fma((f32x2){cur.b.x, cur.b.y}, pb, tlo); thi = __builtin_elementwise_fma((f32x2){cur.b.z, cur.b.w}, pb, thi);
;                     st = (f32x4){tlo.x, tlo.y, thi.x, thi.y};
;                     u[q] = psa * cur.vs.z + cur.vs.y;
;                 }
;                 const float qa = (odd1 ? pz[1] : pz[0]) + dppf<0xB1>(odd1 ? pz[0] : pz[1]);
;                 const float qb = (odd1 ? pz[3] : pz[2]) + dppf<0xB1>(odd1 ? pz[2] : pz[3]);
;                 float r = (odd2 ? qb : qa) + dppf<0x4E>(odd2 ? qa : qb);
;                 r += dppf<0x124>(r); r += dppf<0x128>(r);
;                 const float us = odd2 ? (odd1 ? u[3] : u[2]) : (odd1 ? u[1] : u[0]);
;                 if (j < 4) { const int t = blk * RW_TB + s4 + j; ((float*)(Ub + (size_t)t * (PWP * 2) + URR * 2))[h * 64 + row] = r + us; }
.LBB0_917:
	s_and_b64 vcc, exec, s[26:27]
	s_cbranch_vccz .Lscan_epi_done
	s_lshl_b32 s50, s58, 7
	s_add_u32 s50, s50, 0x1fff800
	v_lshl_add_u32 v76, v194, 3, s50
	global_load_dwordx2 v[78:79], v76, s[40:41]
	s_waitcnt vmcnt(0)
	v_lshlrev_b32_e32 v80, 16, v78
	v_and_b32_e32 v81, 0xffff0000, v78
	v_lshlrev_b32_e32 v82, 16, v79
	v_and_b32_e32 v83, 0xffff0000, v79
	v_pk_mul_f32 v[84:85], v[68:69], v[80:81]
	v_pk_fma_f32 v[84:85], v[70:71], v[82:83], v[84:85]
	v_add_f32_e32 v86, v84, v85
	s_nop 1
	v_add_f32_dpp v156, v145, v145 row_ror:8 row_mask:0xf bank_mask:0xf
	v_add_f32_dpp v157, v147, v147 row_ror:8 row_mask:0xf bank_mask:0xf
	v_add_f32_dpp v156, v149, v149 row_ror:8 row_mask:0xf bank_mask:0xc
	v_add_f32_dpp v157, v86, v86 row_ror:8 row_mask:0xf bank_mask:0xc
	s_nop 0
	s_nop 0
	v_add_f32_dpp v158, v156, v156 row_half_mirror row_mask:0xf bank_mask:0xf
	v_add_f32_dpp v158, v157, v157 row_half_mirror row_mask:0xf bank_mask:0xa
	s_nop 0
	s_nop 0
	v_add_f32_dpp v158, v158, v158 quad_perm:[1,0,3,2] row_mask:0xf bank_mask:0xf bound_ctrl:1
	s_nop 0
	s_nop 0
	v_add_f32_dpp v158, v158, v158 quad_perm:[2,3,0,1] row_mask:0xf bank_mask:0xf bound_ctrl:1
	global_store_dword v159, v158, s[34:35]
	v_add_u32_e32 v159, 0xb000, v159
